# cleanup: redundant lgkmcnt(0) after loop barriers, back-to-back setprio 0/1 pairs, s_nop 0 between inline v_max3 removed
# baseline (speedup 1.0000x reference)
.LBB0_382:
	s_add_u32 s2, s38, 0xfffc0080
	s_addc_u32 s3, s39, -1
	s_add_i32 s23, 0, 0x10000
	s_cmp_eq_u32 s21, 12
	s_cselect_b32 s3, s5, s3
	s_cselect_b32 s2, s8, s2
	v_add_u32_e32 v32, s23, v147
	s_cselect_b32 s65, s11, s20
	s_cselect_b32 s64, s12, s19
	s_add_i32 s57, 0, 0x14000
	ds_read_b128 v[132:135], v32
	ds_read_b128 v[136:139], v32 offset:1024
	ds_read_b128 v[162:165], v32 offset:2048
	ds_read_b128 v[166:169], v32 offset:3072
	v_add_u32_e32 v32, s57, v147
	ds_read_b128 v[170:173], v32
	ds_read_b128 v[174:177], v32 offset:1024
	ds_read_b128 v[178:181], v32 offset:2048
	ds_read_b128 v[182:185], v32 offset:3072
	v_lshl_add_u64 v[34:35], s[38:39], 0, v[150:151]
	s_add_i32 m0, s7, 0xc000
	ds_read_b128 v[186:189], v196
	ds_read_b128 v[198:201], v196 offset:1024
	ds_read_b128 v[202:205], v196 offset:2048
	ds_read_b128 v[206:209], v196 offset:3072
	ds_read_b128 v[210:213], v196 offset:4096
	ds_read_b128 v[220:223], v196 offset:5120
	ds_read_b128 v[224:227], v196 offset:6144
	ds_read_b128 v[228:231], v196 offset:7168
	global_load_lds_dwordx4 v[34:35], off
	v_lshl_add_u64 v[34:35], s[38:39], 0, v[152:153]
	s_add_i32 m0, s7, 0xe000
	s_nop 0
	global_load_lds_dwordx4 v[34:35], off
	s_waitcnt vmcnt(8)
	s_waitcnt lgkmcnt(0)
	s_barrier
	s_setprio 1
	v_mfma_f32_16x16x32_bf16 v[128:131], v[132:135], v[186:189], v[128:131]
	v_mfma_f32_16x16x32_bf16 v[124:127], v[162:165], v[186:189], v[124:127]
	v_mfma_f32_16x16x32_bf16 v[112:115], v[132:135], v[202:205], v[112:115]
	v_mfma_f32_16x16x32_bf16 v[108:111], v[162:165], v[202:205], v[108:111]
	v_mfma_f32_16x16x32_bf16 v[96:99], v[132:135], v[210:213], v[96:99]
	v_mfma_f32_16x16x32_bf16 v[92:95], v[162:165], v[210:213], v[92:95]
	v_mfma_f32_16x16x32_bf16 v[80:83], v[132:135], v[224:227], v[80:83]
	v_mfma_f32_16x16x32_bf16 v[76:79], v[162:165], v[224:227], v[76:79]
	v_mfma_f32_16x16x32_bf16 v[128:131], v[136:139], v[198:201], v[128:131]
	v_mfma_f32_16x16x32_bf16 v[124:127], v[166:169], v[198:201], v[124:127]
	v_mfma_f32_16x16x32_bf16 v[112:115], v[136:139], v[206:209], v[112:115]
	v_mfma_f32_16x16x32_bf16 v[108:111], v[166:169], v[206:209], v[108:111]
	v_mfma_f32_16x16x32_bf16 v[96:99], v[136:139], v[220:223], v[96:99]
	v_mfma_f32_16x16x32_bf16 v[92:95], v[166:169], v[220:223], v[92:95]
	v_mfma_f32_16x16x32_bf16 v[80:83], v[136:139], v[228:231], v[80:83]
	v_mfma_f32_16x16x32_bf16 v[76:79], v[166:169], v[228:231], v[76:79]
	v_mfma_f32_16x16x32_bf16 v[120:123], v[170:173], v[186:189], v[120:123]
	v_mfma_f32_16x16x32_bf16 v[116:119], v[178:181], v[186:189], v[116:119]
	v_mfma_f32_16x16x32_bf16 v[104:107], v[170:173], v[202:205], v[104:107]
	v_mfma_f32_16x16x32_bf16 v[100:103], v[178:181], v[202:205], v[100:103]
	v_mfma_f32_16x16x32_bf16 v[88:91], v[170:173], v[210:213], v[88:91]
	v_mfma_f32_16x16x32_bf16 v[84:87], v[178:181], v[210:213], v[84:87]
	v_mfma_f32_16x16x32_bf16 v[72:75], v[170:173], v[224:227], v[72:75]
	v_mfma_f32_16x16x32_bf16 v[68:71], v[178:181], v[224:227], v[68:71]
	v_mfma_f32_16x16x32_bf16 v[120:123], v[174:177], v[198:201], v[120:123]
	v_mfma_f32_16x16x32_bf16 v[116:119], v[182:185], v[198:201], v[116:119]
	v_mfma_f32_16x16x32_bf16 v[104:107], v[174:177], v[206:209], v[104:107]
	v_mfma_f32_16x16x32_bf16 v[100:103], v[182:185], v[206:209], v[100:103]
	v_mfma_f32_16x16x32_bf16 v[88:91], v[174:177], v[220:223], v[88:91]
	v_mfma_f32_16x16x32_bf16 v[84:87], v[182:185], v[220:223], v[84:87]
	v_mfma_f32_16x16x32_bf16 v[72:75], v[174:177], v[228:231], v[72:75]
	v_mfma_f32_16x16x32_bf16 v[68:71], v[182:185], v[228:231], v[68:71]
	s_setprio 0
	s_barrier
	s_add_i32 s23, s23, s13
	v_lshl_add_u64 v[232:233], s[64:65], 0, v[140:141]
	s_mov_b32 m0, s23
	ds_read_b128 v[186:189], v196 offset:16384
	ds_read_b128 v[198:201], v196 offset:17408
	ds_read_b128 v[202:205], v196 offset:18432
	ds_read_b128 v[206:209], v196 offset:19456
	ds_read_b128 v[210:213], v196 offset:20480
	ds_read_b128 v[220:223], v196 offset:21504
	ds_read_b128 v[224:227], v196 offset:22528
	ds_read_b128 v[228:231], v196 offset:23552
	global_load_lds_dwordx4 v[232:233], off
	s_add_i32 m0, s23, 0x2000
	s_add_u32 s66, s64, 0x40000
	v_lshl_add_u64 v[234:235], s[64:65], 0, v[142:143]
	s_addc_u32 s67, s65, 0
	s_add_i32 s23, s57, s13
	global_load_lds_dwordx4 v[234:235], off
	v_lshl_add_u64 v[34:35], s[66:67], 0, v[140:141]
	s_mov_b32 m0, s23
	v_lshl_add_u64 v[236:237], s[2:3], 0, v[140:141]
	global_load_lds_dwordx4 v[34:35], off
	v_lshl_add_u64 v[34:35], s[66:67], 0, v[142:143]
	s_add_i32 m0, s23, 0x2000
	v_lshl_add_u64 v[238:239], s[2:3], 0, v[142:143]
	global_load_lds_dwordx4 v[34:35], off
	s_mov_b32 m0, s7
	s_nop 0
	global_load_lds_dwordx4 v[236:237], off
	s_mov_b32 m0, s17
	s_nop 0
	global_load_lds_dwordx4 v[238:239], off
	s_waitcnt vmcnt(8)
	s_waitcnt lgkmcnt(0)
	s_barrier
	s_setprio 1
	v_mfma_f32_16x16x32_bf16 v[64:67], v[132:135], v[186:189], v[64:67]
	v_mfma_f32_16x16x32_bf16 v[60:63], v[162:165], v[186:189], v[60:63]
	v_mfma_f32_16x16x32_bf16 v[48:51], v[132:135], v[202:205], v[48:51]
	v_mfma_f32_16x16x32_bf16 v[44:47], v[162:165], v[202:205], v[44:47]
	v_mfma_f32_16x16x32_bf16 v[28:31], v[132:135], v[210:213], v[28:31]
	v_mfma_f32_16x16x32_bf16 v[24:27], v[162:165], v[210:213], v[24:27]
	v_mfma_f32_16x16x32_bf16 v[12:15], v[132:135], v[224:227], v[12:15]
	v_mfma_f32_16x16x32_bf16 v[8:11], v[162:165], v[224:227], v[8:11]
	v_mfma_f32_16x16x32_bf16 v[64:67], v[136:139], v[198:201], v[64:67]
	v_mfma_f32_16x16x32_bf16 v[60:63], v[166:169], v[198:201], v[60:63]
	v_mfma_f32_16x16x32_bf16 v[48:51], v[136:139], v[206:209], v[48:51]
	v_mfma_f32_16x16x32_bf16 v[44:47], v[166:169], v[206:209], v[44:47]
	v_mfma_f32_16x16x32_bf16 v[28:31], v[136:139], v[220:223], v[28:31]
	v_mfma_f32_16x16x32_bf16 v[24:27], v[166:169], v[220:223], v[24:27]
	v_mfma_f32_16x16x32_bf16 v[12:15], v[136:139], v[228:231], v[12:15]
	v_mfma_f32_16x16x32_bf16 v[8:11], v[166:169], v[228:231], v[8:11]
	v_mfma_f32_16x16x32_bf16 v[56:59], v[170:173], v[186:189], v[56:59]
	v_mfma_f32_16x16x32_bf16 v[52:55], v[178:181], v[186:189], v[52:55]
	v_mfma_f32_16x16x32_bf16 v[40:43], v[170:173], v[202:205], v[40:43]
	v_mfma_f32_16x16x32_bf16 v[34:37], v[178:181], v[202:205], v[36:39]
	v_mfma_f32_16x16x32_bf16 v[20:23], v[170:173], v[210:213], v[20:23]
	v_mfma_f32_16x16x32_bf16 v[16:19], v[178:181], v[210:213], v[16:19]
	v_mfma_f32_16x16x32_bf16 v[4:7], v[170:173], v[224:227], v[4:7]
	v_mfma_f32_16x16x32_bf16 v[0:3], v[178:181], v[224:227], v[0:3]
	v_mfma_f32_16x16x32_bf16 v[56:59], v[174:177], v[198:201], v[56:59]
	v_mfma_f32_16x16x32_bf16 v[52:55], v[182:185], v[198:201], v[52:55]
	v_mfma_f32_16x16x32_bf16 v[40:43], v[174:177], v[206:209], v[40:43]
	v_mfma_f32_16x16x32_bf16 v[34:37], v[182:185], v[206:209], v[34:37]
	v_mfma_f32_16x16x32_bf16 v[20:23], v[174:177], v[220:223], v[20:23]
	v_mfma_f32_16x16x32_bf16 v[16:19], v[182:185], v[220:223], v[16:19]
	v_mfma_f32_16x16x32_bf16 v[4:7], v[174:177], v[228:231], v[4:7]
	v_mfma_f32_16x16x32_bf16 v[0:3], v[182:185], v[228:231], v[0:3]
	s_setprio 0
	s_barrier
	s_add_i32 s23, 0, 0x18000
	v_add_u32_e32 v32, s23, v147
	s_add_i32 s57, 0, 0x1c000
	ds_read_b128 v[132:135], v32
	ds_read_b128 v[136:139], v32 offset:1024
	ds_read_b128 v[162:165], v32 offset:2048
	ds_read_b128 v[166:169], v32 offset:3072
	v_add_u32_e32 v32, s57, v147
	ds_read_b128 v[170:173], v32
	ds_read_b128 v[174:177], v32 offset:1024
	ds_read_b128 v[178:181], v32 offset:2048
	ds_read_b128 v[182:185], v32 offset:3072
	s_add_u32 s2, s2, 0x40000
	s_addc_u32 s3, s3, 0
	s_mov_b32 m0, s72
	v_lshl_add_u64 v[38:39], s[2:3], 0, v[140:141]
	ds_read_b128 v[186:189], v196 offset:32768
	ds_read_b128 v[198:201], v196 offset:33792
	ds_read_b128 v[202:205], v196 offset:34816
	ds_read_b128 v[206:209], v196 offset:35840
	ds_read_b128 v[210:213], v196 offset:36864
	ds_read_b128 v[220:223], v196 offset:37888
	ds_read_b128 v[224:227], v196 offset:38912
	ds_read_b128 v[228:231], v196 offset:39936
	global_load_lds_dwordx4 v[38:39], off
	v_lshl_add_u64 v[38:39], s[2:3], 0, v[142:143]
	s_mov_b32 m0, s73
	s_nop 0
	global_load_lds_dwordx4 v[38:39], off
	s_waitcnt vmcnt(8)
	s_waitcnt lgkmcnt(0)
	s_barrier
	s_setprio 1
	v_mfma_f32_16x16x32_bf16 v[128:131], v[132:135], v[186:189], v[128:131]
	v_mfma_f32_16x16x32_bf16 v[124:127], v[162:165], v[186:189], v[124:127]
	v_mfma_f32_16x16x32_bf16 v[112:115], v[132:135], v[202:205], v[112:115]
	v_mfma_f32_16x16x32_bf16 v[108:111], v[162:165], v[202:205], v[108:111]
	v_mfma_f32_16x16x32_bf16 v[96:99], v[132:135], v[210:213], v[96:99]
	v_mfma_f32_16x16x32_bf16 v[92:95], v[162:165], v[210:213], v[92:95]
	v_mfma_f32_16x16x32_bf16 v[80:83], v[132:135], v[224:227], v[80:83]
	v_mfma_f32_16x16x32_bf16 v[76:79], v[162:165], v[224:227], v[76:79]
	v_mfma_f32_16x16x32_bf16 v[128:131], v[136:139], v[198:201], v[128:131]
	v_mfma_f32_16x16x32_bf16 v[124:127], v[166:169], v[198:201], v[124:127]
	v_mfma_f32_16x16x32_bf16 v[112:115], v[136:139], v[206:209], v[112:115]
	v_mfma_f32_16x16x32_bf16 v[108:111], v[166:169], v[206:209], v[108:111]
	v_mfma_f32_16x16x32_bf16 v[96:99], v[136:139], v[220:223], v[96:99]
	v_mfma_f32_16x16x32_bf16 v[92:95], v[166:169], v[220:223], v[92:95]
	v_mfma_f32_16x16x32_bf16 v[80:83], v[136:139], v[228:231], v[80:83]
	v_mfma_f32_16x16x32_bf16 v[76:79], v[166:169], v[228:231], v[76:79]
	v_mfma_f32_16x16x32_bf16 v[120:123], v[170:173], v[186:189], v[120:123]
	v_mfma_f32_16x16x32_bf16 v[116:119], v[178:181], v[186:189], v[116:119]
	v_mfma_f32_16x16x32_bf16 v[104:107], v[170:173], v[202:205], v[104:107]
	v_mfma_f32_16x16x32_bf16 v[100:103], v[178:181], v[202:205], v[100:103]
	v_mfma_f32_16x16x32_bf16 v[88:91], v[170:173], v[210:213], v[88:91]
	v_mfma_f32_16x16x32_bf16 v[84:87], v[178:181], v[210:213], v[84:87]
	v_mfma_f32_16x16x32_bf16 v[72:75], v[170:173], v[224:227], v[72:75]
	v_mfma_f32_16x16x32_bf16 v[68:71], v[178:181], v[224:227], v[68:71]
	v_mfma_f32_16x16x32_bf16 v[120:123], v[174:177], v[198:201], v[120:123]
	v_mfma_f32_16x16x32_bf16 v[116:119], v[182:185], v[198:201], v[116:119]
	v_mfma_f32_16x16x32_bf16 v[104:107], v[174:177], v[206:209], v[104:107]
	v_mfma_f32_16x16x32_bf16 v[100:103], v[182:185], v[206:209], v[100:103]
	v_mfma_f32_16x16x32_bf16 v[88:91], v[174:177], v[220:223], v[88:91]
	v_mfma_f32_16x16x32_bf16 v[84:87], v[182:185], v[220:223], v[84:87]
	v_mfma_f32_16x16x32_bf16 v[72:75], v[174:177], v[228:231], v[72:75]
	v_mfma_f32_16x16x32_bf16 v[68:71], v[182:185], v[228:231], v[68:71]
	s_setprio 0
	s_barrier
	s_add_i32 s2, s23, s13
	v_lshl_add_u64 v[38:39], v[232:233], 0, s[24:25]
	s_mov_b32 m0, s2
	ds_read_b128 v[186:189], v196 offset:49152
	ds_read_b128 v[198:201], v196 offset:50176
	ds_read_b128 v[202:205], v196 offset:51200
	ds_read_b128 v[206:209], v196 offset:52224
	ds_read_b128 v[210:213], v196 offset:53248
	ds_read_b128 v[220:223], v196 offset:54272
	ds_read_b128 v[224:227], v196 offset:55296
	ds_read_b128 v[228:231], v196 offset:56320
	global_load_lds_dwordx4 v[38:39], off
	s_add_i32 m0, s2, 0x2000
	s_add_u32 s2, s64, 0x40080
	v_lshl_add_u64 v[38:39], v[234:235], 0, s[24:25]
	s_addc_u32 s3, s65, 0
	s_add_i32 s23, s57, s13
	global_load_lds_dwordx4 v[38:39], off
	v_lshl_add_u64 v[38:39], s[2:3], 0, v[140:141]
	s_mov_b32 m0, s23
	s_nop 0
	global_load_lds_dwordx4 v[38:39], off
	v_lshl_add_u64 v[38:39], s[2:3], 0, v[142:143]
	s_add_i32 m0, s23, 0x2000
	s_nop 0
	global_load_lds_dwordx4 v[38:39], off
	v_lshl_add_u64 v[38:39], v[236:237], 0, s[24:25]
	s_mov_b32 m0, s70
	s_nop 0
	global_load_lds_dwordx4 v[38:39], off
	v_lshl_add_u64 v[38:39], v[238:239], 0, s[24:25]
	s_mov_b32 m0, s71
	s_nop 0
	global_load_lds_dwordx4 v[38:39], off
	s_waitcnt vmcnt(8)
	s_waitcnt lgkmcnt(0)
	s_barrier
	s_setprio 1
	v_mfma_f32_16x16x32_bf16 v[64:67], v[132:135], v[186:189], v[64:67]
	v_mfma_f32_16x16x32_bf16 v[60:63], v[162:165], v[186:189], v[60:63]
	v_mfma_f32_16x16x32_bf16 v[48:51], v[132:135], v[202:205], v[48:51]
	v_mfma_f32_16x16x32_bf16 v[44:47], v[162:165], v[202:205], v[44:47]
	v_mfma_f32_16x16x32_bf16 v[28:31], v[132:135], v[210:213], v[28:31]
	v_mfma_f32_16x16x32_bf16 v[24:27], v[162:165], v[210:213], v[24:27]
	v_mfma_f32_16x16x32_bf16 v[12:15], v[132:135], v[224:227], v[12:15]
	v_mfma_f32_16x16x32_bf16 v[8:11], v[162:165], v[224:227], v[8:11]
	v_mfma_f32_16x16x32_bf16 v[64:67], v[136:139], v[198:201], v[64:67]
	v_mfma_f32_16x16x32_bf16 v[60:63], v[166:169], v[198:201], v[60:63]
	v_mfma_f32_16x16x32_bf16 v[48:51], v[136:139], v[206:209], v[48:51]
	v_mfma_f32_16x16x32_bf16 v[44:47], v[166:169], v[206:209], v[44:47]
	v_mfma_f32_16x16x32_bf16 v[28:31], v[136:139], v[220:223], v[28:31]
	v_mfma_f32_16x16x32_bf16 v[24:27], v[166:169], v[220:223], v[24:27]
	v_mfma_f32_16x16x32_bf16 v[12:15], v[136:139], v[228:231], v[12:15]
	v_mfma_f32_16x16x32_bf16 v[8:11], v[166:169], v[228:231], v[8:11]
	v_mfma_f32_16x16x32_bf16 v[56:59], v[170:173], v[186:189], v[56:59]
	v_mfma_f32_16x16x32_bf16 v[52:55], v[178:181], v[186:189], v[52:55]
	v_mfma_f32_16x16x32_bf16 v[38:41], v[170:173], v[202:205], v[40:43]
	v_mfma_f32_16x16x32_bf16 v[34:37], v[178:181], v[202:205], v[34:37]
	v_mfma_f32_16x16x32_bf16 v[20:23], v[170:173], v[210:213], v[20:23]
	v_mfma_f32_16x16x32_bf16 v[16:19], v[178:181], v[210:213], v[16:19]
	v_mfma_f32_16x16x32_bf16 v[4:7], v[170:173], v[224:227], v[4:7]
	v_mfma_f32_16x16x32_bf16 v[0:3], v[178:181], v[224:227], v[0:3]
	v_mfma_f32_16x16x32_bf16 v[56:59], v[174:177], v[198:201], v[56:59]
	v_mfma_f32_16x16x32_bf16 v[52:55], v[182:185], v[198:201], v[52:55]
	v_mfma_f32_16x16x32_bf16 v[40:43], v[174:177], v[206:209], v[38:41]
	v_mfma_f32_16x16x32_bf16 v[36:39], v[182:185], v[206:209], v[34:37]
	v_mfma_f32_16x16x32_bf16 v[20:23], v[174:177], v[220:223], v[20:23]
	v_mfma_f32_16x16x32_bf16 v[16:19], v[182:185], v[220:223], v[16:19]
	v_mfma_f32_16x16x32_bf16 v[4:7], v[174:177], v[228:231], v[4:7]
	v_mfma_f32_16x16x32_bf16 v[0:3], v[182:185], v[228:231], v[0:3]
	s_setprio 0
	s_barrier
	s_add_i32 s21, s21, 2
	s_add_u32 s38, s38, 0x100
	s_addc_u32 s39, s39, 0
	s_add_u32 s19, s19, 0x100
	s_addc_u32 s20, s20, 0
	s_cmp_gt_u32 s21, 13
	s_cbranch_scc0 .LBB0_382
	s_and_b64 vcc, exec, s[52:53]
	s_cbranch_vccz .LBB0_385
	s_barrier

.LBB0_982:
	s_add_i32 s2, s41, 16
	s_cmp_lt_i32 s2, s29
	s_cselect_b32 s2, s2, s41
	s_lshl_b32 s2, s2, 4
	s_add_i32 s2, s2, s23
	v_or_b32_e32 v24, s2, v132
	v_cmp_gt_i32_e32 vcc, s28, v24
	v_mov_b32_e32 v25, s2
	s_min_i32 s2, s17, 47
	v_cndmask_b32_e32 v24, v25, v24, vcc
	s_ashr_i32 s3, s2, 3
	v_ashrrev_i32_e32 v25, 31, v24
	s_lshl_b32 s3, s3, 2
	v_readlane_b32 s18, v254, 24
	v_lshl_add_u64 v[24:25], v[24:25], 2, s[46:47]
	s_add_i32 s3, s18, s3
	global_load_dword v233, v[24:25], off
	v_mov_b32_e32 v24, s3
	ds_read_b32 v24, v24
	s_lshl_b32 s2, s2, 4
	s_and_b32 s2, s2, 0x70
	v_readlane_b32 s48, v251, 1
	v_readlane_b32 s52, v251, 5
	s_waitcnt lgkmcnt(0)
	v_lshlrev_b32_e32 v24, 7, v24
	v_or_b32_e32 v24, s2, v24
	s_min_i32 s2, s17, 46
	s_add_i32 s2, s2, 1
	s_ashr_i32 s3, s2, 3
	s_lshl_b32 s3, s3, 2
	s_add_i32 s3, s18, s3
	s_waitcnt vmcnt(3)
	v_mov_b32_e32 v28, s3
	ds_read_b32 v28, v28
	s_lshl_b32 s2, s2, 4
	s_and_b32 s2, s2, 0x70
	v_add_u32_e32 v24, v24, v186
	v_ashrrev_i32_e32 v25, 31, v24
	s_waitcnt lgkmcnt(0)
	v_lshlrev_b32_e32 v28, 7, v28
	v_or_b32_e32 v28, s2, v28
	v_add_u32_e32 v28, v28, v186
	v_ashrrev_i32_e32 v29, 31, v28
	v_lshlrev_b64 v[24:25], 11, v[24:25]
	v_lshlrev_b64 v[28:29], 11, v[28:29]
	v_or_b32_e32 v24, v24, v227
	v_readlane_b32 s53, v251, 6
	v_readlane_b32 s54, v251, 7
	v_readlane_b32 s55, v251, 8
	v_or_b32_e32 v28, v28, v227
	v_lshl_add_u64 v[26:27], s[52:53], 0, v[24:25]
	v_lshl_add_u64 v[24:25], s[54:55], 0, v[24:25]
	v_lshl_add_u64 v[30:31], s[52:53], 0, v[28:29]
	v_lshl_add_u64 v[28:29], s[54:55], 0, v[28:29]
	global_load_dwordx4 v[34:37], v[26:27], off
	global_load_dwordx4 v[38:41], v[30:31], off
	v_and_b32_e32 v32, 0x1fff, v220
	global_load_dwordx4 v[24:27], v[24:25], off
	v_readlane_b32 s49, v251, 2
	global_load_dwordx4 v[28:31], v[28:29], off
	ds_read_b128 v[42:45], v136
	ds_read_b128 v[46:49], v137
	ds_read_b128 v[50:53], v228
	ds_read_b128 v[54:57], v229
	ds_read_b128 v[58:61], v136 offset:1024
	ds_read_b128 v[62:65], v137 offset:1024
	ds_read_b128 v[66:69], v228 offset:1024
	ds_read_b128 v[70:73], v229 offset:1024
	v_readlane_b32 s50, v251, 3
	v_readlane_b32 s51, v251, 4
	v_readlane_b32 s56, v251, 9
	v_readlane_b32 s57, v251, 10
	v_readlane_b32 s58, v251, 11
	v_readlane_b32 s59, v251, 12
	v_readlane_b32 s60, v251, 13
	v_readlane_b32 s61, v251, 14
	v_readlane_b32 s62, v251, 15
	v_readlane_b32 s63, v251, 16
	v_lshrrev_b32_e32 v118, 14, v220
	v_or_b32_e32 v120, s30, v32
	s_waitcnt lgkmcnt(7)
	v_mfma_f32_16x16x32_bf16 v[42:45], v[42:45], v[8:11], 0
	s_waitcnt lgkmcnt(6)
	v_mfma_f32_16x16x32_bf16 v[42:45], v[46:49], v[12:15], v[42:45]
	s_waitcnt lgkmcnt(5)
	v_mfma_f32_16x16x32_bf16 v[42:45], v[50:53], v[16:19], v[42:45]
	s_waitcnt vmcnt(5) lgkmcnt(4)
	v_mfma_f32_16x16x32_bf16 v[114:117], v[54:57], v[20:23], v[42:45]
	s_waitcnt lgkmcnt(3)
	v_mfma_f32_16x16x32_bf16 v[42:45], v[58:61], v[8:11], 0
	s_waitcnt lgkmcnt(2)
	v_mfma_f32_16x16x32_bf16 v[42:45], v[62:65], v[12:15], v[42:45]
	s_waitcnt lgkmcnt(1)
	v_mfma_f32_16x16x32_bf16 v[42:45], v[66:69], v[16:19], v[42:45]
	s_waitcnt lgkmcnt(0)
	v_mfma_f32_16x16x32_bf16 v[110:113], v[70:73], v[20:23], v[42:45]
	s_nop 5
	ds_read_b128 v[42:45], v136 offset:8192
	ds_read_b128 v[46:49], v136 offset:9216
	ds_read_b128 v[50:53], v137 offset:8192
	ds_read_b128 v[54:57], v137 offset:9216
	ds_read_b128 v[58:61], v228 offset:8192
	ds_read_b128 v[62:65], v228 offset:9216
	ds_read_b128 v[66:69], v229 offset:8192
	ds_read_b128 v[70:73], v229 offset:9216
	s_waitcnt lgkmcnt(7)
	v_mfma_f32_16x16x32_bf16 v[42:45], v[42:45], v[8:11], 0
	s_waitcnt lgkmcnt(5)
	v_mfma_f32_16x16x32_bf16 v[42:45], v[50:53], v[12:15], v[42:45]
	s_waitcnt lgkmcnt(3)
	v_mfma_f32_16x16x32_bf16 v[42:45], v[58:61], v[16:19], v[42:45]
	s_waitcnt lgkmcnt(1)
	v_mfma_f32_16x16x32_bf16 v[106:109], v[66:69], v[20:23], v[42:45]
	v_mfma_f32_16x16x32_bf16 v[42:45], v[46:49], v[8:11], 0
	v_mfma_f32_16x16x32_bf16 v[42:45], v[54:57], v[12:15], v[42:45]
	v_mfma_f32_16x16x32_bf16 v[42:45], v[62:65], v[16:19], v[42:45]
	s_waitcnt lgkmcnt(0)
	v_mfma_f32_16x16x32_bf16 v[102:105], v[70:73], v[20:23], v[42:45]
	s_nop 5
	ds_read_b128 v[42:45], v136 offset:16384
	ds_read_b128 v[46:49], v136 offset:17408
	ds_read_b128 v[50:53], v137 offset:16384
	ds_read_b128 v[54:57], v137 offset:17408
	ds_read_b128 v[58:61], v228 offset:16384
	ds_read_b128 v[62:65], v228 offset:17408
	ds_read_b128 v[66:69], v229 offset:16384
	ds_read_b128 v[70:73], v229 offset:17408
	s_waitcnt lgkmcnt(7)
	v_mfma_f32_16x16x32_bf16 v[42:45], v[42:45], v[8:11], 0
	s_waitcnt lgkmcnt(5)
	v_mfma_f32_16x16x32_bf16 v[42:45], v[50:53], v[12:15], v[42:45]
	s_waitcnt lgkmcnt(3)
	v_mfma_f32_16x16x32_bf16 v[42:45], v[58:61], v[16:19], v[42:45]
	s_waitcnt lgkmcnt(1)
	v_mfma_f32_16x16x32_bf16 v[98:101], v[66:69], v[20:23], v[42:45]
	v_mfma_f32_16x16x32_bf16 v[42:45], v[46:49], v[8:11], 0
	v_mfma_f32_16x16x32_bf16 v[42:45], v[54:57], v[12:15], v[42:45]
	v_mfma_f32_16x16x32_bf16 v[42:45], v[62:65], v[16:19], v[42:45]
	s_waitcnt lgkmcnt(0)
	v_mfma_f32_16x16x32_bf16 v[94:97], v[70:73], v[20:23], v[42:45]
	s_nop 5
	ds_read_b128 v[42:45], v136 offset:24576
	ds_read_b128 v[46:49], v136 offset:25600
	ds_read_b128 v[50:53], v137 offset:24576
	ds_read_b128 v[54:57], v137 offset:25600
	ds_read_b128 v[58:61], v228 offset:24576
	ds_read_b128 v[62:65], v228 offset:25600
	ds_read_b128 v[66:69], v229 offset:24576
	ds_read_b128 v[70:73], v229 offset:25600
	s_waitcnt lgkmcnt(7)
	v_mfma_f32_16x16x32_bf16 v[42:45], v[42:45], v[8:11], 0
	s_waitcnt lgkmcnt(5)
	v_mfma_f32_16x16x32_bf16 v[42:45], v[50:53], v[12:15], v[42:45]
	s_waitcnt lgkmcnt(3)
	v_mfma_f32_16x16x32_bf16 v[42:45], v[58:61], v[16:19], v[42:45]
	s_waitcnt lgkmcnt(1)
	v_mfma_f32_16x16x32_bf16 v[90:93], v[66:69], v[20:23], v[42:45]
	v_mfma_f32_16x16x32_bf16 v[42:45], v[46:49], v[8:11], 0
	v_mfma_f32_16x16x32_bf16 v[42:45], v[54:57], v[12:15], v[42:45]
	v_mfma_f32_16x16x32_bf16 v[42:45], v[62:65], v[16:19], v[42:45]
	s_waitcnt lgkmcnt(0)
	v_mfma_f32_16x16x32_bf16 v[86:89], v[70:73], v[20:23], v[42:45]
	s_nop 5
	ds_read_b128 v[42:45], v136 offset:32768
	ds_read_b128 v[46:49], v136 offset:33792
	ds_read_b128 v[50:53], v137 offset:32768
	ds_read_b128 v[54:57], v137 offset:33792
	ds_read_b128 v[58:61], v228 offset:32768
	ds_read_b128 v[62:65], v228 offset:33792
	ds_read_b128 v[66:69], v229 offset:32768
	ds_read_b128 v[70:73], v229 offset:33792
	s_waitcnt lgkmcnt(7)
	v_mfma_f32_16x16x32_bf16 v[42:45], v[42:45], v[8:11], 0
	s_waitcnt lgkmcnt(5)
	v_mfma_f32_16x16x32_bf16 v[42:45], v[50:53], v[12:15], v[42:45]
	s_waitcnt lgkmcnt(3)
	v_mfma_f32_16x16x32_bf16 v[42:45], v[58:61], v[16:19], v[42:45]
	s_waitcnt lgkmcnt(1)
	v_mfma_f32_16x16x32_bf16 v[82:85], v[66:69], v[20:23], v[42:45]
	v_mfma_f32_16x16x32_bf16 v[42:45], v[46:49], v[8:11], 0
	v_mfma_f32_16x16x32_bf16 v[42:45], v[54:57], v[12:15], v[42:45]
	v_mfma_f32_16x16x32_bf16 v[42:45], v[62:65], v[16:19], v[42:45]
	s_waitcnt lgkmcnt(0)
	v_mfma_f32_16x16x32_bf16 v[78:81], v[70:73], v[20:23], v[42:45]
	s_nop 5
	ds_read_b128 v[42:45], v136 offset:40960
	ds_read_b128 v[46:49], v136 offset:41984
	ds_read_b128 v[50:53], v137 offset:40960
	ds_read_b128 v[54:57], v137 offset:41984
	ds_read_b128 v[58:61], v228 offset:40960
	ds_read_b128 v[62:65], v228 offset:41984
	ds_read_b128 v[66:69], v229 offset:40960
	ds_read_b128 v[70:73], v229 offset:41984
	s_waitcnt lgkmcnt(7)
	v_mfma_f32_16x16x32_bf16 v[42:45], v[42:45], v[8:11], 0
	s_waitcnt lgkmcnt(5)
	v_mfma_f32_16x16x32_bf16 v[42:45], v[50:53], v[12:15], v[42:45]
	s_waitcnt lgkmcnt(3)
	v_mfma_f32_16x16x32_bf16 v[42:45], v[58:61], v[16:19], v[42:45]
	s_waitcnt lgkmcnt(1)
	v_mfma_f32_16x16x32_bf16 v[74:77], v[66:69], v[20:23], v[42:45]
	v_mfma_f32_16x16x32_bf16 v[42:45], v[46:49], v[8:11], 0
	v_mfma_f32_16x16x32_bf16 v[42:45], v[54:57], v[12:15], v[42:45]
	v_mfma_f32_16x16x32_bf16 v[42:45], v[62:65], v[16:19], v[42:45]
	s_waitcnt lgkmcnt(0)
	v_mfma_f32_16x16x32_bf16 v[70:73], v[70:73], v[20:23], v[42:45]
	s_nop 5
	ds_read_b128 v[42:45], v136 offset:49152
	ds_read_b128 v[46:49], v136 offset:50176
	ds_read_b128 v[50:53], v137 offset:49152
	ds_read_b128 v[54:57], v137 offset:50176
	ds_read_b128 v[58:61], v228 offset:49152
	ds_read_b128 v[62:65], v228 offset:50176
	ds_read_b128 v[66:69], v229 offset:49152
	ds_read_b128 v[234:237], v229 offset:50176
	s_waitcnt lgkmcnt(7)
	v_mfma_f32_16x16x32_bf16 v[42:45], v[42:45], v[8:11], 0
	s_waitcnt lgkmcnt(5)
	v_mfma_f32_16x16x32_bf16 v[42:45], v[50:53], v[12:15], v[42:45]
	s_waitcnt lgkmcnt(3)
	v_mfma_f32_16x16x32_bf16 v[42:45], v[58:61], v[16:19], v[42:45]
	s_waitcnt lgkmcnt(1)
	v_mfma_f32_16x16x32_bf16 v[66:69], v[66:69], v[20:23], v[42:45]
	v_mfma_f32_16x16x32_bf16 v[42:45], v[46:49], v[8:11], 0
	v_mfma_f32_16x16x32_bf16 v[42:45], v[54:57], v[12:15], v[42:45]
	v_mfma_f32_16x16x32_bf16 v[42:45], v[62:65], v[16:19], v[42:45]
	s_waitcnt lgkmcnt(0)
	v_mfma_f32_16x16x32_bf16 v[62:65], v[234:237], v[20:23], v[42:45]
	s_nop 5
	ds_read_b128 v[42:45], v136 offset:57344
	ds_read_b128 v[46:49], v136 offset:58368
	ds_read_b128 v[50:53], v137 offset:57344
	ds_read_b128 v[54:57], v137 offset:58368
	ds_read_b128 v[58:61], v228 offset:57344
	ds_read_b128 v[234:237], v228 offset:58368
	ds_read_b128 v[238:241], v229 offset:57344
	ds_read_b128 v[242:245], v229 offset:58368
	s_waitcnt lgkmcnt(7)
	v_mfma_f32_16x16x32_bf16 v[42:45], v[42:45], v[8:11], 0
	s_waitcnt lgkmcnt(6)
	v_mfma_f32_16x16x32_bf16 v[8:11], v[46:49], v[8:11], 0
	s_waitcnt lgkmcnt(4)
	v_mfma_f32_16x16x32_bf16 v[8:11], v[54:57], v[12:15], v[8:11]
	v_mfma_f32_16x16x32_bf16 v[42:45], v[50:53], v[12:15], v[42:45]
	s_waitcnt lgkmcnt(2)
	v_mfma_f32_16x16x32_bf16 v[8:11], v[234:237], v[16:19], v[8:11]
	v_mfma_f32_16x16x32_bf16 v[42:45], v[58:61], v[16:19], v[42:45]
	s_waitcnt lgkmcnt(0)
	v_mfma_f32_16x16x32_bf16 v[8:11], v[242:245], v[20:23], v[8:11]
	v_mfma_f32_16x16x32_bf16 v[58:61], v[238:241], v[20:23], v[42:45]
	v_max3_f32 v12, v217, v114, v115
	v_max3_f32 v13, v218, v116, v117
	s_nop 4
	ds_read_b128 v[42:45], v133
	ds_read_b128 v[46:49], v133 offset:8704
	ds_read_b128 v[50:53], v133 offset:17408
	ds_read_b128 v[54:57], v133 offset:26112
	v_max3_f32 v12, v12, v110, v111
	v_max3_f32 v13, v13, v112, v113
	v_max3_f32 v12, v12, v106, v107
	v_max3_f32 v13, v13, v108, v109
	v_max3_f32 v12, v12, v102, v103
	v_max3_f32 v13, v13, v104, v105
	v_max3_f32 v12, v12, v98, v99
	v_max3_f32 v13, v13, v100, v101
	v_max3_f32 v12, v12, v94, v95
	v_max3_f32 v13, v13, v96, v97
	v_max3_f32 v12, v12, v90, v91
	v_max3_f32 v13, v13, v92, v93
	v_max3_f32 v12, v12, v86, v87
	v_max3_f32 v13, v13, v88, v89
	v_max3_f32 v12, v12, v82, v83
	v_max3_f32 v13, v13, v84, v85
	v_max3_f32 v12, v12, v78, v79
	v_max3_f32 v13, v13, v80, v81
	v_max3_f32 v12, v12, v74, v75
	v_max3_f32 v13, v13, v76, v77
	v_max3_f32 v12, v12, v70, v71
	v_max3_f32 v13, v13, v72, v73
	v_max3_f32 v12, v12, v66, v67
	v_max3_f32 v13, v13, v68, v69
	v_max3_f32 v12, v12, v62, v63
	v_max3_f32 v13, v13, v64, v65
	v_max3_f32 v12, v12, v58, v59
	v_max3_f32 v13, v13, v60, v61
	v_max3_f32 v12, v12, v8, v9
	v_max3_f32 v13, v13, v10, v11
	v_max_f32 v12, v12, v13
	v_mov_b32_e32 v13, v12
	s_nop 1
	v_permlane16_swap_b32_e32 v13, v12
	s_waitcnt lgkmcnt(0)
	v_max_f32 v12, v12, v13
	v_mov_b32_e32 v13, v12
	s_nop 1
	v_permlane32_swap_b32_e32 v13, v12
	s_waitcnt lgkmcnt(0)
	v_max_f32 v130, v12, v13
	s_nop 0
	v_mov_b32_e32 v131, v130
	v_pk_add_f32 v[12:13], v[114:115], v[130:131] neg_lo:[0,1] neg_hi:[0,1]
	v_pk_add_f32 v[14:15], v[116:117], v[130:131] neg_lo:[0,1] neg_hi:[0,1]
	v_pk_add_f32 v[16:17], v[110:111], v[130:131] neg_lo:[0,1] neg_hi:[0,1]
	v_pk_add_f32 v[18:19], v[112:113], v[130:131] neg_lo:[0,1] neg_hi:[0,1]
	v_pk_add_f32 v[102:103], v[102:103], v[130:131] neg_lo:[0,1] neg_hi:[0,1]
	v_pk_add_f32 v[104:105], v[104:105], v[130:131] neg_lo:[0,1] neg_hi:[0,1]
	s_nop 0
	v_exp_f32_e32 v12, v12
	v_exp_f32_e32 v13, v13
	v_exp_f32_e32 v14, v14
	v_exp_f32_e32 v15, v15
	v_exp_f32_e32 v16, v16
	v_exp_f32_e32 v18, v18
	v_exp_f32_e32 v19, v19
	v_exp_f32_e32 v17, v17
	v_pk_add_f32 v[20:21], v[12:13], 0 op_sel_hi:[1,0]
	v_pk_add_f32 v[22:23], v[14:15], 0 op_sel_hi:[1,0]
	v_exp_f32_e32 v102, v102
	v_pk_add_f32 v[110:111], v[22:23], v[18:19]
	v_pk_add_f32 v[112:113], v[20:21], v[16:17]
	v_pk_add_f32 v[20:21], v[106:107], v[130:131] neg_lo:[0,1] neg_hi:[0,1]
	v_pk_add_f32 v[22:23], v[108:109], v[130:131] neg_lo:[0,1] neg_hi:[0,1]
	v_exp_f32_e32 v104, v104
	v_exp_f32_e32 v20, v20
	v_exp_f32_e32 v21, v21
	v_exp_f32_e32 v22, v22
	v_exp_f32_e32 v23, v23
	v_exp_f32_e32 v105, v105
	v_exp_f32_e32 v103, v103
	v_pk_add_f32 v[98:99], v[98:99], v[130:131] neg_lo:[0,1] neg_hi:[0,1]
	v_pk_add_f32 v[100:101], v[100:101], v[130:131] neg_lo:[0,1] neg_hi:[0,1]
	v_pk_add_f32 v[94:95], v[94:95], v[130:131] neg_lo:[0,1] neg_hi:[0,1]
	v_pk_add_f32 v[96:97], v[96:97], v[130:131] neg_lo:[0,1] neg_hi:[0,1]
	v_pk_add_f32 v[90:91], v[90:91], v[130:131] neg_lo:[0,1] neg_hi:[0,1]
	v_pk_add_f32 v[92:93], v[92:93], v[130:131] neg_lo:[0,1] neg_hi:[0,1]
	s_nop 0
	v_exp_f32_e32 v98, v98
	v_exp_f32_e32 v99, v99
	v_exp_f32_e32 v100, v100
	v_exp_f32_e32 v101, v101
	v_exp_f32_e32 v94, v94
	v_exp_f32_e32 v96, v96
	v_exp_f32_e32 v97, v97
	v_exp_f32_e32 v95, v95
	v_pk_add_f32 v[106:107], v[112:113], v[20:21]
	v_pk_add_f32 v[108:109], v[110:111], v[22:23]
	v_exp_f32_e32 v90, v90
	v_exp_f32_e32 v91, v91
	v_exp_f32_e32 v92, v92
	v_exp_f32_e32 v93, v93
	v_pk_add_f32 v[108:109], v[108:109], v[104:105]
	v_pk_add_f32 v[106:107], v[106:107], v[102:103]
	v_pk_add_f32 v[108:109], v[108:109], v[100:101]
	v_pk_add_f32 v[106:107], v[106:107], v[98:99]
	v_pk_add_f32 v[108:109], v[108:109], v[96:97]
	v_pk_add_f32 v[106:107], v[106:107], v[94:95]
	v_pk_add_f32 v[86:87], v[86:87], v[130:131] neg_lo:[0,1] neg_hi:[0,1]
	v_pk_add_f32 v[88:89], v[88:89], v[130:131] neg_lo:[0,1] neg_hi:[0,1]
	v_pk_add_f32 v[82:83], v[82:83], v[130:131] neg_lo:[0,1] neg_hi:[0,1]
	v_pk_add_f32 v[84:85], v[84:85], v[130:131] neg_lo:[0,1] neg_hi:[0,1]
	v_pk_add_f32 v[78:79], v[78:79], v[130:131] neg_lo:[0,1] neg_hi:[0,1]
	v_pk_add_f32 v[80:81], v[80:81], v[130:131] neg_lo:[0,1] neg_hi:[0,1]
	s_nop 0
	v_exp_f32_e32 v110, v86
	v_exp_f32_e32 v112, v88
	v_exp_f32_e32 v113, v89
	v_exp_f32_e32 v111, v87
	v_pk_add_f32 v[86:87], v[106:107], v[90:91]
	v_pk_add_f32 v[88:89], v[108:109], v[92:93]
	v_exp_f32_e32 v106, v82
	v_exp_f32_e32 v107, v83
	v_exp_f32_e32 v108, v84
	v_exp_f32_e32 v109, v85
	v_exp_f32_e32 v114, v78
	v_exp_f32_e32 v116, v80
	v_exp_f32_e32 v117, v81
	v_exp_f32_e32 v115, v79
	v_pk_add_f32 v[74:75], v[74:75], v[130:131] neg_lo:[0,1] neg_hi:[0,1]
	v_pk_add_f32 v[76:77], v[76:77], v[130:131] neg_lo:[0,1] neg_hi:[0,1]
	v_pk_add_f32 v[88:89], v[88:89], v[112:113]
	v_exp_f32_e32 v188, v74
	v_exp_f32_e32 v189, v75
	v_exp_f32_e32 v234, v76
	v_exp_f32_e32 v235, v77
	v_pk_add_f32 v[86:87], v[86:87], v[110:111]
	v_pk_add_f32 v[70:71], v[70:71], v[130:131] neg_lo:[0,1] neg_hi:[0,1]
	v_pk_add_f32 v[72:73], v[72:73], v[130:131] neg_lo:[0,1] neg_hi:[0,1]
	v_pk_add_f32 v[80:81], v[88:89], v[108:109]
	v_exp_f32_e32 v236, v70
	v_exp_f32_e32 v238, v72
	v_exp_f32_e32 v239, v73
	v_exp_f32_e32 v237, v71
	v_pk_add_f32 v[78:79], v[86:87], v[106:107]
	v_pk_add_f32 v[66:67], v[66:67], v[130:131] neg_lo:[0,1] neg_hi:[0,1]
	v_pk_add_f32 v[68:69], v[68:69], v[130:131] neg_lo:[0,1] neg_hi:[0,1]
	v_pk_add_f32 v[80:81], v[80:81], v[116:117]
	v_exp_f32_e32 v240, v66
	v_exp_f32_e32 v241, v67
	v_exp_f32_e32 v242, v68
	v_exp_f32_e32 v243, v69
	v_pk_add_f32 v[78:79], v[78:79], v[114:115]
	v_pk_add_f32 v[62:63], v[62:63], v[130:131] neg_lo:[0,1] neg_hi:[0,1]
	v_pk_add_f32 v[64:65], v[64:65], v[130:131] neg_lo:[0,1] neg_hi:[0,1]
	v_pk_add_f32 v[72:73], v[80:81], v[234:235]
	v_exp_f32_e32 v244, v62
	v_exp_f32_e32 v246, v64
	v_exp_f32_e32 v247, v65
	v_exp_f32_e32 v245, v63
	v_pk_add_f32 v[70:71], v[78:79], v[188:189]
	v_pk_add_f32 v[58:59], v[58:59], v[130:131] neg_lo:[0,1] neg_hi:[0,1]
	v_pk_add_f32 v[60:61], v[60:61], v[130:131] neg_lo:[0,1] neg_hi:[0,1]
	v_pk_add_f32 v[8:9], v[8:9], v[130:131] neg_lo:[0,1] neg_hi:[0,1]
	v_pk_add_f32 v[10:11], v[10:11], v[130:131] neg_lo:[0,1] neg_hi:[0,1]
	v_pk_add_f32 v[72:73], v[72:73], v[238:239]
	v_exp_f32_e32 v248, v58
	v_exp_f32_e32 v249, v59
	v_exp_f32_e32 v158, v60
	v_exp_f32_e32 v159, v61
	v_pk_add_f32 v[70:71], v[70:71], v[236:237]
	v_exp_f32_e32 v8, v8
	v_exp_f32_e32 v10, v10
	v_exp_f32_e32 v11, v11
	v_exp_f32_e32 v9, v9
	v_pk_add_f32 v[62:63], v[70:71], v[240:241]
	v_pk_add_f32 v[64:65], v[72:73], v[242:243]
	v_pk_add_f32 v[62:63], v[62:63], v[244:245]
	v_pk_add_f32 v[64:65], v[64:65], v[246:247]
	v_pk_add_f32 v[58:59], v[62:63], v[248:249]
	v_pk_add_f32 v[60:61], v[64:65], v[158:159]
	v_pk_add_f32 v[58:59], v[58:59], v[8:9]
	v_pk_add_f32 v[60:61], v[60:61], v[10:11]
	s_nop 0
	v_pk_mov_b32 v[62:63], v[58:59], v[60:61] op_sel:[1,0]
	v_mov_b32_e32 v59, v61
	v_pk_add_f32 v[58:59], v[62:63], v[58:59]
	s_nop 0
	v_add_f32_e32 v32, v58, v59
	ds_read_b128 v[58:61], v133 offset:34816
	ds_read_b128 v[62:65], v133 offset:43520
	ds_read_b128 v[66:69], v133 offset:52224
	ds_read_b128 v[70:73], v133 offset:60928
	v_mov_b32_e32 v74, v32
	s_nop 1
	v_permlane16_swap_b32_e32 v74, v32
	s_waitcnt lgkmcnt(0)
	v_add_f32_e32 v119, v32, v74
	v_cvt_pk_bf16_f32 v74, v12, v13
	v_cvt_pk_bf16_f32 v75, v14, v15
	v_cvt_pk_bf16_f32 v76, v16, v17
	v_cvt_pk_bf16_f32 v77, v18, v19
	v_cvt_pk_bf16_f32 v78, v20, v21
	v_cvt_pk_bf16_f32 v79, v22, v23
	v_cvt_pk_bf16_f32 v80, v102, v103
	v_cvt_pk_bf16_f32 v81, v104, v105
	v_cvt_pk_bf16_f32 v82, v98, v99
	v_cvt_pk_bf16_f32 v83, v100, v101
	v_cvt_pk_bf16_f32 v84, v94, v95
	v_cvt_pk_bf16_f32 v85, v96, v97
	v_cvt_pk_bf16_f32 v86, v90, v91
	v_cvt_pk_bf16_f32 v87, v92, v93
	v_cvt_pk_bf16_f32 v88, v110, v111
	v_cvt_pk_bf16_f32 v89, v112, v113
	v_cvt_pk_bf16_f32 v90, v106, v107
	v_cvt_pk_bf16_f32 v91, v108, v109
	v_cvt_pk_bf16_f32 v92, v114, v115
	v_cvt_pk_bf16_f32 v93, v116, v117
	v_cvt_pk_bf16_f32 v94, v188, v189
	v_cvt_pk_bf16_f32 v95, v234, v235
	v_cvt_pk_bf16_f32 v96, v236, v237
	v_cvt_pk_bf16_f32 v97, v238, v239
	v_cvt_pk_bf16_f32 v98, v240, v241
	v_cvt_pk_bf16_f32 v99, v242, v243
	v_cvt_pk_bf16_f32 v100, v244, v245
	v_cvt_pk_bf16_f32 v101, v246, v247
	v_mov_b32_e32 v106, v119
	s_nop 1
	v_permlane32_swap_b32_e32 v106, v119
	v_cvt_pk_bf16_f32 v102, v248, v249
	v_cvt_pk_bf16_f32 v103, v158, v159
	v_cvt_pk_bf16_f32 v104, v8, v9
	v_cvt_pk_bf16_f32 v105, v10, v11
	v_and_b32_e32 v8, 0x1fff, v230
	v_or_b32_e32 v8, s30, v8
	v_ashrrev_i32_e32 v9, 31, v8
	v_lshrrev_b32_e32 v10, 13, v230
	v_lshlrev_b64 v[8:9], 11, v[8:9]
	v_and_or_b32 v10, v10, 1, s31
	v_lshl_add_u64 v[8:9], s[4:5], 0, v[8:9]
	v_lshlrev_b32_e32 v32, 8, v10
	v_lshl_add_u64 v[8:9], v[8:9], 0, v[32:33]
	v_mov_b32_e32 v129, v33
	v_lshl_add_u64 v[20:21], v[8:9], 0, v[128:129]
	global_load_dwordx4 v[8:11], v[20:21], off
	global_load_dwordx4 v[12:15], v[20:21], off offset:64
	global_load_dwordx4 v[16:19], v[20:21], off offset:128
	s_nop 0
	global_load_dwordx4 v[20:23], v[20:21], off offset:192
	s_waitcnt lgkmcnt(0)
	v_add_f32_e32 v131, v119, v106
	v_bfe_u32 v129, v220, 13, 1
	v_ashrrev_i32_e32 v121, 31, v120
	v_mfma_f32_16x16x32_bf16 v[42:45], v[42:45], v[74:77], 0
	v_mfma_f32_16x16x32_bf16 v[46:49], v[46:49], v[74:77], 0
	v_mfma_f32_16x16x32_bf16 v[50:53], v[50:53], v[74:77], 0
	v_mfma_f32_16x16x32_bf16 v[54:57], v[54:57], v[74:77], 0
	v_mfma_f32_16x16x32_bf16 v[58:61], v[58:61], v[74:77], 0
	v_mfma_f32_16x16x32_bf16 v[62:65], v[62:65], v[74:77], 0
	v_mfma_f32_16x16x32_bf16 v[66:69], v[66:69], v[74:77], 0
	v_mfma_f32_16x16x32_bf16 v[70:73], v[70:73], v[74:77], 0
	ds_read_b128 v[74:77], v133 offset:64
	ds_read_b128 v[106:109], v133 offset:8768
	ds_read_b128 v[110:113], v133 offset:17472
	ds_read_b128 v[114:117], v133 offset:26176
	ds_read_b128 v[234:237], v133 offset:34880
	ds_read_b128 v[238:241], v133 offset:43584
	ds_read_b128 v[242:245], v133 offset:52288
	ds_read_b128 v[246:249], v133 offset:60992
	s_waitcnt lgkmcnt(7)
	v_mfma_f32_16x16x32_bf16 v[42:45], v[74:77], v[78:81], v[42:45]
	s_waitcnt lgkmcnt(6)
	v_mfma_f32_16x16x32_bf16 v[46:49], v[106:109], v[78:81], v[46:49]
	s_waitcnt lgkmcnt(5)
	v_mfma_f32_16x16x32_bf16 v[50:53], v[110:113], v[78:81], v[50:53]
	s_waitcnt lgkmcnt(4)
	v_mfma_f32_16x16x32_bf16 v[54:57], v[114:117], v[78:81], v[54:57]
	s_waitcnt lgkmcnt(3)
	v_mfma_f32_16x16x32_bf16 v[58:61], v[234:237], v[78:81], v[58:61]
	s_waitcnt lgkmcnt(2)
	v_mfma_f32_16x16x32_bf16 v[62:65], v[238:241], v[78:81], v[62:65]
	s_waitcnt lgkmcnt(1)
	v_mfma_f32_16x16x32_bf16 v[66:69], v[242:245], v[78:81], v[66:69]
	s_waitcnt lgkmcnt(0)
	v_mfma_f32_16x16x32_bf16 v[70:73], v[246:249], v[78:81], v[70:73]
	ds_read_b128 v[74:77], v133 offset:128
	ds_read_b128 v[78:81], v133 offset:8832
	ds_read_b128 v[106:109], v133 offset:17536
	ds_read_b128 v[110:113], v133 offset:26240
	ds_read_b128 v[114:117], v133 offset:34944
	ds_read_b128 v[234:237], v133 offset:43648
	ds_read_b128 v[238:241], v133 offset:52352
	ds_read_b128 v[242:245], v133 offset:61056
	s_waitcnt lgkmcnt(7)
	v_mfma_f32_16x16x32_bf16 v[42:45], v[74:77], v[82:85], v[42:45]
	s_waitcnt lgkmcnt(6)
	v_mfma_f32_16x16x32_bf16 v[46:49], v[78:81], v[82:85], v[46:49]
	s_waitcnt lgkmcnt(5)
	v_mfma_f32_16x16x32_bf16 v[50:53], v[106:109], v[82:85], v[50:53]
	s_waitcnt lgkmcnt(4)
	v_mfma_f32_16x16x32_bf16 v[54:57], v[110:113], v[82:85], v[54:57]
	s_waitcnt lgkmcnt(3)
	v_mfma_f32_16x16x32_bf16 v[58:61], v[114:117], v[82:85], v[58:61]
	s_waitcnt lgkmcnt(2)
	v_mfma_f32_16x16x32_bf16 v[62:65], v[234:237], v[82:85], v[62:65]
	s_waitcnt lgkmcnt(1)
	v_mfma_f32_16x16x32_bf16 v[66:69], v[238:241], v[82:85], v[66:69]
	s_waitcnt lgkmcnt(0)
	v_mfma_f32_16x16x32_bf16 v[70:73], v[242:245], v[82:85], v[70:73]
	ds_read_b128 v[74:77], v133 offset:192
	ds_read_b128 v[78:81], v133 offset:8896
	ds_read_b128 v[82:85], v133 offset:17600
	ds_read_b128 v[106:109], v133 offset:26304
	ds_read_b128 v[110:113], v133 offset:35008
	ds_read_b128 v[114:117], v133 offset:43712
	ds_read_b128 v[234:237], v133 offset:52416
	ds_read_b128 v[238:241], v133 offset:61120
	s_waitcnt lgkmcnt(7)
	v_mfma_f32_16x16x32_bf16 v[42:45], v[74:77], v[86:89], v[42:45]
	s_waitcnt lgkmcnt(6)
	v_mfma_f32_16x16x32_bf16 v[46:49], v[78:81], v[86:89], v[46:49]
	s_waitcnt lgkmcnt(5)
	v_mfma_f32_16x16x32_bf16 v[50:53], v[82:85], v[86:89], v[50:53]
	s_waitcnt lgkmcnt(4)
	v_mfma_f32_16x16x32_bf16 v[54:57], v[106:109], v[86:89], v[54:57]
	s_waitcnt lgkmcnt(3)
	v_mfma_f32_16x16x32_bf16 v[58:61], v[110:113], v[86:89], v[58:61]
	s_waitcnt lgkmcnt(2)
	v_mfma_f32_16x16x32_bf16 v[62:65], v[114:117], v[86:89], v[62:65]
	s_waitcnt lgkmcnt(1)
	v_mfma_f32_16x16x32_bf16 v[66:69], v[234:237], v[86:89], v[66:69]
	s_waitcnt lgkmcnt(0)
	v_mfma_f32_16x16x32_bf16 v[70:73], v[238:241], v[86:89], v[70:73]
	ds_read_b128 v[74:77], v133 offset:256
	ds_read_b128 v[78:81], v133 offset:8960
	ds_read_b128 v[82:85], v133 offset:17664
	ds_read_b128 v[86:89], v133 offset:26368
	ds_read_b128 v[106:109], v133 offset:35072
	ds_read_b128 v[110:113], v133 offset:43776
	ds_read_b128 v[114:117], v133 offset:52480
	ds_read_b128 v[234:237], v133 offset:61184
	s_waitcnt lgkmcnt(7)
	v_mfma_f32_16x16x32_bf16 v[42:45], v[74:77], v[90:93], v[42:45]
	s_waitcnt lgkmcnt(6)
	v_mfma_f32_16x16x32_bf16 v[46:49], v[78:81], v[90:93], v[46:49]
	s_waitcnt lgkmcnt(5)
	v_mfma_f32_16x16x32_bf16 v[50:53], v[82:85], v[90:93], v[50:53]
	s_waitcnt lgkmcnt(4)
	v_mfma_f32_16x16x32_bf16 v[54:57], v[86:89], v[90:93], v[54:57]
	s_waitcnt lgkmcnt(3)
	v_mfma_f32_16x16x32_bf16 v[58:61], v[106:109], v[90:93], v[58:61]
	s_waitcnt lgkmcnt(2)
	v_mfma_f32_16x16x32_bf16 v[62:65], v[110:113], v[90:93], v[62:65]
	s_waitcnt lgkmcnt(1)
	v_mfma_f32_16x16x32_bf16 v[66:69], v[114:117], v[90:93], v[66:69]
	s_waitcnt lgkmcnt(0)
	v_mfma_f32_16x16x32_bf16 v[70:73], v[234:237], v[90:93], v[70:73]
	ds_read_b128 v[74:77], v133 offset:320
	ds_read_b128 v[78:81], v133 offset:9024
	ds_read_b128 v[82:85], v133 offset:17728
	ds_read_b128 v[86:89], v133 offset:26432
	ds_read_b128 v[90:93], v133 offset:35136
	ds_read_b128 v[106:109], v133 offset:43840
	ds_read_b128 v[110:113], v133 offset:52544
	ds_read_b128 v[114:117], v133 offset:61248
	s_waitcnt lgkmcnt(7)
	v_mfma_f32_16x16x32_bf16 v[42:45], v[74:77], v[94:97], v[42:45]
	s_waitcnt lgkmcnt(6)
	v_mfma_f32_16x16x32_bf16 v[46:49], v[78:81], v[94:97], v[46:49]
	s_waitcnt lgkmcnt(5)
	v_mfma_f32_16x16x32_bf16 v[50:53], v[82:85], v[94:97], v[50:53]
	s_waitcnt lgkmcnt(4)
	v_mfma_f32_16x16x32_bf16 v[54:57], v[86:89], v[94:97], v[54:57]
	s_waitcnt lgkmcnt(3)
	v_mfma_f32_16x16x32_bf16 v[58:61], v[90:93], v[94:97], v[58:61]
	s_waitcnt lgkmcnt(2)
	v_mfma_f32_16x16x32_bf16 v[62:65], v[106:109], v[94:97], v[62:65]
	s_waitcnt lgkmcnt(1)
	v_mfma_f32_16x16x32_bf16 v[66:69], v[110:113], v[94:97], v[66:69]
	s_waitcnt lgkmcnt(0)
	v_mfma_f32_16x16x32_bf16 v[70:73], v[114:117], v[94:97], v[70:73]
	ds_read_b128 v[74:77], v133 offset:384
	ds_read_b128 v[78:81], v133 offset:9088
	ds_read_b128 v[82:85], v133 offset:17792
	ds_read_b128 v[86:89], v133 offset:26496
	ds_read_b128 v[90:93], v133 offset:35200
	ds_read_b128 v[94:97], v133 offset:43904
	ds_read_b128 v[106:109], v133 offset:52608
	ds_read_b128 v[110:113], v133 offset:61312
	s_waitcnt lgkmcnt(7)
	v_mfma_f32_16x16x32_bf16 v[42:45], v[74:77], v[98:101], v[42:45]
	s_waitcnt lgkmcnt(6)
	v_mfma_f32_16x16x32_bf16 v[46:49], v[78:81], v[98:101], v[46:49]
	s_waitcnt lgkmcnt(5)
	v_mfma_f32_16x16x32_bf16 v[50:53], v[82:85], v[98:101], v[50:53]
	s_waitcnt lgkmcnt(4)
	v_mfma_f32_16x16x32_bf16 v[54:57], v[86:89], v[98:101], v[54:57]
	s_waitcnt lgkmcnt(3)
	v_mfma_f32_16x16x32_bf16 v[58:61], v[90:93], v[98:101], v[58:61]
	s_waitcnt lgkmcnt(2)
	v_mfma_f32_16x16x32_bf16 v[62:65], v[94:97], v[98:101], v[62:65]
	s_waitcnt lgkmcnt(1)
	v_mfma_f32_16x16x32_bf16 v[66:69], v[106:109], v[98:101], v[66:69]
	s_waitcnt lgkmcnt(0)
	v_mfma_f32_16x16x32_bf16 v[70:73], v[110:113], v[98:101], v[70:73]
	ds_read_b128 v[74:77], v133 offset:448
	ds_read_b128 v[78:81], v133 offset:9152
	ds_read_b128 v[82:85], v133 offset:17856
	ds_read_b128 v[86:89], v133 offset:26560
	ds_read_b128 v[90:93], v133 offset:35264
	ds_read_b128 v[94:97], v133 offset:43968
	ds_read_b128 v[98:101], v133 offset:52672
	ds_read_b128 v[106:109], v133 offset:61376
	s_waitcnt lgkmcnt(7)
	v_mfma_f32_16x16x32_bf16 v[74:77], v[74:77], v[102:105], v[42:45]
	s_waitcnt lgkmcnt(6)
	v_mfma_f32_16x16x32_bf16 v[44:47], v[78:81], v[102:105], v[46:49]
	s_waitcnt lgkmcnt(5)
	v_mfma_f32_16x16x32_bf16 v[48:51], v[82:85], v[102:105], v[50:53]
	s_waitcnt lgkmcnt(4)
	v_mfma_f32_16x16x32_bf16 v[52:55], v[86:89], v[102:105], v[54:57]
	s_waitcnt lgkmcnt(3)
	v_mfma_f32_16x16x32_bf16 v[56:59], v[90:93], v[102:105], v[58:61]
	s_waitcnt lgkmcnt(2)
	v_mfma_f32_16x16x32_bf16 v[60:63], v[94:97], v[102:105], v[62:65]
	s_waitcnt lgkmcnt(1)
	v_mfma_f32_16x16x32_bf16 v[64:67], v[98:101], v[102:105], v[66:69]
	s_waitcnt lgkmcnt(0)
	v_mfma_f32_16x16x32_bf16 v[68:71], v[106:109], v[102:105], v[70:73]
	s_nop 2
	v_lshlrev_b64 v[72:73], 3, v[120:121]
	v_rcp_f32_e32 v32, v131
	v_or3_b32 v42, v129, s31, v72
	v_mov_b32_e32 v119, v33
	v_mad_u64_u32 v[42:43], s[2:3], v42, 3, v[118:119]
	v_mad_i32_i24 v43, v73, 3, v43
	v_lshlrev_b64 v[72:73], 7, v[42:43]
	v_lshl_add_u64 v[78:79], v[124:125], 0, v[72:73]
	v_pk_mul_f32 v[44:45], v[32:33], v[44:45] op_sel_hi:[0,1]
	v_mov_b32_e32 v73, v33
	v_cvt_pk_fp8_f32 v73, v44, v45
	v_pk_mul_f32 v[74:75], v[32:33], v[74:75] op_sel_hi:[0,1]
	v_mov_b32_e32 v72, v33
	v_pk_mul_f32 v[46:47], v[32:33], v[46:47] op_sel_hi:[0,1]
	v_cvt_pk_fp8_f32 v72, v74, v75
	v_cvt_pk_fp8_f32 v73, v46, v47 op_sel:[0,0,1]
	v_pk_mul_f32 v[46:47], v[32:33], v[48:49] op_sel_hi:[0,1]
	v_mov_b32_e32 v74, v33
	v_cvt_pk_fp8_f32 v74, v46, v47
	v_pk_mul_f32 v[46:47], v[32:33], v[52:53] op_sel_hi:[0,1]
	v_mov_b32_e32 v75, v33
	v_cvt_pk_fp8_f32 v75, v46, v47
	v_pk_mul_f32 v[44:45], v[32:33], v[50:51] op_sel_hi:[0,1]
	v_cvt_pk_fp8_f32 v74, v44, v45 op_sel:[0,0,1]
	v_pk_mul_f32 v[44:45], v[32:33], v[54:55] op_sel_hi:[0,1]
	v_cvt_pk_fp8_f32 v75, v44, v45 op_sel:[0,0,1]
	v_pk_mul_f32 v[48:49], v[32:33], v[56:57] op_sel_hi:[0,1]
	v_mov_b32_e32 v44, v33
	v_cvt_pk_fp8_f32 v44, v48, v49
	v_pk_mul_f32 v[48:49], v[32:33], v[60:61] op_sel_hi:[0,1]
	v_mov_b32_e32 v45, v33
	v_cvt_pk_fp8_f32 v45, v48, v49
	v_pk_mul_f32 v[46:47], v[32:33], v[58:59] op_sel_hi:[0,1]
	v_cvt_pk_fp8_f32 v44, v46, v47 op_sel:[0,0,1]
	v_pk_mul_f32 v[46:47], v[32:33], v[62:63] op_sel_hi:[0,1]
	v_cvt_pk_fp8_f32 v45, v46, v47 op_sel:[0,0,1]
	v_pk_mul_f32 v[50:51], v[32:33], v[64:65] op_sel_hi:[0,1]
	v_mov_b32_e32 v46, v33
	v_cvt_pk_fp8_f32 v46, v50, v51
	v_pk_mul_f32 v[50:51], v[32:33], v[68:69] op_sel_hi:[0,1]
	v_mov_b32_e32 v47, v33
	v_cvt_pk_fp8_f32 v47, v50, v51
	v_pk_mul_f32 v[76:77], v[32:33], v[76:77] op_sel_hi:[0,1]
	v_pk_mul_f32 v[48:49], v[32:33], v[66:67] op_sel_hi:[0,1]
	v_cvt_pk_fp8_f32 v72, v76, v77 op_sel:[0,0,1]
	v_cvt_pk_fp8_f32 v46, v48, v49 op_sel:[0,0,1]
	v_pk_mul_f32 v[48:49], v[32:33], v[70:71] op_sel_hi:[0,1]
	v_cvt_pk_fp8_f32 v47, v48, v49 op_sel:[0,0,1]
	v_cmp_gt_i32_e32 vcc, s28, v232
	s_nop 1
	v_cndmask_b32_e32 v49, v123, v79, vcc
	v_cndmask_b32_e32 v48, v122, v78, vcc
	global_store_dwordx4 v[48:49], v[72:75], off
	global_store_dwordx4 v[48:49], v[44:47], off offset:16
	s_and_saveexec_b64 s[2:3], s[38:39]
	s_cbranch_execz .LBB0_984
	v_lshl_add_u64 v[42:43], v[42:43], 3, s[6:7]
	v_cndmask_b32_e32 v43, v127, v43, vcc
	v_cndmask_b32_e32 v42, v126, v42, vcc
	global_store_dwordx2 v[42:43], v[130:131], off

.Latt2_wait_done:
	v_max3_f32 v42, v106, v110, v112
	s_waitcnt lgkmcnt(7)
	v_mfma_f32_16x16x32_bf16 v[44:47], v[44:47], v[38:41], 0
	v_cmp_gt_u32_e32 vcc, v138, v43
	s_waitcnt lgkmcnt(5)
	v_mfma_f32_16x16x32_bf16 v[44:47], v[52:55], v[34:37], v[44:47]
	v_mov_b32_e32 v52, s22
	s_waitcnt lgkmcnt(3)
	v_mfma_f32_16x16x32_bf16 v[44:47], v[56:59], v[28:31], v[44:47]
	v_mfma_f32_16x16x32_bf16 v[48:51], v[48:51], v[38:41], 0
	s_waitcnt lgkmcnt(1)
	v_mfma_f32_16x16x32_bf16 v[44:47], v[68:71], v[24:27], v[44:47]
	v_mfma_f32_16x16x32_bf16 v[48:51], v[60:63], v[34:37], v[48:51]
	v_mfma_f32_16x16x32_bf16 v[48:51], v[64:67], v[28:31], v[48:51]
	s_nop 5
	v_cndmask_b32_e32 v52, v44, v52, vcc
	v_cmp_lt_u32_e32 vcc, v138, v43
	s_nop 1
	v_cndmask_b32_e32 v58, v52, v44, vcc
	v_or_b32_e32 v44, 2, v138
	v_cndmask_b32_e32 v59, v217, v45, vcc
	v_cmp_le_u32_e32 vcc, v44, v43
	v_or_b32_e32 v44, 3, v138
	v_or_b32_e32 v45, 4, v138
	v_cndmask_b32_e32 v60, v217, v46, vcc
	v_cmp_le_u32_e32 vcc, v44, v43
	v_mov_b32_e32 v44, s22
	s_nop 0
	v_cndmask_b32_e32 v61, v217, v47, vcc
	s_waitcnt lgkmcnt(0)
	v_mfma_f32_16x16x32_bf16 v[46:49], v[72:75], v[24:27], v[48:51]
	v_cmp_gt_u32_e32 vcc, v45, v43
	s_nop 6
	v_cndmask_b32_e32 v62, v46, v44, vcc
	v_or_b32_e32 v44, 5, v138
	v_cmp_le_u32_e32 vcc, v44, v43
	v_or_b32_e32 v44, 6, v138
	s_nop 0
	v_cndmask_b32_e32 v63, v217, v47, vcc
	v_cmp_le_u32_e32 vcc, v44, v43
	v_or_b32_e32 v44, 7, v138
	s_nop 0
	v_cndmask_b32_e32 v64, v217, v48, vcc
	v_cmp_le_u32_e32 vcc, v44, v43
	s_nop 1
	v_cndmask_b32_e32 v65, v217, v49, vcc
	ds_read_b128 v[44:47], v248 offset:8192
	ds_read_b128 v[48:51], v248 offset:9216
	ds_read_b128 v[52:55], v249 offset:8192
	ds_read_b128 v[68:71], v249 offset:9216
	ds_read_b128 v[72:75], v250 offset:8192
	ds_read_b128 v[76:79], v250 offset:9216
	ds_read_b128 v[80:83], v220 offset:8192
	ds_read_b128 v[84:87], v220 offset:9216
	s_waitcnt lgkmcnt(7)
	v_mfma_f32_16x16x32_bf16 v[44:47], v[44:47], v[38:41], 0
	s_waitcnt lgkmcnt(5)
	v_mfma_f32_16x16x32_bf16 v[44:47], v[52:55], v[34:37], v[44:47]
	v_or_b32_e32 v53, 32, v138
	v_mov_b32_e32 v52, s22
	v_cmp_gt_u32_e32 vcc, v53, v43
	s_waitcnt lgkmcnt(3)
	v_mfma_f32_16x16x32_bf16 v[44:47], v[72:75], v[28:31], v[44:47]
	v_mfma_f32_16x16x32_bf16 v[48:51], v[48:51], v[38:41], 0
	s_waitcnt lgkmcnt(1)
	v_mfma_f32_16x16x32_bf16 v[44:47], v[80:83], v[24:27], v[44:47]
	v_mfma_f32_16x16x32_bf16 v[48:51], v[68:71], v[34:37], v[48:51]
	v_mfma_f32_16x16x32_bf16 v[48:51], v[76:79], v[28:31], v[48:51]
	s_nop 5
	v_cndmask_b32_e32 v66, v44, v52, vcc
	v_or_b32_e32 v44, 33, v138
	v_cmp_le_u32_e32 vcc, v44, v43
	v_or_b32_e32 v44, 34, v138
	s_nop 0
	v_cndmask_b32_e32 v67, v217, v45, vcc
	v_cmp_le_u32_e32 vcc, v44, v43
	v_or_b32_e32 v44, 35, v138
	v_or_b32_e32 v45, 36, v138
	v_cndmask_b32_e32 v68, v217, v46, vcc
	v_cmp_le_u32_e32 vcc, v44, v43
	v_mov_b32_e32 v44, s22
	s_nop 0
	v_cndmask_b32_e32 v69, v217, v47, vcc
	s_waitcnt lgkmcnt(0)
	v_mfma_f32_16x16x32_bf16 v[46:49], v[84:87], v[24:27], v[48:51]
	v_cmp_gt_u32_e32 vcc, v45, v43
	s_nop 6
	v_cndmask_b32_e32 v70, v46, v44, vcc
	v_or_b32_e32 v44, 37, v138
	v_cmp_le_u32_e32 vcc, v44, v43
	v_or_b32_e32 v44, 38, v138
	s_nop 0
	v_cndmask_b32_e32 v71, v217, v47, vcc
	v_cmp_le_u32_e32 vcc, v44, v43
	v_or_b32_e32 v44, 39, v138
	s_nop 0
	v_cndmask_b32_e32 v72, v217, v48, vcc
	v_cmp_le_u32_e32 vcc, v44, v43
	s_nop 1
	v_cndmask_b32_e32 v73, v217, v49, vcc
	ds_read_b128 v[44:47], v248 offset:16384
	ds_read_b128 v[48:51], v248 offset:17408
	ds_read_b128 v[52:55], v249 offset:16384
	ds_read_b128 v[76:79], v249 offset:17408
	ds_read_b128 v[80:83], v250 offset:16384
	ds_read_b128 v[84:87], v250 offset:17408
	ds_read_b128 v[88:91], v220 offset:16384
	ds_read_b128 v[92:95], v220 offset:17408
	s_waitcnt lgkmcnt(7)
	v_mfma_f32_16x16x32_bf16 v[44:47], v[44:47], v[38:41], 0
	s_waitcnt lgkmcnt(5)
	v_mfma_f32_16x16x32_bf16 v[44:47], v[52:55], v[34:37], v[44:47]
	v_or_b32_e32 v53, 64, v138
	v_mov_b32_e32 v52, s22
	v_cmp_gt_u32_e32 vcc, v53, v43
	s_waitcnt lgkmcnt(3)
	v_mfma_f32_16x16x32_bf16 v[44:47], v[80:83], v[28:31], v[44:47]
	v_mfma_f32_16x16x32_bf16 v[48:51], v[48:51], v[38:41], 0
	s_waitcnt lgkmcnt(1)
	v_mfma_f32_16x16x32_bf16 v[44:47], v[88:91], v[24:27], v[44:47]
	v_mfma_f32_16x16x32_bf16 v[48:51], v[76:79], v[34:37], v[48:51]
	v_mfma_f32_16x16x32_bf16 v[48:51], v[84:87], v[28:31], v[48:51]
	s_nop 5
	v_cndmask_b32_e32 v74, v44, v52, vcc
	v_or_b32_e32 v44, 0x41, v138
	v_cmp_le_u32_e32 vcc, v44, v43
	v_or_b32_e32 v44, 0x42, v138
	s_nop 0
	v_cndmask_b32_e32 v75, v217, v45, vcc
	v_cmp_le_u32_e32 vcc, v44, v43
	v_or_b32_e32 v44, 0x43, v138
	v_or_b32_e32 v45, 0x44, v138
	v_cndmask_b32_e32 v76, v217, v46, vcc
	v_cmp_le_u32_e32 vcc, v44, v43
	v_mov_b32_e32 v44, s22
	s_nop 0
	v_cndmask_b32_e32 v77, v217, v47, vcc
	s_waitcnt lgkmcnt(0)
	v_mfma_f32_16x16x32_bf16 v[46:49], v[92:95], v[24:27], v[48:51]
	v_cmp_gt_u32_e32 vcc, v45, v43
	s_nop 6
	v_cndmask_b32_e32 v78, v46, v44, vcc
	v_or_b32_e32 v44, 0x45, v138
	v_cmp_le_u32_e32 vcc, v44, v43
	v_or_b32_e32 v44, 0x46, v138
	s_nop 0
	v_cndmask_b32_e32 v79, v217, v47, vcc
	v_cmp_le_u32_e32 vcc, v44, v43
	v_or_b32_e32 v44, 0x47, v138
	s_nop 0
	v_cndmask_b32_e32 v80, v217, v48, vcc
	v_cmp_le_u32_e32 vcc, v44, v43
	s_nop 1
	v_cndmask_b32_e32 v81, v217, v49, vcc
	ds_read_b128 v[44:47], v248 offset:24576
	ds_read_b128 v[48:51], v248 offset:25600
	ds_read_b128 v[52:55], v249 offset:24576
	ds_read_b128 v[84:87], v249 offset:25600
	ds_read_b128 v[88:91], v250 offset:24576
	ds_read_b128 v[92:95], v250 offset:25600
	ds_read_b128 v[96:99], v220 offset:24576
	ds_read_b128 v[100:103], v220 offset:25600
	s_waitcnt lgkmcnt(7)
	v_mfma_f32_16x16x32_bf16 v[44:47], v[44:47], v[38:41], 0
	s_waitcnt lgkmcnt(5)
	v_mfma_f32_16x16x32_bf16 v[44:47], v[52:55], v[34:37], v[44:47]
	v_or_b32_e32 v53, 0x60, v138
	v_mov_b32_e32 v52, s22
	v_cmp_gt_u32_e32 vcc, v53, v43
	s_waitcnt lgkmcnt(3)
	v_mfma_f32_16x16x32_bf16 v[44:47], v[88:91], v[28:31], v[44:47]
	v_mfma_f32_16x16x32_bf16 v[48:51], v[48:51], v[38:41], 0
	s_waitcnt lgkmcnt(1)
	v_mfma_f32_16x16x32_bf16 v[44:47], v[96:99], v[24:27], v[44:47]
	v_mfma_f32_16x16x32_bf16 v[48:51], v[84:87], v[34:37], v[48:51]
	v_mfma_f32_16x16x32_bf16 v[48:51], v[92:95], v[28:31], v[48:51]
	s_nop 5
	v_cndmask_b32_e32 v82, v44, v52, vcc
	v_or_b32_e32 v44, 0x61, v138
	v_cmp_le_u32_e32 vcc, v44, v43
	v_or_b32_e32 v44, 0x62, v138
	s_nop 0
	v_cndmask_b32_e32 v83, v217, v45, vcc
	v_cmp_le_u32_e32 vcc, v44, v43
	v_or_b32_e32 v44, 0x63, v138
	v_or_b32_e32 v45, 0x64, v138
	v_cndmask_b32_e32 v84, v217, v46, vcc
	v_cmp_le_u32_e32 vcc, v44, v43
	v_mov_b32_e32 v44, s22
	s_nop 0
	v_cndmask_b32_e32 v85, v217, v47, vcc
	s_waitcnt lgkmcnt(0)
	v_mfma_f32_16x16x32_bf16 v[46:49], v[100:103], v[24:27], v[48:51]
	v_cmp_gt_u32_e32 vcc, v45, v43
	s_nop 6
	v_cndmask_b32_e32 v86, v46, v44, vcc
	v_or_b32_e32 v44, 0x65, v138
	v_cmp_le_u32_e32 vcc, v44, v43
	v_or_b32_e32 v44, 0x66, v138
	s_nop 0
	v_cndmask_b32_e32 v87, v217, v47, vcc
	v_cmp_le_u32_e32 vcc, v44, v43
	v_or_b32_e32 v44, 0x67, v138
	s_nop 0
	v_cndmask_b32_e32 v88, v217, v48, vcc
	v_cmp_le_u32_e32 vcc, v44, v43
	s_nop 1
	v_cndmask_b32_e32 v89, v217, v49, vcc
	ds_read_b128 v[44:47], v248 offset:32768
	ds_read_b128 v[48:51], v248 offset:33792
	ds_read_b128 v[52:55], v249 offset:32768
	ds_read_b128 v[92:95], v249 offset:33792
	ds_read_b128 v[96:99], v250 offset:32768
	ds_read_b128 v[100:103], v250 offset:33792
	ds_read_b128 v[114:117], v220 offset:32768
	ds_read_b128 v[118:121], v220 offset:33792
	s_waitcnt lgkmcnt(7)
	v_mfma_f32_16x16x32_bf16 v[44:47], v[44:47], v[38:41], 0
	s_waitcnt lgkmcnt(5)
	v_mfma_f32_16x16x32_bf16 v[44:47], v[52:55], v[34:37], v[44:47]
	v_or_b32_e32 v53, 0x80, v138
	v_mov_b32_e32 v52, s22
	v_cmp_gt_u32_e32 vcc, v53, v43
	s_waitcnt lgkmcnt(3)
	v_mfma_f32_16x16x32_bf16 v[44:47], v[96:99], v[28:31], v[44:47]
	v_mfma_f32_16x16x32_bf16 v[48:51], v[48:51], v[38:41], 0
	s_waitcnt lgkmcnt(1)
	v_mfma_f32_16x16x32_bf16 v[44:47], v[114:117], v[24:27], v[44:47]
	v_mfma_f32_16x16x32_bf16 v[48:51], v[92:95], v[34:37], v[48:51]
	v_mfma_f32_16x16x32_bf16 v[48:51], v[100:103], v[28:31], v[48:51]
	s_nop 5
	v_cndmask_b32_e32 v90, v44, v52, vcc
	v_or_b32_e32 v44, 0x81, v138
	v_cmp_le_u32_e32 vcc, v44, v43
	v_or_b32_e32 v44, 0x82, v138
	s_nop 0
	v_cndmask_b32_e32 v91, v217, v45, vcc
	v_cmp_le_u32_e32 vcc, v44, v43
	v_or_b32_e32 v44, 0x83, v138
	v_or_b32_e32 v45, 0x84, v138
	v_cndmask_b32_e32 v92, v217, v46, vcc
	v_cmp_le_u32_e32 vcc, v44, v43
	v_mov_b32_e32 v44, s22
	s_nop 0
	v_cndmask_b32_e32 v93, v217, v47, vcc
	s_waitcnt lgkmcnt(0)
	v_mfma_f32_16x16x32_bf16 v[46:49], v[118:121], v[24:27], v[48:51]
	v_cmp_gt_u32_e32 vcc, v45, v43
	s_nop 6
	v_cndmask_b32_e32 v94, v46, v44, vcc
	v_or_b32_e32 v44, 0x85, v138
	v_cmp_le_u32_e32 vcc, v44, v43
	v_or_b32_e32 v44, 0x86, v138
	s_nop 0
	v_cndmask_b32_e32 v95, v217, v47, vcc
	v_cmp_le_u32_e32 vcc, v44, v43
	v_or_b32_e32 v44, 0x87, v138
	s_nop 0
	v_cndmask_b32_e32 v96, v217, v48, vcc
	v_cmp_le_u32_e32 vcc, v44, v43
	s_nop 1
	v_cndmask_b32_e32 v97, v217, v49, vcc
	ds_read_b128 v[44:47], v248 offset:40960
	ds_read_b128 v[48:51], v248 offset:41984
	ds_read_b128 v[52:55], v249 offset:40960
	ds_read_b128 v[100:103], v249 offset:41984
	ds_read_b128 v[114:117], v250 offset:40960
	ds_read_b128 v[118:121], v250 offset:41984
	ds_read_b128 v[122:125], v220 offset:40960
	ds_read_b128 v[126:129], v220 offset:41984
	s_waitcnt lgkmcnt(7)
	v_mfma_f32_16x16x32_bf16 v[44:47], v[44:47], v[38:41], 0
	v_cmp_gt_u32_e32 vcc, v197, v43
	s_waitcnt lgkmcnt(5)
	v_mfma_f32_16x16x32_bf16 v[44:47], v[52:55], v[34:37], v[44:47]
	v_mov_b32_e32 v52, s22
	v_mfma_f32_16x16x32_bf16 v[48:51], v[48:51], v[38:41], 0
	s_waitcnt lgkmcnt(3)
	v_mfma_f32_16x16x32_bf16 v[44:47], v[114:117], v[28:31], v[44:47]
	v_mfma_f32_16x16x32_bf16 v[48:51], v[100:103], v[34:37], v[48:51]
	s_waitcnt lgkmcnt(1)
	v_mfma_f32_16x16x32_bf16 v[44:47], v[122:125], v[24:27], v[44:47]
	v_mfma_f32_16x16x32_bf16 v[48:51], v[118:121], v[28:31], v[48:51]
	s_nop 6
	v_cndmask_b32_e32 v98, v44, v52, vcc
	v_cmp_le_u32_e32 vcc, v199, v43
	v_mov_b32_e32 v44, s22
	s_nop 0
	v_cndmask_b32_e32 v99, v217, v45, vcc
	v_cmp_le_u32_e32 vcc, v201, v43
	s_nop 1
	v_cndmask_b32_e32 v102, v217, v46, vcc
	v_cmp_le_u32_e32 vcc, v202, v43
	s_nop 1
	v_cndmask_b32_e32 v103, v217, v47, vcc
	s_waitcnt lgkmcnt(0)
	v_mfma_f32_16x16x32_bf16 v[46:49], v[126:129], v[24:27], v[48:51]
	v_cmp_gt_u32_e32 vcc, v203, v43
	s_nop 6
	v_cndmask_b32_e32 v100, v46, v44, vcc
	v_cmp_le_u32_e32 vcc, v204, v43
	s_nop 1
	v_cndmask_b32_e32 v101, v217, v47, vcc
	v_cmp_le_u32_e32 vcc, v205, v43
	s_nop 1
	v_cndmask_b32_e32 v104, v217, v48, vcc
	v_cmp_le_u32_e32 vcc, v206, v43
	s_nop 1
	v_cndmask_b32_e32 v105, v217, v49, vcc
	ds_read_b128 v[44:47], v248 offset:49152
	ds_read_b128 v[48:51], v248 offset:50176
	ds_read_b128 v[52:55], v249 offset:49152
	ds_read_b128 v[114:117], v249 offset:50176
	ds_read_b128 v[118:121], v250 offset:49152
	ds_read_b128 v[122:125], v250 offset:50176
	ds_read_b128 v[126:129], v220 offset:49152
	ds_read_b128 v[130:133], v220 offset:50176
	s_waitcnt lgkmcnt(7)
	v_mfma_f32_16x16x32_bf16 v[44:47], v[44:47], v[38:41], 0
	v_cmp_gt_u32_e32 vcc, v207, v43
	s_waitcnt lgkmcnt(5)
	v_mfma_f32_16x16x32_bf16 v[44:47], v[52:55], v[34:37], v[44:47]
	v_mov_b32_e32 v52, s22
	v_mfma_f32_16x16x32_bf16 v[48:51], v[48:51], v[38:41], 0
	s_waitcnt lgkmcnt(3)
	v_mfma_f32_16x16x32_bf16 v[44:47], v[118:121], v[28:31], v[44:47]
	v_mfma_f32_16x16x32_bf16 v[48:51], v[114:117], v[34:37], v[48:51]
	s_waitcnt lgkmcnt(1)
	v_mfma_f32_16x16x32_bf16 v[44:47], v[126:129], v[24:27], v[44:47]
	v_mfma_f32_16x16x32_bf16 v[48:51], v[122:125], v[28:31], v[48:51]
	s_nop 6
	v_cndmask_b32_e32 v108, v44, v52, vcc
	v_cmp_le_u32_e32 vcc, v208, v43
	v_mov_b32_e32 v44, s22
	s_nop 0
	v_cndmask_b32_e32 v109, v217, v45, vcc
	v_cmp_le_u32_e32 vcc, v209, v43
	s_nop 1
	v_cndmask_b32_e32 v118, v217, v46, vcc
	v_cmp_le_u32_e32 vcc, v210, v43
	s_nop 1
	v_cndmask_b32_e32 v119, v217, v47, vcc
	s_waitcnt lgkmcnt(0)
	v_mfma_f32_16x16x32_bf16 v[46:49], v[130:133], v[24:27], v[48:51]
	v_cmp_gt_u32_e32 vcc, v211, v43
	s_nop 6
	v_cndmask_b32_e32 v116, v46, v44, vcc
	v_cmp_le_u32_e32 vcc, v212, v43
	s_nop 1
	v_cndmask_b32_e32 v117, v217, v47, vcc
	v_cmp_le_u32_e32 vcc, v213, v43
	s_nop 1
	v_cndmask_b32_e32 v120, v217, v48, vcc
	v_cmp_le_u32_e32 vcc, v221, v43
	s_nop 1
	v_cndmask_b32_e32 v121, v217, v49, vcc
	ds_read_b128 v[44:47], v248 offset:57344
	ds_read_b128 v[48:51], v248 offset:58368
	ds_read_b128 v[52:55], v249 offset:57344
	ds_read_b128 v[122:125], v249 offset:58368
	ds_read_b128 v[126:129], v250 offset:57344
	ds_read_b128 v[130:133], v250 offset:58368
	ds_read_b128 v[134:137], v220 offset:57344
	ds_read_b128 v[190:193], v220 offset:58368
	s_waitcnt lgkmcnt(7)
	v_mfma_f32_16x16x32_bf16 v[44:47], v[44:47], v[38:41], 0
	v_cmp_gt_u32_e32 vcc, v222, v43
	s_waitcnt lgkmcnt(5)
	v_mfma_f32_16x16x32_bf16 v[44:47], v[52:55], v[34:37], v[44:47]
	v_mfma_f32_16x16x32_bf16 v[48:51], v[48:51], v[38:41], 0
	v_mov_b32_e32 v38, s22
	s_waitcnt lgkmcnt(3)
	v_mfma_f32_16x16x32_bf16 v[44:47], v[126:129], v[28:31], v[44:47]
	v_mfma_f32_16x16x32_bf16 v[48:51], v[122:125], v[34:37], v[48:51]
	v_mov_b32_e32 v36, s22
	s_waitcnt lgkmcnt(1)
	v_mfma_f32_16x16x32_bf16 v[44:47], v[134:137], v[24:27], v[44:47]
	v_mfma_f32_16x16x32_bf16 v[28:31], v[130:133], v[28:31], v[48:51]
	s_waitcnt lgkmcnt(0)
	v_mfma_f32_16x16x32_bf16 v[24:27], v[190:193], v[24:27], v[28:31]
	s_nop 4
	v_cndmask_b32_e32 v38, v44, v38, vcc
	v_cmp_le_u32_e32 vcc, v223, v43
	s_nop 1
	v_cndmask_b32_e32 v39, v217, v45, vcc
	v_cmp_le_u32_e32 vcc, v224, v43
	s_nop 1
	v_cndmask_b32_e32 v34, v217, v46, vcc
	v_cmp_le_u32_e32 vcc, v225, v43
	s_nop 1
	v_cndmask_b32_e32 v35, v217, v47, vcc
	v_cmp_gt_u32_e32 vcc, v226, v43
	s_nop 1
	v_cndmask_b32_e32 v24, v24, v36, vcc
	v_cmp_le_u32_e32 vcc, v227, v43
	s_nop 1
	v_cndmask_b32_e32 v25, v217, v25, vcc
	v_cmp_le_u32_e32 vcc, v228, v43
	s_nop 1
	v_cndmask_b32_e32 v26, v217, v26, vcc
	v_cmp_le_u32_e32 vcc, v229, v43
	s_nop 1
	v_cndmask_b32_e32 v27, v217, v27, vcc
	v_max3_f32 v28, v42, v58, v59
	v_max3_f32 v29, v218, v60, v61
	v_and_b32_e32 v30, 64, v216
	v_max3_f32 v28, v28, v62, v63
	v_max3_f32 v29, v29, v64, v65
	v_add_u32_e32 v30, 64, v30
	v_max3_f32 v28, v28, v66, v67
	v_max3_f32 v29, v29, v68, v69
	ds_read_b128 v[42:45], v230
	ds_read_b128 v[46:49], v230 offset:8704
	ds_read_b128 v[50:53], v230 offset:17408
	ds_read_b128 v[54:57], v230 offset:26112
	v_max3_f32 v28, v28, v70, v71
	v_max3_f32 v29, v29, v72, v73
	v_max3_f32 v28, v28, v74, v75
	v_max3_f32 v29, v29, v76, v77
	v_max3_f32 v28, v28, v78, v79
	v_max3_f32 v29, v29, v80, v81
	v_max3_f32 v28, v28, v82, v83
	v_max3_f32 v29, v29, v84, v85
	v_max3_f32 v28, v28, v86, v87
	v_max3_f32 v29, v29, v88, v89
	v_max3_f32 v28, v28, v90, v91
	v_max3_f32 v29, v29, v92, v93
	v_max3_f32 v28, v28, v94, v95
	v_max3_f32 v29, v29, v96, v97
	v_max3_f32 v28, v28, v98, v99
	v_max3_f32 v29, v29, v102, v103
	v_max3_f32 v28, v28, v100, v101
	v_max3_f32 v29, v29, v104, v105
	v_max3_f32 v28, v28, v108, v109
	v_max3_f32 v29, v29, v118, v119
	v_max3_f32 v28, v28, v116, v117
	v_max3_f32 v29, v29, v120, v121
	v_max3_f32 v28, v28, v38, v39
	v_max3_f32 v29, v29, v34, v35
	v_max3_f32 v28, v28, v24, v25
	v_max3_f32 v29, v29, v26, v27
	v_max_f32 v28, v28, v29
	v_xor_b32_e32 v29, 16, v216
	v_cmp_lt_i32_e32 vcc, v29, v30
	s_nop 1
	v_cndmask_b32_e32 v29, v216, v29, vcc
	v_lshlrev_b32_e32 v160, 2, v29
	v_mov_b32_e32 v29, v28
	s_nop 1
	v_permlane16_swap_b32_e32 v29, v28
	s_waitcnt lgkmcnt(0)
	v_max_f32 v28, v28, v29
	v_xor_b32_e32 v29, 32, v216
	v_cmp_lt_i32_e32 vcc, v29, v30
	s_nop 1
	v_cndmask_b32_e32 v29, v216, v29, vcc
	v_lshlrev_b32_e32 v161, 2, v29
	v_mov_b32_e32 v29, v28
	s_nop 1
	v_permlane32_swap_b32_e32 v29, v28
	s_waitcnt lgkmcnt(0)
	v_max_f32 v114, v28, v29
	s_nop 0
	v_mov_b32_e32 v115, v114
	v_pk_add_f32 v[28:29], v[58:59], v[114:115] neg_lo:[0,1] neg_hi:[0,1]
	v_pk_add_f32 v[30:31], v[60:61], v[114:115] neg_lo:[0,1] neg_hi:[0,1]
	v_pk_add_f32 v[36:37], v[62:63], v[114:115] neg_lo:[0,1] neg_hi:[0,1]
	v_pk_add_f32 v[40:41], v[64:65], v[114:115] neg_lo:[0,1] neg_hi:[0,1]
	v_pk_add_f32 v[38:39], v[38:39], v[114:115] neg_lo:[0,1] neg_hi:[0,1]
	v_pk_add_f32 v[34:35], v[34:35], v[114:115] neg_lo:[0,1] neg_hi:[0,1]
	s_nop 0
	v_exp_f32_e32 v28, v28
	v_exp_f32_e32 v29, v29
	v_exp_f32_e32 v30, v30
	v_exp_f32_e32 v31, v31
	v_exp_f32_e32 v36, v36
	v_exp_f32_e32 v40, v40
	v_exp_f32_e32 v41, v41
	v_exp_f32_e32 v37, v37
	v_pk_add_f32 v[58:59], v[28:29], 0 op_sel_hi:[1,0]
	v_pk_add_f32 v[60:61], v[30:31], 0 op_sel_hi:[1,0]
	v_exp_f32_e32 v38, v38
	v_pk_add_f32 v[62:63], v[60:61], v[40:41]
	v_pk_add_f32 v[64:65], v[58:59], v[36:37]
	v_pk_add_f32 v[58:59], v[66:67], v[114:115] neg_lo:[0,1] neg_hi:[0,1]
	v_pk_add_f32 v[60:61], v[68:69], v[114:115] neg_lo:[0,1] neg_hi:[0,1]
	v_pk_add_f32 v[66:67], v[70:71], v[114:115] neg_lo:[0,1] neg_hi:[0,1]
	v_pk_add_f32 v[68:69], v[72:73], v[114:115] neg_lo:[0,1] neg_hi:[0,1]
	v_pk_add_f32 v[70:71], v[74:75], v[114:115] neg_lo:[0,1] neg_hi:[0,1]
	v_pk_add_f32 v[72:73], v[76:77], v[114:115] neg_lo:[0,1] neg_hi:[0,1]
	s_nop 0
	v_exp_f32_e32 v58, v58
	v_exp_f32_e32 v59, v59
	v_exp_f32_e32 v60, v60
	v_exp_f32_e32 v61, v61
	v_exp_f32_e32 v66, v66
	v_exp_f32_e32 v68, v68
	v_exp_f32_e32 v69, v69
	v_exp_f32_e32 v67, v67
	v_exp_f32_e32 v70, v70
	v_exp_f32_e32 v71, v71
	v_exp_f32_e32 v72, v72
	v_exp_f32_e32 v73, v73
	v_pk_add_f32 v[74:75], v[78:79], v[114:115] neg_lo:[0,1] neg_hi:[0,1]
	v_pk_add_f32 v[76:77], v[80:81], v[114:115] neg_lo:[0,1] neg_hi:[0,1]
	v_pk_add_f32 v[64:65], v[64:65], v[58:59]
	v_exp_f32_e32 v74, v74
	v_exp_f32_e32 v76, v76
	v_exp_f32_e32 v77, v77
	v_exp_f32_e32 v75, v75
	v_pk_add_f32 v[62:63], v[62:63], v[60:61]
	v_pk_add_f32 v[78:79], v[82:83], v[114:115] neg_lo:[0,1] neg_hi:[0,1]
	v_pk_add_f32 v[80:81], v[84:85], v[114:115] neg_lo:[0,1] neg_hi:[0,1]
	v_pk_add_f32 v[64:65], v[64:65], v[66:67]
	v_exp_f32_e32 v122, v78
	v_exp_f32_e32 v123, v79
	v_exp_f32_e32 v124, v80
	v_exp_f32_e32 v125, v81
	v_pk_add_f32 v[62:63], v[62:63], v[68:69]
	v_pk_add_f32 v[78:79], v[86:87], v[114:115] neg_lo:[0,1] neg_hi:[0,1]
	v_pk_add_f32 v[80:81], v[88:89], v[114:115] neg_lo:[0,1] neg_hi:[0,1]
	v_pk_add_f32 v[64:65], v[64:65], v[70:71]
	v_exp_f32_e32 v126, v78
	v_exp_f32_e32 v128, v80
	v_exp_f32_e32 v129, v81
	v_exp_f32_e32 v127, v79
	v_pk_add_f32 v[62:63], v[62:63], v[72:73]
	v_pk_add_f32 v[78:79], v[90:91], v[114:115] neg_lo:[0,1] neg_hi:[0,1]
	v_pk_add_f32 v[80:81], v[92:93], v[114:115] neg_lo:[0,1] neg_hi:[0,1]
	v_pk_add_f32 v[64:65], v[64:65], v[74:75]
	v_exp_f32_e32 v130, v78
	v_exp_f32_e32 v131, v79
	v_exp_f32_e32 v132, v80
	v_exp_f32_e32 v133, v81
	v_pk_add_f32 v[62:63], v[62:63], v[76:77]
	v_pk_add_f32 v[78:79], v[94:95], v[114:115] neg_lo:[0,1] neg_hi:[0,1]
	v_pk_add_f32 v[80:81], v[96:97], v[114:115] neg_lo:[0,1] neg_hi:[0,1]
	v_pk_add_f32 v[64:65], v[64:65], v[122:123]
	v_exp_f32_e32 v134, v78
	v_exp_f32_e32 v136, v80
	v_exp_f32_e32 v137, v81
	v_exp_f32_e32 v135, v79
	v_pk_add_f32 v[62:63], v[62:63], v[124:125]
	v_pk_add_f32 v[78:79], v[98:99], v[114:115] neg_lo:[0,1] neg_hi:[0,1]
	v_pk_add_f32 v[80:81], v[102:103], v[114:115] neg_lo:[0,1] neg_hi:[0,1]
	v_pk_add_f32 v[64:65], v[64:65], v[126:127]
	v_exp_f32_e32 v158, v78
	v_exp_f32_e32 v159, v79
	v_exp_f32_e32 v190, v80
	v_exp_f32_e32 v191, v81
	v_pk_add_f32 v[62:63], v[62:63], v[128:129]
	v_pk_add_f32 v[78:79], v[100:101], v[114:115] neg_lo:[0,1] neg_hi:[0,1]
	v_pk_add_f32 v[80:81], v[104:105], v[114:115] neg_lo:[0,1] neg_hi:[0,1]
	v_pk_add_f32 v[64:65], v[64:65], v[130:131]
	v_exp_f32_e32 v192, v78
	v_exp_f32_e32 v194, v80
	v_exp_f32_e32 v195, v81
	v_exp_f32_e32 v193, v79
	v_pk_add_f32 v[62:63], v[62:63], v[132:133]
	v_pk_add_f32 v[78:79], v[108:109], v[114:115] neg_lo:[0,1] neg_hi:[0,1]
	v_pk_add_f32 v[80:81], v[118:119], v[114:115] neg_lo:[0,1] neg_hi:[0,1]
	v_pk_add_f32 v[64:65], v[64:65], v[134:135]
	v_exp_f32_e32 v108, v78
	v_exp_f32_e32 v109, v79
	v_exp_f32_e32 v118, v80
	v_exp_f32_e32 v119, v81
	v_pk_add_f32 v[62:63], v[62:63], v[136:137]
	v_pk_add_f32 v[78:79], v[116:117], v[114:115] neg_lo:[0,1] neg_hi:[0,1]
	v_pk_add_f32 v[80:81], v[120:121], v[114:115] neg_lo:[0,1] neg_hi:[0,1]
	v_pk_add_f32 v[64:65], v[64:65], v[158:159]
	v_exp_f32_e32 v116, v78
	v_exp_f32_e32 v120, v80
	v_exp_f32_e32 v121, v81
	v_exp_f32_e32 v117, v79
	v_pk_add_f32 v[62:63], v[62:63], v[190:191]
	v_exp_f32_e32 v39, v39
	v_exp_f32_e32 v34, v34
	v_exp_f32_e32 v35, v35
	v_pk_add_f32 v[24:25], v[24:25], v[114:115] neg_lo:[0,1] neg_hi:[0,1]
	v_pk_add_f32 v[26:27], v[26:27], v[114:115] neg_lo:[0,1] neg_hi:[0,1]
	v_pk_add_f32 v[62:63], v[62:63], v[194:195]
	v_pk_add_f32 v[64:65], v[64:65], v[192:193]
	v_exp_f32_e32 v24, v24
	v_exp_f32_e32 v26, v26
	v_exp_f32_e32 v27, v27
	v_exp_f32_e32 v25, v25
	v_pk_add_f32 v[64:65], v[64:65], v[108:109]
	v_pk_add_f32 v[62:63], v[62:63], v[118:119]
	v_pk_add_f32 v[64:65], v[64:65], v[116:117]
	v_pk_add_f32 v[62:63], v[62:63], v[120:121]
	v_pk_add_f32 v[64:65], v[64:65], v[38:39]
	v_pk_add_f32 v[62:63], v[62:63], v[34:35]
	v_pk_add_f32 v[64:65], v[64:65], v[24:25]
	v_pk_add_f32 v[62:63], v[62:63], v[26:27]
	v_add_f32_e32 v64, v64, v65
	v_add_f32_e32 v62, v62, v63
	v_add_f32_e32 v62, v64, v62
	v_mov_b32_e32 v63, v62
	s_nop 1
	v_permlane16_swap_b32_e32 v63, v62
	ds_read_b128 v[90:93], v230 offset:34816
	ds_read_b128 v[94:97], v230 offset:43520
	ds_read_b128 v[98:101], v230 offset:52224
	ds_read_b128 v[86:89], v230 offset:60928
	v_cvt_pk_bf16_f32 v102, v28, v29
	v_cvt_pk_bf16_f32 v103, v30, v31
	v_cvt_pk_bf16_f32 v104, v36, v37
	s_waitcnt lgkmcnt(4)
	v_add_f32_e32 v185, v62, v63
	ds_bpermute_b32 v187, v161, v185
	v_cvt_pk_bf16_f32 v105, v40, v41
	v_cvt_pk_bf16_f32 v82, v58, v59
	v_cvt_pk_bf16_f32 v83, v60, v61
	v_cvt_pk_bf16_f32 v84, v66, v67
	v_cvt_pk_bf16_f32 v85, v68, v69
	v_cvt_pk_bf16_f32 v78, v70, v71
	v_cvt_pk_bf16_f32 v79, v72, v73
	v_cvt_pk_bf16_f32 v80, v74, v75
	v_cvt_pk_bf16_f32 v81, v76, v77
	v_cvt_pk_bf16_f32 v74, v122, v123
	v_cvt_pk_bf16_f32 v75, v124, v125
	v_cvt_pk_bf16_f32 v76, v126, v127
	v_cvt_pk_bf16_f32 v77, v128, v129
	v_cvt_pk_bf16_f32 v70, v130, v131
	v_cvt_pk_bf16_f32 v71, v132, v133
	v_cvt_pk_bf16_f32 v72, v134, v135
	v_cvt_pk_bf16_f32 v73, v136, v137
	v_cvt_pk_bf16_f32 v66, v158, v159
	v_cvt_pk_bf16_f32 v67, v190, v191
	v_cvt_pk_bf16_f32 v68, v192, v193
	v_cvt_pk_bf16_f32 v69, v194, v195
	v_cvt_pk_bf16_f32 v62, v108, v109
	v_cvt_pk_bf16_f32 v63, v118, v119
	v_cvt_pk_bf16_f32 v64, v116, v117
	v_cvt_pk_bf16_f32 v65, v120, v121
	v_cvt_pk_bf16_f32 v58, v38, v39
	v_cvt_pk_bf16_f32 v59, v34, v35
	v_cvt_pk_bf16_f32 v60, v24, v25
	v_cvt_pk_bf16_f32 v61, v26, v27
	s_add_i32 s28, s23, 8
	s_cmp_lg_u32 s23, 24
	s_cselect_b32 s23, s28, 24
	s_add_i32 s23, s23, s11
	s_lshl_b32 s29, s23, 4
	s_and_b32 s29, s29, 0xf0
	v_or_b32_e32 v108, s29, v183
	s_ashr_i32 s23, s23, 4
	v_ashrrev_i32_e32 v109, 31, v108
	s_add_i32 s23, s23, s19
	v_lshlrev_b64 v[24:25], 11, v[108:109]
	s_lshl_b32 s30, s23, 7
	v_lshl_add_u64 v[24:25], s[0:1], 0, v[24:25]
	s_ashr_i32 s31, s30, 31
	v_lshl_add_u64 v[24:25], s[30:31], 1, v[24:25]
	v_lshl_add_u64 v[24:25], v[24:25], 0, v[32:33]
	global_load_dwordx4 v[38:41], v[24:25], off
	global_load_dwordx4 v[34:37], v[24:25], off offset:64
	global_load_dwordx4 v[28:31], v[24:25], off offset:128
	s_nop 0
	global_load_dwordx4 v[24:27], v[24:25], off offset:192
	s_ashr_i32 s29, s23, 31
	v_mov_b32_e32 v116, s23
	v_mov_b32_e32 v117, s29
	s_and_b64 vcc, exec, s[38:39]
	v_lshl_add_u64 v[108:109], v[108:109], 3, v[116:117]
	s_cbranch_vccnz .LBB0_1128
	v_mad_u64_u32 v[116:117], s[30:31], v108, 24, s[4:5]
	v_mad_i32_i24 v117, v109, 24, v117
	global_load_dwordx2 v[190:191], v[116:117], off
	s_branch .LBB0_1129

.LBB0_1424:
	s_add_u32 s2, s50, 0xfffc0080
	s_addc_u32 s3, s51, -1
	s_add_i32 s55, 0, 0x10000
	s_cmp_eq_u32 s54, 12
	s_cselect_b32 s3, s21, s3
	s_cselect_b32 s2, s23, s2
	s_cselect_b32 s53, s28, s45
	s_cselect_b32 s52, s29, s43
	s_add_i32 s58, 0, 0x14000
	v_add_u32_e32 v142, s55, v191
	v_add_u32_e32 v158, s58, v191
	ds_read_b128 v[114:117], v142
	ds_read_b128 v[122:125], v142 offset:1024
	ds_read_b128 v[130:133], v142 offset:2048
	ds_read_b128 v[142:145], v142 offset:3072
	ds_read_b128 v[146:149], v158
	ds_read_b128 v[150:153], v158 offset:1024
	ds_read_b128 v[172:175], v158 offset:2048
	ds_read_b128 v[176:179], v158 offset:3072
	v_lshl_add_u64 v[158:159], s[50:51], 0, v[32:33]
	s_add_i32 m0, s63, 0xc000
	ds_read_b128 v[180:183], v193
	ds_read_b128 v[184:187], v193 offset:1024
	ds_read_b128 v[194:197], v193 offset:2048
	ds_read_b128 v[198:201], v193 offset:3072
	ds_read_b128 v[202:205], v193 offset:4096
	ds_read_b128 v[206:209], v193 offset:5120
	ds_read_b128 v[210:213], v193 offset:6144
	ds_read_b128 v[220:223], v193 offset:7168
	global_load_lds_dwordx4 v[158:159], off
	v_lshl_add_u64 v[158:159], s[50:51], 0, v[170:171]
	s_add_i32 m0, s63, 0xe000
	s_nop 0
	global_load_lds_dwordx4 v[158:159], off
	s_waitcnt vmcnt(8)
	s_waitcnt lgkmcnt(0)
	s_barrier
	s_setprio 1
	v_mfma_f32_16x16x32_bf16 v[138:141], v[114:117], v[180:183], v[138:141]
	v_mfma_f32_16x16x32_bf16 v[134:137], v[130:133], v[180:183], v[134:137]
	v_mfma_f32_16x16x32_bf16 v[110:113], v[114:117], v[194:197], v[110:113]
	v_mfma_f32_16x16x32_bf16 v[106:109], v[130:133], v[194:197], v[106:109]
	v_mfma_f32_16x16x32_bf16 v[94:97], v[114:117], v[202:205], v[94:97]
	v_mfma_f32_16x16x32_bf16 v[90:93], v[130:133], v[202:205], v[90:93]
	v_mfma_f32_16x16x32_bf16 v[78:81], v[114:117], v[210:213], v[78:81]
	v_mfma_f32_16x16x32_bf16 v[74:77], v[130:133], v[210:213], v[74:77]
	v_mfma_f32_16x16x32_bf16 v[138:141], v[122:125], v[184:187], v[138:141]
	v_mfma_f32_16x16x32_bf16 v[134:137], v[142:145], v[184:187], v[134:137]
	v_mfma_f32_16x16x32_bf16 v[110:113], v[122:125], v[198:201], v[110:113]
	v_mfma_f32_16x16x32_bf16 v[106:109], v[142:145], v[198:201], v[106:109]
	v_mfma_f32_16x16x32_bf16 v[94:97], v[122:125], v[206:209], v[94:97]
	v_mfma_f32_16x16x32_bf16 v[90:93], v[142:145], v[206:209], v[90:93]
	v_mfma_f32_16x16x32_bf16 v[78:81], v[122:125], v[220:223], v[78:81]
	v_mfma_f32_16x16x32_bf16 v[74:77], v[142:145], v[220:223], v[74:77]
	v_mfma_f32_16x16x32_bf16 v[126:129], v[146:149], v[180:183], v[126:129]
	v_mfma_f32_16x16x32_bf16 v[118:121], v[172:175], v[180:183], v[118:121]
	v_mfma_f32_16x16x32_bf16 v[102:105], v[146:149], v[194:197], v[102:105]
	v_mfma_f32_16x16x32_bf16 v[98:101], v[172:175], v[194:197], v[98:101]
	v_mfma_f32_16x16x32_bf16 v[86:89], v[146:149], v[202:205], v[86:89]
	v_mfma_f32_16x16x32_bf16 v[82:85], v[172:175], v[202:205], v[82:85]
	v_mfma_f32_16x16x32_bf16 v[70:73], v[146:149], v[210:213], v[70:73]
	v_mfma_f32_16x16x32_bf16 v[66:69], v[172:175], v[210:213], v[66:69]
	v_mfma_f32_16x16x32_bf16 v[126:129], v[150:153], v[184:187], v[126:129]
	v_mfma_f32_16x16x32_bf16 v[118:121], v[176:179], v[184:187], v[118:121]
	v_mfma_f32_16x16x32_bf16 v[102:105], v[150:153], v[198:201], v[102:105]
	v_mfma_f32_16x16x32_bf16 v[98:101], v[176:179], v[198:201], v[98:101]
	v_mfma_f32_16x16x32_bf16 v[86:89], v[150:153], v[206:209], v[86:89]
	v_mfma_f32_16x16x32_bf16 v[82:85], v[176:179], v[206:209], v[82:85]
	v_mfma_f32_16x16x32_bf16 v[70:73], v[150:153], v[220:223], v[70:73]
	v_mfma_f32_16x16x32_bf16 v[66:69], v[176:179], v[220:223], v[66:69]
	s_setprio 0
	s_barrier
	s_add_i32 s55, s55, s62
	v_lshl_add_u64 v[158:159], s[52:53], 0, v[166:167]
	s_mov_b32 m0, s55
	ds_read_b128 v[180:183], v193 offset:16384
	ds_read_b128 v[184:187], v193 offset:17408
	ds_read_b128 v[194:197], v193 offset:18432
	ds_read_b128 v[198:201], v193 offset:19456
	ds_read_b128 v[202:205], v193 offset:20480
	ds_read_b128 v[206:209], v193 offset:21504
	ds_read_b128 v[210:213], v193 offset:22528
	ds_read_b128 v[220:223], v193 offset:23552
	global_load_lds_dwordx4 v[158:159], off
	s_add_i32 m0, s55, 0x2000
	s_add_u32 s56, s52, 0x40000
	v_lshl_add_u64 v[160:161], s[52:53], 0, v[162:163]
	s_addc_u32 s57, s53, 0
	s_add_i32 s55, s58, s62
	global_load_lds_dwordx4 v[160:161], off
	v_lshl_add_u64 v[188:189], s[56:57], 0, v[166:167]
	s_mov_b32 m0, s55
	v_lshl_add_u64 v[224:225], s[2:3], 0, v[164:165]
	global_load_lds_dwordx4 v[188:189], off
	v_lshl_add_u64 v[188:189], s[56:57], 0, v[162:163]
	s_add_i32 m0, s55, 0x2000
	s_nop 0
	global_load_lds_dwordx4 v[188:189], off
	v_lshl_add_u64 v[188:189], s[2:3], 0, v[168:169]
	s_mov_b32 m0, s63
	s_nop 0
	global_load_lds_dwordx4 v[188:189], off
	s_mov_b32 m0, s64
	s_nop 0
	global_load_lds_dwordx4 v[224:225], off
	s_waitcnt vmcnt(8)
	s_waitcnt lgkmcnt(0)
	s_barrier
	s_setprio 1
	v_mfma_f32_16x16x32_bf16 v[62:65], v[114:117], v[180:183], v[62:65]
	v_mfma_f32_16x16x32_bf16 v[58:61], v[130:133], v[180:183], v[58:61]
	v_mfma_f32_16x16x32_bf16 v[46:49], v[114:117], v[194:197], v[46:49]
	v_mfma_f32_16x16x32_bf16 v[42:45], v[130:133], v[194:197], v[42:45]
	v_mfma_f32_16x16x32_bf16 v[28:31], v[114:117], v[202:205], v[28:31]
	v_mfma_f32_16x16x32_bf16 v[24:27], v[130:133], v[202:205], v[24:27]
	v_mfma_f32_16x16x32_bf16 v[12:15], v[114:117], v[210:213], v[12:15]
	v_mfma_f32_16x16x32_bf16 v[8:11], v[130:133], v[210:213], v[8:11]
	v_mfma_f32_16x16x32_bf16 v[62:65], v[122:125], v[184:187], v[62:65]
	v_mfma_f32_16x16x32_bf16 v[58:61], v[142:145], v[184:187], v[58:61]
	v_mfma_f32_16x16x32_bf16 v[46:49], v[122:125], v[198:201], v[46:49]
	v_mfma_f32_16x16x32_bf16 v[42:45], v[142:145], v[198:201], v[42:45]
	v_mfma_f32_16x16x32_bf16 v[28:31], v[122:125], v[206:209], v[28:31]
	v_mfma_f32_16x16x32_bf16 v[24:27], v[142:145], v[206:209], v[24:27]
	v_mfma_f32_16x16x32_bf16 v[12:15], v[122:125], v[220:223], v[12:15]
	v_mfma_f32_16x16x32_bf16 v[8:11], v[142:145], v[220:223], v[8:11]
	v_mfma_f32_16x16x32_bf16 v[54:57], v[146:149], v[180:183], v[54:57]
	v_mfma_f32_16x16x32_bf16 v[50:53], v[172:175], v[180:183], v[50:53]
	v_mfma_f32_16x16x32_bf16 v[38:41], v[146:149], v[194:197], v[38:41]
	v_mfma_f32_16x16x32_bf16 v[34:37], v[172:175], v[194:197], v[34:37]
	v_mfma_f32_16x16x32_bf16 v[20:23], v[146:149], v[202:205], v[20:23]
	v_mfma_f32_16x16x32_bf16 v[16:19], v[172:175], v[202:205], v[16:19]
	v_mfma_f32_16x16x32_bf16 v[4:7], v[146:149], v[210:213], v[4:7]
	v_mfma_f32_16x16x32_bf16 v[0:3], v[172:175], v[210:213], v[0:3]
	v_mfma_f32_16x16x32_bf16 v[54:57], v[150:153], v[184:187], v[54:57]
	v_mfma_f32_16x16x32_bf16 v[50:53], v[176:179], v[184:187], v[50:53]
	v_mfma_f32_16x16x32_bf16 v[38:41], v[150:153], v[198:201], v[38:41]
	v_mfma_f32_16x16x32_bf16 v[34:37], v[176:179], v[198:201], v[34:37]
	v_mfma_f32_16x16x32_bf16 v[20:23], v[150:153], v[206:209], v[20:23]
	v_mfma_f32_16x16x32_bf16 v[16:19], v[176:179], v[206:209], v[16:19]
	v_mfma_f32_16x16x32_bf16 v[4:7], v[150:153], v[220:223], v[4:7]
	v_mfma_f32_16x16x32_bf16 v[0:3], v[176:179], v[220:223], v[0:3]
	s_setprio 0
	s_barrier
	s_add_i32 s55, 0, 0x18000
	s_add_i32 s56, 0, 0x1c000
	v_add_u32_e32 v142, s55, v191
	v_add_u32_e32 v176, s56, v191
	ds_read_b128 v[114:117], v142
	ds_read_b128 v[122:125], v142 offset:1024
	ds_read_b128 v[130:133], v142 offset:2048
	ds_read_b128 v[142:145], v142 offset:3072
	ds_read_b128 v[146:149], v176
	ds_read_b128 v[150:153], v176 offset:1024
	ds_read_b128 v[172:175], v176 offset:2048
	ds_read_b128 v[176:179], v176 offset:3072
	s_add_u32 s2, s2, 0x40000
	s_addc_u32 s3, s3, 0
	s_mov_b32 m0, s65
	v_lshl_add_u64 v[226:227], s[2:3], 0, v[168:169]
	ds_read_b128 v[180:183], v193 offset:32768
	ds_read_b128 v[184:187], v193 offset:33792
	ds_read_b128 v[194:197], v193 offset:34816
	ds_read_b128 v[198:201], v193 offset:35840
	ds_read_b128 v[202:205], v193 offset:36864
	ds_read_b128 v[206:209], v193 offset:37888
	ds_read_b128 v[210:213], v193 offset:38912
	ds_read_b128 v[220:223], v193 offset:39936
	global_load_lds_dwordx4 v[226:227], off
	v_lshl_add_u64 v[226:227], s[2:3], 0, v[164:165]
	s_mov_b32 m0, s66
	s_nop 0
	global_load_lds_dwordx4 v[226:227], off
	s_waitcnt vmcnt(8)
	s_waitcnt lgkmcnt(0)
	s_barrier
	s_setprio 1
	v_mfma_f32_16x16x32_bf16 v[138:141], v[114:117], v[180:183], v[138:141]
	v_mfma_f32_16x16x32_bf16 v[134:137], v[130:133], v[180:183], v[134:137]
	v_mfma_f32_16x16x32_bf16 v[110:113], v[114:117], v[194:197], v[110:113]
	v_mfma_f32_16x16x32_bf16 v[106:109], v[130:133], v[194:197], v[106:109]
	v_mfma_f32_16x16x32_bf16 v[94:97], v[114:117], v[202:205], v[94:97]
	v_mfma_f32_16x16x32_bf16 v[90:93], v[130:133], v[202:205], v[90:93]
	v_mfma_f32_16x16x32_bf16 v[78:81], v[114:117], v[210:213], v[78:81]
	v_mfma_f32_16x16x32_bf16 v[74:77], v[130:133], v[210:213], v[74:77]
	v_mfma_f32_16x16x32_bf16 v[138:141], v[122:125], v[184:187], v[138:141]
	v_mfma_f32_16x16x32_bf16 v[134:137], v[142:145], v[184:187], v[134:137]
	v_mfma_f32_16x16x32_bf16 v[110:113], v[122:125], v[198:201], v[110:113]
	v_mfma_f32_16x16x32_bf16 v[106:109], v[142:145], v[198:201], v[106:109]
	v_mfma_f32_16x16x32_bf16 v[94:97], v[122:125], v[206:209], v[94:97]
	v_mfma_f32_16x16x32_bf16 v[90:93], v[142:145], v[206:209], v[90:93]
	v_mfma_f32_16x16x32_bf16 v[78:81], v[122:125], v[220:223], v[78:81]
	v_mfma_f32_16x16x32_bf16 v[74:77], v[142:145], v[220:223], v[74:77]
	v_mfma_f32_16x16x32_bf16 v[126:129], v[146:149], v[180:183], v[126:129]
	v_mfma_f32_16x16x32_bf16 v[118:121], v[172:175], v[180:183], v[118:121]
	v_mfma_f32_16x16x32_bf16 v[102:105], v[146:149], v[194:197], v[102:105]
	v_mfma_f32_16x16x32_bf16 v[98:101], v[172:175], v[194:197], v[98:101]
	v_mfma_f32_16x16x32_bf16 v[86:89], v[146:149], v[202:205], v[86:89]
	v_mfma_f32_16x16x32_bf16 v[82:85], v[172:175], v[202:205], v[82:85]
	v_mfma_f32_16x16x32_bf16 v[70:73], v[146:149], v[210:213], v[70:73]
	v_mfma_f32_16x16x32_bf16 v[66:69], v[172:175], v[210:213], v[66:69]
	v_mfma_f32_16x16x32_bf16 v[126:129], v[150:153], v[184:187], v[126:129]
	v_mfma_f32_16x16x32_bf16 v[118:121], v[176:179], v[184:187], v[118:121]
	v_mfma_f32_16x16x32_bf16 v[102:105], v[150:153], v[198:201], v[102:105]
	v_mfma_f32_16x16x32_bf16 v[98:101], v[176:179], v[198:201], v[98:101]
	v_mfma_f32_16x16x32_bf16 v[86:89], v[150:153], v[206:209], v[86:89]
	v_mfma_f32_16x16x32_bf16 v[82:85], v[176:179], v[206:209], v[82:85]
	v_mfma_f32_16x16x32_bf16 v[70:73], v[150:153], v[220:223], v[70:73]
	v_mfma_f32_16x16x32_bf16 v[66:69], v[176:179], v[220:223], v[66:69]
	s_setprio 0
	s_barrier
	s_add_i32 s2, s55, s62
	v_lshl_add_u64 v[158:159], v[158:159], 0, s[24:25]
	s_mov_b32 m0, s2
	ds_read_b128 v[180:183], v193 offset:49152
	ds_read_b128 v[184:187], v193 offset:50176
	ds_read_b128 v[194:197], v193 offset:51200
	ds_read_b128 v[198:201], v193 offset:52224
	ds_read_b128 v[202:205], v193 offset:53248
	ds_read_b128 v[206:209], v193 offset:54272
	ds_read_b128 v[210:213], v193 offset:55296
	ds_read_b128 v[220:223], v193 offset:56320
	global_load_lds_dwordx4 v[158:159], off
	s_add_i32 m0, s2, 0x2000
	s_add_u32 s2, s52, 0x40080
	v_lshl_add_u64 v[158:159], v[160:161], 0, s[24:25]
	s_addc_u32 s3, s53, 0
	s_add_i32 s52, s56, s62
	global_load_lds_dwordx4 v[158:159], off
	v_lshl_add_u64 v[158:159], s[2:3], 0, v[166:167]
	s_mov_b32 m0, s52
	s_nop 0
	global_load_lds_dwordx4 v[158:159], off
	v_lshl_add_u64 v[158:159], s[2:3], 0, v[162:163]
	s_add_i32 m0, s52, 0x2000
	s_nop 0
	global_load_lds_dwordx4 v[158:159], off
	v_lshl_add_u64 v[158:159], v[188:189], 0, s[24:25]
	s_mov_b32 m0, s8
	s_nop 0
	global_load_lds_dwordx4 v[158:159], off
	v_lshl_add_u64 v[158:159], v[224:225], 0, s[24:25]
	s_mov_b32 m0, s12
	s_nop 0
	global_load_lds_dwordx4 v[158:159], off
	s_waitcnt vmcnt(8)
	s_waitcnt lgkmcnt(0)
	s_barrier
	s_setprio 1
	v_mfma_f32_16x16x32_bf16 v[62:65], v[114:117], v[180:183], v[62:65]
	v_mfma_f32_16x16x32_bf16 v[58:61], v[130:133], v[180:183], v[58:61]
	v_mfma_f32_16x16x32_bf16 v[46:49], v[114:117], v[194:197], v[46:49]
	v_mfma_f32_16x16x32_bf16 v[42:45], v[130:133], v[194:197], v[42:45]
	v_mfma_f32_16x16x32_bf16 v[28:31], v[114:117], v[202:205], v[28:31]
	v_mfma_f32_16x16x32_bf16 v[24:27], v[130:133], v[202:205], v[24:27]
	v_mfma_f32_16x16x32_bf16 v[12:15], v[114:117], v[210:213], v[12:15]
	v_mfma_f32_16x16x32_bf16 v[8:11], v[130:133], v[210:213], v[8:11]
	v_mfma_f32_16x16x32_bf16 v[62:65], v[122:125], v[184:187], v[62:65]
	v_mfma_f32_16x16x32_bf16 v[58:61], v[142:145], v[184:187], v[58:61]
	v_mfma_f32_16x16x32_bf16 v[46:49], v[122:125], v[198:201], v[46:49]
	v_mfma_f32_16x16x32_bf16 v[42:45], v[142:145], v[198:201], v[42:45]
	v_mfma_f32_16x16x32_bf16 v[28:31], v[122:125], v[206:209], v[28:31]
	v_mfma_f32_16x16x32_bf16 v[24:27], v[142:145], v[206:209], v[24:27]
	v_mfma_f32_16x16x32_bf16 v[12:15], v[122:125], v[220:223], v[12:15]
	v_mfma_f32_16x16x32_bf16 v[8:11], v[142:145], v[220:223], v[8:11]
	v_mfma_f32_16x16x32_bf16 v[54:57], v[146:149], v[180:183], v[54:57]
	v_mfma_f32_16x16x32_bf16 v[50:53], v[172:175], v[180:183], v[50:53]
	v_mfma_f32_16x16x32_bf16 v[38:41], v[146:149], v[194:197], v[38:41]
	v_mfma_f32_16x16x32_bf16 v[34:37], v[172:175], v[194:197], v[34:37]
	v_mfma_f32_16x16x32_bf16 v[20:23], v[146:149], v[202:205], v[20:23]
	v_mfma_f32_16x16x32_bf16 v[16:19], v[172:175], v[202:205], v[16:19]
	v_mfma_f32_16x16x32_bf16 v[4:7], v[146:149], v[210:213], v[4:7]
	v_mfma_f32_16x16x32_bf16 v[0:3], v[172:175], v[210:213], v[0:3]
	v_mfma_f32_16x16x32_bf16 v[54:57], v[150:153], v[184:187], v[54:57]
	v_mfma_f32_16x16x32_bf16 v[50:53], v[176:179], v[184:187], v[50:53]
	v_mfma_f32_16x16x32_bf16 v[38:41], v[150:153], v[198:201], v[38:41]
	v_mfma_f32_16x16x32_bf16 v[34:37], v[176:179], v[198:201], v[34:37]
	v_mfma_f32_16x16x32_bf16 v[20:23], v[150:153], v[206:209], v[20:23]
	v_mfma_f32_16x16x32_bf16 v[16:19], v[176:179], v[206:209], v[16:19]
	v_mfma_f32_16x16x32_bf16 v[4:7], v[150:153], v[220:223], v[4:7]
	v_mfma_f32_16x16x32_bf16 v[0:3], v[176:179], v[220:223], v[0:3]
	s_setprio 0
	s_barrier
	s_add_i32 s54, s54, 2
	s_add_u32 s50, s50, 0x100
	s_addc_u32 s51, s51, 0
	s_add_u32 s43, s43, 0x100
	s_addc_u32 s45, s45, 0
	s_cmp_gt_u32 s54, 13
	s_cbranch_scc0 .LBB0_1424
	s_and_b64 vcc, exec, s[40:41]
	s_cbranch_vccz .LBB0_1427
	s_barrier

.LBB0_1688:
	s_add_u32 s0, s46, s38
	s_addc_u32 s1, s47, s39
	s_add_u32 s0, s0, 0x100
	s_addc_u32 s1, s1, 0
	s_add_u32 s59, s12, s38
	s_addc_u32 s61, s21, s39
	s_add_i32 s66, 0, 0x10000
	s_cmpk_eq_i32 s38, 0x700
	s_cselect_b32 s3, s19, s1
	s_cselect_b32 s2, s20, s0
	v_add_u32_e32 v32, s66, v184
	s_cselect_b32 s1, s23, s61
	s_cselect_b32 s0, s40, s59
	s_add_i32 s59, 0, 0x14000
	ds_read_b128 v[134:137], v32
	ds_read_b128 v[162:165], v32 offset:1024
	ds_read_b128 v[166:169], v32 offset:2048
	ds_read_b128 v[170:173], v32 offset:3072
	v_add_u32_e32 v32, s59, v184
	ds_read_b128 v[174:177], v32
	ds_read_b128 v[178:181], v32 offset:1024
	ds_read_b128 v[188:191], v32 offset:2048
	ds_read_b128 v[192:195], v32 offset:3072
	v_lshl_add_u64 v[152:153], v[130:131], 0, s[38:39]
	s_add_i32 m0, s7, 0xc000
	ds_read_b128 v[196:199], v187
	ds_read_b128 v[200:203], v187 offset:1024
	ds_read_b128 v[204:207], v187 offset:2048
	ds_read_b128 v[208:211], v187 offset:3072
	ds_read_b128 v[220:223], v187 offset:4096
	ds_read_b128 v[224:227], v187 offset:5120
	ds_read_b128 v[228:231], v187 offset:6144
	ds_read_b128 v[232:235], v187 offset:7168
	global_load_lds_dwordx4 v[152:153], off
	v_lshl_add_u64 v[152:153], v[132:133], 0, s[38:39]
	s_add_i32 m0, s7, 0xe000
	s_nop 0
	global_load_lds_dwordx4 v[152:153], off
	s_waitcnt vmcnt(8)
	s_waitcnt lgkmcnt(0)
	s_barrier
	s_setprio 1
	v_mfma_f32_16x16x32_bf16 v[126:129], v[134:137], v[196:199], v[126:129]
	v_mfma_f32_16x16x32_bf16 v[122:125], v[166:169], v[196:199], v[122:125]
	v_mfma_f32_16x16x32_bf16 v[118:121], v[134:137], v[204:207], v[118:121]
	v_mfma_f32_16x16x32_bf16 v[114:117], v[166:169], v[204:207], v[114:117]
	v_mfma_f32_16x16x32_bf16 v[110:113], v[134:137], v[220:223], v[110:113]
	v_mfma_f32_16x16x32_bf16 v[106:109], v[166:169], v[220:223], v[106:109]
	v_mfma_f32_16x16x32_bf16 v[102:105], v[134:137], v[228:231], v[102:105]
	v_mfma_f32_16x16x32_bf16 v[98:101], v[166:169], v[228:231], v[98:101]
	v_mfma_f32_16x16x32_bf16 v[126:129], v[162:165], v[200:203], v[126:129]
	v_mfma_f32_16x16x32_bf16 v[122:125], v[170:173], v[200:203], v[122:125]
	v_mfma_f32_16x16x32_bf16 v[118:121], v[162:165], v[208:211], v[118:121]
	v_mfma_f32_16x16x32_bf16 v[114:117], v[170:173], v[208:211], v[114:117]
	v_mfma_f32_16x16x32_bf16 v[110:113], v[162:165], v[224:227], v[110:113]
	v_mfma_f32_16x16x32_bf16 v[106:109], v[170:173], v[224:227], v[106:109]
	v_mfma_f32_16x16x32_bf16 v[102:105], v[162:165], v[232:235], v[102:105]
	v_mfma_f32_16x16x32_bf16 v[98:101], v[170:173], v[232:235], v[98:101]
	v_mfma_f32_16x16x32_bf16 v[94:97], v[174:177], v[196:199], v[94:97]
	v_mfma_f32_16x16x32_bf16 v[90:93], v[188:191], v[196:199], v[90:93]
	v_mfma_f32_16x16x32_bf16 v[86:89], v[174:177], v[204:207], v[86:89]
	v_mfma_f32_16x16x32_bf16 v[82:85], v[188:191], v[204:207], v[82:85]
	v_mfma_f32_16x16x32_bf16 v[78:81], v[174:177], v[220:223], v[78:81]
	v_mfma_f32_16x16x32_bf16 v[74:77], v[188:191], v[220:223], v[74:77]
	v_mfma_f32_16x16x32_bf16 v[70:73], v[174:177], v[228:231], v[70:73]
	v_mfma_f32_16x16x32_bf16 v[66:69], v[188:191], v[228:231], v[66:69]
	v_mfma_f32_16x16x32_bf16 v[94:97], v[178:181], v[200:203], v[94:97]
	v_mfma_f32_16x16x32_bf16 v[90:93], v[192:195], v[200:203], v[90:93]
	v_mfma_f32_16x16x32_bf16 v[86:89], v[178:181], v[208:211], v[86:89]
	v_mfma_f32_16x16x32_bf16 v[82:85], v[192:195], v[208:211], v[82:85]
	v_mfma_f32_16x16x32_bf16 v[78:81], v[178:181], v[224:227], v[78:81]
	v_mfma_f32_16x16x32_bf16 v[74:77], v[192:195], v[224:227], v[74:77]
	v_mfma_f32_16x16x32_bf16 v[70:73], v[178:181], v[232:235], v[70:73]
	v_mfma_f32_16x16x32_bf16 v[66:69], v[192:195], v[232:235], v[66:69]
	s_setprio 0
	s_barrier
	s_add_i32 s61, s66, s18
	v_lshl_add_u64 v[152:153], s[0:1], 0, v[142:143]
	s_mov_b32 m0, s61
	ds_read_b128 v[196:199], v187 offset:16384
	ds_read_b128 v[200:203], v187 offset:17408
	ds_read_b128 v[204:207], v187 offset:18432
	ds_read_b128 v[208:211], v187 offset:19456
	ds_read_b128 v[220:223], v187 offset:20480
	ds_read_b128 v[224:227], v187 offset:21504
	ds_read_b128 v[228:231], v187 offset:22528
	ds_read_b128 v[232:235], v187 offset:23552
	global_load_lds_dwordx4 v[152:153], off
	s_add_i32 m0, s61, 0x2000
	s_add_u32 s66, s0, 0x40000
	v_lshl_add_u64 v[212:213], s[0:1], 0, v[138:139]
	s_addc_u32 s67, s1, 0
	s_add_i32 s59, s59, s18
	global_load_lds_dwordx4 v[212:213], off
	v_lshl_add_u64 v[236:237], s[66:67], 0, v[142:143]
	s_mov_b32 m0, s59
	v_lshl_add_u64 v[238:239], s[2:3], 0, v[140:141]
	global_load_lds_dwordx4 v[236:237], off
	v_lshl_add_u64 v[236:237], s[66:67], 0, v[138:139]
	s_add_i32 m0, s59, 0x2000
	s_nop 0
	global_load_lds_dwordx4 v[236:237], off
	v_lshl_add_u64 v[236:237], s[2:3], 0, v[144:145]
	s_mov_b32 m0, s7
	s_nop 0
	global_load_lds_dwordx4 v[236:237], off
	s_mov_b32 m0, s30
	s_nop 0
	global_load_lds_dwordx4 v[238:239], off
	s_waitcnt vmcnt(8)
	s_waitcnt lgkmcnt(0)
	s_barrier
	s_setprio 1
	v_mfma_f32_16x16x32_bf16 v[62:65], v[134:137], v[196:199], v[62:65]
	v_mfma_f32_16x16x32_bf16 v[58:61], v[166:169], v[196:199], v[58:61]
	v_mfma_f32_16x16x32_bf16 v[54:57], v[134:137], v[204:207], v[54:57]
	v_mfma_f32_16x16x32_bf16 v[50:53], v[166:169], v[204:207], v[50:53]
	v_mfma_f32_16x16x32_bf16 v[46:49], v[134:137], v[220:223], v[46:49]
	v_mfma_f32_16x16x32_bf16 v[42:45], v[166:169], v[220:223], v[42:45]
	v_mfma_f32_16x16x32_bf16 v[38:41], v[134:137], v[228:231], v[38:41]
	v_mfma_f32_16x16x32_bf16 v[34:37], v[166:169], v[228:231], v[34:37]
	v_mfma_f32_16x16x32_bf16 v[62:65], v[162:165], v[200:203], v[62:65]
	v_mfma_f32_16x16x32_bf16 v[58:61], v[170:173], v[200:203], v[58:61]
	v_mfma_f32_16x16x32_bf16 v[54:57], v[162:165], v[208:211], v[54:57]
	v_mfma_f32_16x16x32_bf16 v[50:53], v[170:173], v[208:211], v[50:53]
	v_mfma_f32_16x16x32_bf16 v[46:49], v[162:165], v[224:227], v[46:49]
	v_mfma_f32_16x16x32_bf16 v[42:45], v[170:173], v[224:227], v[42:45]
	v_mfma_f32_16x16x32_bf16 v[38:41], v[162:165], v[232:235], v[38:41]
	v_mfma_f32_16x16x32_bf16 v[34:37], v[170:173], v[232:235], v[34:37]
	v_mfma_f32_16x16x32_bf16 v[28:31], v[174:177], v[196:199], v[28:31]
	v_mfma_f32_16x16x32_bf16 v[24:27], v[188:191], v[196:199], v[24:27]
	v_mfma_f32_16x16x32_bf16 v[20:23], v[174:177], v[204:207], v[20:23]
	v_mfma_f32_16x16x32_bf16 v[16:19], v[188:191], v[204:207], v[16:19]
	v_mfma_f32_16x16x32_bf16 v[12:15], v[174:177], v[220:223], v[12:15]
	v_mfma_f32_16x16x32_bf16 v[8:11], v[188:191], v[220:223], v[8:11]
	v_mfma_f32_16x16x32_bf16 v[4:7], v[174:177], v[228:231], v[4:7]
	v_mfma_f32_16x16x32_bf16 v[0:3], v[188:191], v[228:231], v[0:3]
	v_mfma_f32_16x16x32_bf16 v[28:31], v[178:181], v[200:203], v[28:31]
	v_mfma_f32_16x16x32_bf16 v[24:27], v[192:195], v[200:203], v[24:27]
	v_mfma_f32_16x16x32_bf16 v[20:23], v[178:181], v[208:211], v[20:23]
	v_mfma_f32_16x16x32_bf16 v[16:19], v[192:195], v[208:211], v[16:19]
	v_mfma_f32_16x16x32_bf16 v[12:15], v[178:181], v[224:227], v[12:15]
	v_mfma_f32_16x16x32_bf16 v[8:11], v[192:195], v[224:227], v[8:11]
	v_mfma_f32_16x16x32_bf16 v[4:7], v[178:181], v[232:235], v[4:7]
	v_mfma_f32_16x16x32_bf16 v[0:3], v[192:195], v[232:235], v[0:3]
	s_setprio 0
	s_barrier
	s_add_i32 s59, 0, 0x18000
	v_add_u32_e32 v32, s59, v184
	s_add_i32 s61, 0, 0x1c000
	ds_read_b128 v[134:137], v32
	ds_read_b128 v[162:165], v32 offset:1024
	ds_read_b128 v[166:169], v32 offset:2048
	ds_read_b128 v[170:173], v32 offset:3072
	v_add_u32_e32 v32, s61, v184
	ds_read_b128 v[174:177], v32
	ds_read_b128 v[178:181], v32 offset:1024
	ds_read_b128 v[188:191], v32 offset:2048
	ds_read_b128 v[192:195], v32 offset:3072
	s_add_u32 s2, s2, 0x40000
	s_addc_u32 s3, s3, 0
	s_mov_b32 m0, s31
	v_lshl_add_u64 v[240:241], s[2:3], 0, v[144:145]
	ds_read_b128 v[196:199], v187 offset:32768
	ds_read_b128 v[200:203], v187 offset:33792
	ds_read_b128 v[204:207], v187 offset:34816
	ds_read_b128 v[208:211], v187 offset:35840
	ds_read_b128 v[220:223], v187 offset:36864
	ds_read_b128 v[224:227], v187 offset:37888
	ds_read_b128 v[228:231], v187 offset:38912
	ds_read_b128 v[232:235], v187 offset:39936
	global_load_lds_dwordx4 v[240:241], off
	v_lshl_add_u64 v[240:241], s[2:3], 0, v[140:141]
	s_mov_b32 m0, s43
	s_nop 0
	global_load_lds_dwordx4 v[240:241], off
	s_waitcnt vmcnt(8)
	s_waitcnt lgkmcnt(0)
	s_barrier
	s_setprio 1
	v_mfma_f32_16x16x32_bf16 v[126:129], v[134:137], v[196:199], v[126:129]
	v_mfma_f32_16x16x32_bf16 v[122:125], v[166:169], v[196:199], v[122:125]
	v_mfma_f32_16x16x32_bf16 v[118:121], v[134:137], v[204:207], v[118:121]
	v_mfma_f32_16x16x32_bf16 v[114:117], v[166:169], v[204:207], v[114:117]
	v_mfma_f32_16x16x32_bf16 v[110:113], v[134:137], v[220:223], v[110:113]
	v_mfma_f32_16x16x32_bf16 v[106:109], v[166:169], v[220:223], v[106:109]
	v_mfma_f32_16x16x32_bf16 v[102:105], v[134:137], v[228:231], v[102:105]
	v_mfma_f32_16x16x32_bf16 v[98:101], v[166:169], v[228:231], v[98:101]
	v_mfma_f32_16x16x32_bf16 v[126:129], v[162:165], v[200:203], v[126:129]
	v_mfma_f32_16x16x32_bf16 v[122:125], v[170:173], v[200:203], v[122:125]
	v_mfma_f32_16x16x32_bf16 v[118:121], v[162:165], v[208:211], v[118:121]
	v_mfma_f32_16x16x32_bf16 v[114:117], v[170:173], v[208:211], v[114:117]
	v_mfma_f32_16x16x32_bf16 v[110:113], v[162:165], v[224:227], v[110:113]
	v_mfma_f32_16x16x32_bf16 v[106:109], v[170:173], v[224:227], v[106:109]
	v_mfma_f32_16x16x32_bf16 v[102:105], v[162:165], v[232:235], v[102:105]
	v_mfma_f32_16x16x32_bf16 v[98:101], v[170:173], v[232:235], v[98:101]
	v_mfma_f32_16x16x32_bf16 v[94:97], v[174:177], v[196:199], v[94:97]
	v_mfma_f32_16x16x32_bf16 v[90:93], v[188:191], v[196:199], v[90:93]
	v_mfma_f32_16x16x32_bf16 v[86:89], v[174:177], v[204:207], v[86:89]
	v_mfma_f32_16x16x32_bf16 v[82:85], v[188:191], v[204:207], v[82:85]
	v_mfma_f32_16x16x32_bf16 v[78:81], v[174:177], v[220:223], v[78:81]
	v_mfma_f32_16x16x32_bf16 v[74:77], v[188:191], v[220:223], v[74:77]
	v_mfma_f32_16x16x32_bf16 v[70:73], v[174:177], v[228:231], v[70:73]
	v_mfma_f32_16x16x32_bf16 v[66:69], v[188:191], v[228:231], v[66:69]
	v_mfma_f32_16x16x32_bf16 v[94:97], v[178:181], v[200:203], v[94:97]
	v_mfma_f32_16x16x32_bf16 v[90:93], v[192:195], v[200:203], v[90:93]
	v_mfma_f32_16x16x32_bf16 v[86:89], v[178:181], v[208:211], v[86:89]
	v_mfma_f32_16x16x32_bf16 v[82:85], v[192:195], v[208:211], v[82:85]
	v_mfma_f32_16x16x32_bf16 v[78:81], v[178:181], v[224:227], v[78:81]
	v_mfma_f32_16x16x32_bf16 v[74:77], v[192:195], v[224:227], v[74:77]
	v_mfma_f32_16x16x32_bf16 v[70:73], v[178:181], v[232:235], v[70:73]
	v_mfma_f32_16x16x32_bf16 v[66:69], v[192:195], v[232:235], v[66:69]
	s_setprio 0
	s_barrier
	s_add_i32 s2, s59, s18
	v_lshl_add_u64 v[152:153], v[152:153], 0, s[24:25]
	s_mov_b32 m0, s2
	ds_read_b128 v[196:199], v187 offset:49152
	ds_read_b128 v[200:203], v187 offset:50176
	ds_read_b128 v[204:207], v187 offset:51200
	ds_read_b128 v[208:211], v187 offset:52224
	ds_read_b128 v[220:223], v187 offset:53248
	ds_read_b128 v[224:227], v187 offset:54272
	ds_read_b128 v[228:231], v187 offset:55296
	ds_read_b128 v[232:235], v187 offset:56320
	global_load_lds_dwordx4 v[152:153], off
	s_add_i32 m0, s2, 0x2000
	s_add_u32 s0, s0, 0x40080
	v_lshl_add_u64 v[152:153], v[212:213], 0, s[24:25]
	s_addc_u32 s1, s1, 0
	s_add_i32 s2, s61, s18
	global_load_lds_dwordx4 v[152:153], off
	v_lshl_add_u64 v[152:153], s[0:1], 0, v[142:143]
	s_mov_b32 m0, s2
	s_nop 0
	global_load_lds_dwordx4 v[152:153], off
	v_lshl_add_u64 v[152:153], s[0:1], 0, v[138:139]
	s_add_i32 m0, s2, 0x2000
	s_nop 0
	global_load_lds_dwordx4 v[152:153], off
	v_lshl_add_u64 v[152:153], v[236:237], 0, s[24:25]
	s_mov_b32 m0, s68
	s_nop 0
	global_load_lds_dwordx4 v[152:153], off
	v_lshl_add_u64 v[152:153], v[238:239], 0, s[24:25]
	s_mov_b32 m0, s69
	s_nop 0
	global_load_lds_dwordx4 v[152:153], off
	s_waitcnt vmcnt(8)
	s_waitcnt lgkmcnt(0)
	s_barrier
	s_setprio 1
	v_mfma_f32_16x16x32_bf16 v[62:65], v[134:137], v[196:199], v[62:65]
	v_mfma_f32_16x16x32_bf16 v[58:61], v[166:169], v[196:199], v[58:61]
	v_mfma_f32_16x16x32_bf16 v[54:57], v[134:137], v[204:207], v[54:57]
	v_mfma_f32_16x16x32_bf16 v[50:53], v[166:169], v[204:207], v[50:53]
	v_mfma_f32_16x16x32_bf16 v[46:49], v[134:137], v[220:223], v[46:49]
	v_mfma_f32_16x16x32_bf16 v[42:45], v[166:169], v[220:223], v[42:45]
	v_mfma_f32_16x16x32_bf16 v[38:41], v[134:137], v[228:231], v[38:41]
	v_mfma_f32_16x16x32_bf16 v[34:37], v[166:169], v[228:231], v[34:37]
	v_mfma_f32_16x16x32_bf16 v[62:65], v[162:165], v[200:203], v[62:65]
	v_mfma_f32_16x16x32_bf16 v[58:61], v[170:173], v[200:203], v[58:61]
	v_mfma_f32_16x16x32_bf16 v[54:57], v[162:165], v[208:211], v[54:57]
	v_mfma_f32_16x16x32_bf16 v[50:53], v[170:173], v[208:211], v[50:53]
	v_mfma_f32_16x16x32_bf16 v[46:49], v[162:165], v[224:227], v[46:49]
	v_mfma_f32_16x16x32_bf16 v[42:45], v[170:173], v[224:227], v[42:45]
	v_mfma_f32_16x16x32_bf16 v[38:41], v[162:165], v[232:235], v[38:41]
	v_mfma_f32_16x16x32_bf16 v[34:37], v[170:173], v[232:235], v[34:37]
	v_mfma_f32_16x16x32_bf16 v[28:31], v[174:177], v[196:199], v[28:31]
	v_mfma_f32_16x16x32_bf16 v[24:27], v[188:191], v[196:199], v[24:27]
	v_mfma_f32_16x16x32_bf16 v[20:23], v[174:177], v[204:207], v[20:23]
	v_mfma_f32_16x16x32_bf16 v[16:19], v[188:191], v[204:207], v[16:19]
	v_mfma_f32_16x16x32_bf16 v[12:15], v[174:177], v[220:223], v[12:15]
	v_mfma_f32_16x16x32_bf16 v[8:11], v[188:191], v[220:223], v[8:11]
	v_mfma_f32_16x16x32_bf16 v[4:7], v[174:177], v[228:231], v[4:7]
	v_mfma_f32_16x16x32_bf16 v[0:3], v[188:191], v[228:231], v[0:3]
	v_mfma_f32_16x16x32_bf16 v[28:31], v[178:181], v[200:203], v[28:31]
	v_mfma_f32_16x16x32_bf16 v[24:27], v[192:195], v[200:203], v[24:27]
	v_mfma_f32_16x16x32_bf16 v[20:23], v[178:181], v[208:211], v[20:23]
	v_mfma_f32_16x16x32_bf16 v[16:19], v[192:195], v[208:211], v[16:19]
	v_mfma_f32_16x16x32_bf16 v[12:15], v[178:181], v[224:227], v[12:15]
	v_mfma_f32_16x16x32_bf16 v[8:11], v[192:195], v[224:227], v[8:11]
	v_mfma_f32_16x16x32_bf16 v[4:7], v[178:181], v[232:235], v[4:7]
	v_mfma_f32_16x16x32_bf16 v[0:3], v[192:195], v[232:235], v[0:3]
	s_setprio 0
	s_barrier
	s_add_i32 s41, s41, 2
	s_add_u32 s38, s38, 0x100
	s_addc_u32 s39, s39, 0
	s_cmp_gt_u32 s41, 13
	s_cbranch_scc0 .LBB0_1688
	s_and_b64 vcc, exec, s[56:57]
	s_cbranch_vccz .LBB0_1691
	s_barrier

.LBB0_2226:
	s_add_u32 s0, s50, 0xfffc0080
	s_addc_u32 s1, s51, -1
	s_add_i32 s55, 0, 0x10000
	s_cmp_eq_u32 s54, 12
	s_cselect_b32 s3, s21, s1
	s_cselect_b32 s2, s23, s0
	s_cselect_b32 s1, s43, s53
	s_cselect_b32 s0, s45, s52
	s_add_i32 s58, 0, 0x14000
	v_add_u32_e32 v142, s55, v191
	v_add_u32_e32 v158, s58, v191
	ds_read_b128 v[114:117], v142
	ds_read_b128 v[122:125], v142 offset:1024
	ds_read_b128 v[130:133], v142 offset:2048
	ds_read_b128 v[142:145], v142 offset:3072
	ds_read_b128 v[146:149], v158
	ds_read_b128 v[150:153], v158 offset:1024
	ds_read_b128 v[172:175], v158 offset:2048
	ds_read_b128 v[176:179], v158 offset:3072
	v_lshl_add_u64 v[188:189], s[50:51], 0, v[32:33]
	s_add_i32 m0, s30, 0xc000
	ds_read_b128 v[180:183], v193
	ds_read_b128 v[184:187], v193 offset:1024
	ds_read_b128 v[194:197], v193 offset:2048
	ds_read_b128 v[198:201], v193 offset:3072
	ds_read_b128 v[202:205], v193 offset:4096
	ds_read_b128 v[206:209], v193 offset:5120
	ds_read_b128 v[210:213], v193 offset:6144
	ds_read_b128 v[220:223], v193 offset:7168
	global_load_lds_dwordx4 v[188:189], off
	v_lshl_add_u64 v[188:189], s[50:51], 0, v[170:171]
	s_add_i32 m0, s30, 0xe000
	s_nop 0
	global_load_lds_dwordx4 v[188:189], off
	s_waitcnt vmcnt(8)
	s_waitcnt lgkmcnt(0)
	s_barrier
	s_setprio 1
	v_mfma_f32_16x16x32_bf16 v[138:141], v[114:117], v[180:183], v[138:141]
	v_mfma_f32_16x16x32_bf16 v[134:137], v[130:133], v[180:183], v[134:137]
	v_mfma_f32_16x16x32_bf16 v[110:113], v[114:117], v[194:197], v[110:113]
	v_mfma_f32_16x16x32_bf16 v[106:109], v[130:133], v[194:197], v[106:109]
	v_mfma_f32_16x16x32_bf16 v[94:97], v[114:117], v[202:205], v[94:97]
	v_mfma_f32_16x16x32_bf16 v[90:93], v[130:133], v[202:205], v[90:93]
	v_mfma_f32_16x16x32_bf16 v[78:81], v[114:117], v[210:213], v[78:81]
	v_mfma_f32_16x16x32_bf16 v[74:77], v[130:133], v[210:213], v[74:77]
	v_mfma_f32_16x16x32_bf16 v[138:141], v[122:125], v[184:187], v[138:141]
	v_mfma_f32_16x16x32_bf16 v[134:137], v[142:145], v[184:187], v[134:137]
	v_mfma_f32_16x16x32_bf16 v[110:113], v[122:125], v[198:201], v[110:113]
	v_mfma_f32_16x16x32_bf16 v[106:109], v[142:145], v[198:201], v[106:109]
	v_mfma_f32_16x16x32_bf16 v[94:97], v[122:125], v[206:209], v[94:97]
	v_mfma_f32_16x16x32_bf16 v[90:93], v[142:145], v[206:209], v[90:93]
	v_mfma_f32_16x16x32_bf16 v[78:81], v[122:125], v[220:223], v[78:81]
	v_mfma_f32_16x16x32_bf16 v[74:77], v[142:145], v[220:223], v[74:77]
	v_mfma_f32_16x16x32_bf16 v[126:129], v[146:149], v[180:183], v[126:129]
	v_mfma_f32_16x16x32_bf16 v[118:121], v[172:175], v[180:183], v[118:121]
	v_mfma_f32_16x16x32_bf16 v[102:105], v[146:149], v[194:197], v[102:105]
	v_mfma_f32_16x16x32_bf16 v[98:101], v[172:175], v[194:197], v[98:101]
	v_mfma_f32_16x16x32_bf16 v[86:89], v[146:149], v[202:205], v[86:89]
	v_mfma_f32_16x16x32_bf16 v[82:85], v[172:175], v[202:205], v[82:85]
	v_mfma_f32_16x16x32_bf16 v[70:73], v[146:149], v[210:213], v[70:73]
	v_mfma_f32_16x16x32_bf16 v[66:69], v[172:175], v[210:213], v[66:69]
	v_mfma_f32_16x16x32_bf16 v[126:129], v[150:153], v[184:187], v[126:129]
	v_mfma_f32_16x16x32_bf16 v[118:121], v[176:179], v[184:187], v[118:121]
	v_mfma_f32_16x16x32_bf16 v[102:105], v[150:153], v[198:201], v[102:105]
	v_mfma_f32_16x16x32_bf16 v[98:101], v[176:179], v[198:201], v[98:101]
	v_mfma_f32_16x16x32_bf16 v[86:89], v[150:153], v[206:209], v[86:89]
	v_mfma_f32_16x16x32_bf16 v[82:85], v[176:179], v[206:209], v[82:85]
	v_mfma_f32_16x16x32_bf16 v[70:73], v[150:153], v[220:223], v[70:73]
	v_mfma_f32_16x16x32_bf16 v[66:69], v[176:179], v[220:223], v[66:69]
	s_setprio 0
	s_barrier
	s_add_i32 s55, s55, s29
	v_lshl_add_u64 v[188:189], s[0:1], 0, v[166:167]
	s_mov_b32 m0, s55
	ds_read_b128 v[180:183], v193 offset:16384
	ds_read_b128 v[184:187], v193 offset:17408
	ds_read_b128 v[194:197], v193 offset:18432
	ds_read_b128 v[198:201], v193 offset:19456
	ds_read_b128 v[202:205], v193 offset:20480
	ds_read_b128 v[206:209], v193 offset:21504
	ds_read_b128 v[210:213], v193 offset:22528
	ds_read_b128 v[220:223], v193 offset:23552
	global_load_lds_dwordx4 v[188:189], off
	s_add_i32 m0, s55, 0x2000
	s_add_u32 s56, s0, 0x40000
	v_lshl_add_u64 v[224:225], s[0:1], 0, v[162:163]
	s_addc_u32 s57, s1, 0
	s_add_i32 s55, s58, s29
	global_load_lds_dwordx4 v[224:225], off
	v_lshl_add_u64 v[226:227], s[56:57], 0, v[166:167]
	s_mov_b32 m0, s55
	v_lshl_add_u64 v[228:229], s[2:3], 0, v[164:165]
	global_load_lds_dwordx4 v[226:227], off
	v_lshl_add_u64 v[226:227], s[56:57], 0, v[162:163]
	s_add_i32 m0, s55, 0x2000
	s_nop 0
	global_load_lds_dwordx4 v[226:227], off
	v_lshl_add_u64 v[226:227], s[2:3], 0, v[168:169]
	s_mov_b32 m0, s30
	s_nop 0
	global_load_lds_dwordx4 v[226:227], off
	s_mov_b32 m0, s31
	s_nop 0
	global_load_lds_dwordx4 v[228:229], off
	s_waitcnt vmcnt(8)
	s_waitcnt lgkmcnt(0)
	s_barrier
	s_setprio 1
	v_mfma_f32_16x16x32_bf16 v[62:65], v[114:117], v[180:183], v[62:65]
	v_mfma_f32_16x16x32_bf16 v[58:61], v[130:133], v[180:183], v[58:61]
	v_mfma_f32_16x16x32_bf16 v[46:49], v[114:117], v[194:197], v[46:49]
	v_mfma_f32_16x16x32_bf16 v[42:45], v[130:133], v[194:197], v[42:45]
	v_mfma_f32_16x16x32_bf16 v[28:31], v[114:117], v[202:205], v[28:31]
	v_mfma_f32_16x16x32_bf16 v[24:27], v[130:133], v[202:205], v[24:27]
	v_mfma_f32_16x16x32_bf16 v[12:15], v[114:117], v[210:213], v[12:15]
	v_mfma_f32_16x16x32_bf16 v[8:11], v[130:133], v[210:213], v[8:11]
	v_mfma_f32_16x16x32_bf16 v[62:65], v[122:125], v[184:187], v[62:65]
	v_mfma_f32_16x16x32_bf16 v[58:61], v[142:145], v[184:187], v[58:61]
	v_mfma_f32_16x16x32_bf16 v[46:49], v[122:125], v[198:201], v[46:49]
	v_mfma_f32_16x16x32_bf16 v[42:45], v[142:145], v[198:201], v[42:45]
	v_mfma_f32_16x16x32_bf16 v[28:31], v[122:125], v[206:209], v[28:31]
	v_mfma_f32_16x16x32_bf16 v[24:27], v[142:145], v[206:209], v[24:27]
	v_mfma_f32_16x16x32_bf16 v[12:15], v[122:125], v[220:223], v[12:15]
	v_mfma_f32_16x16x32_bf16 v[8:11], v[142:145], v[220:223], v[8:11]
	v_mfma_f32_16x16x32_bf16 v[54:57], v[146:149], v[180:183], v[54:57]
	v_mfma_f32_16x16x32_bf16 v[50:53], v[172:175], v[180:183], v[50:53]
	v_mfma_f32_16x16x32_bf16 v[38:41], v[146:149], v[194:197], v[38:41]
	v_mfma_f32_16x16x32_bf16 v[34:37], v[172:175], v[194:197], v[34:37]
	v_mfma_f32_16x16x32_bf16 v[20:23], v[146:149], v[202:205], v[20:23]
	v_mfma_f32_16x16x32_bf16 v[16:19], v[172:175], v[202:205], v[16:19]
	v_mfma_f32_16x16x32_bf16 v[4:7], v[146:149], v[210:213], v[4:7]
	v_mfma_f32_16x16x32_bf16 v[0:3], v[172:175], v[210:213], v[0:3]
	v_mfma_f32_16x16x32_bf16 v[54:57], v[150:153], v[184:187], v[54:57]
	v_mfma_f32_16x16x32_bf16 v[50:53], v[176:179], v[184:187], v[50:53]
	v_mfma_f32_16x16x32_bf16 v[38:41], v[150:153], v[198:201], v[38:41]
	v_mfma_f32_16x16x32_bf16 v[34:37], v[176:179], v[198:201], v[34:37]
	v_mfma_f32_16x16x32_bf16 v[20:23], v[150:153], v[206:209], v[20:23]
	v_mfma_f32_16x16x32_bf16 v[16:19], v[176:179], v[206:209], v[16:19]
	v_mfma_f32_16x16x32_bf16 v[4:7], v[150:153], v[220:223], v[4:7]
	v_mfma_f32_16x16x32_bf16 v[0:3], v[176:179], v[220:223], v[0:3]
	s_setprio 0
	s_barrier
	s_add_i32 s55, 0, 0x18000
	s_add_i32 s56, 0, 0x1c000
	v_add_u32_e32 v142, s55, v191
	v_add_u32_e32 v158, s56, v191
	ds_read_b128 v[114:117], v142
	ds_read_b128 v[122:125], v142 offset:1024
	ds_read_b128 v[130:133], v142 offset:2048
	ds_read_b128 v[142:145], v142 offset:3072
	ds_read_b128 v[146:149], v158
	ds_read_b128 v[150:153], v158 offset:1024
	ds_read_b128 v[172:175], v158 offset:2048
	ds_read_b128 v[176:179], v158 offset:3072
	s_add_u32 s2, s2, 0x40000
	s_addc_u32 s3, s3, 0
	s_mov_b32 m0, s62
	v_lshl_add_u64 v[230:231], s[2:3], 0, v[168:169]
	ds_read_b128 v[180:183], v193 offset:32768
	ds_read_b128 v[184:187], v193 offset:33792
	ds_read_b128 v[194:197], v193 offset:34816
	ds_read_b128 v[198:201], v193 offset:35840
	ds_read_b128 v[202:205], v193 offset:36864
	ds_read_b128 v[206:209], v193 offset:37888
	ds_read_b128 v[210:213], v193 offset:38912
	ds_read_b128 v[220:223], v193 offset:39936
	global_load_lds_dwordx4 v[230:231], off
	v_lshl_add_u64 v[230:231], s[2:3], 0, v[164:165]
	s_mov_b32 m0, s63
	s_nop 0
	global_load_lds_dwordx4 v[230:231], off
	s_waitcnt vmcnt(8)
	s_waitcnt lgkmcnt(0)
	s_barrier
	s_setprio 1
	v_mfma_f32_16x16x32_bf16 v[138:141], v[114:117], v[180:183], v[138:141]
	v_mfma_f32_16x16x32_bf16 v[134:137], v[130:133], v[180:183], v[134:137]
	v_mfma_f32_16x16x32_bf16 v[110:113], v[114:117], v[194:197], v[110:113]
	v_mfma_f32_16x16x32_bf16 v[106:109], v[130:133], v[194:197], v[106:109]
	v_mfma_f32_16x16x32_bf16 v[94:97], v[114:117], v[202:205], v[94:97]
	v_mfma_f32_16x16x32_bf16 v[90:93], v[130:133], v[202:205], v[90:93]
	v_mfma_f32_16x16x32_bf16 v[78:81], v[114:117], v[210:213], v[78:81]
	v_mfma_f32_16x16x32_bf16 v[74:77], v[130:133], v[210:213], v[74:77]
	v_mfma_f32_16x16x32_bf16 v[138:141], v[122:125], v[184:187], v[138:141]
	v_mfma_f32_16x16x32_bf16 v[134:137], v[142:145], v[184:187], v[134:137]
	v_mfma_f32_16x16x32_bf16 v[110:113], v[122:125], v[198:201], v[110:113]
	v_mfma_f32_16x16x32_bf16 v[106:109], v[142:145], v[198:201], v[106:109]
	v_mfma_f32_16x16x32_bf16 v[94:97], v[122:125], v[206:209], v[94:97]
	v_mfma_f32_16x16x32_bf16 v[90:93], v[142:145], v[206:209], v[90:93]
	v_mfma_f32_16x16x32_bf16 v[78:81], v[122:125], v[220:223], v[78:81]
	v_mfma_f32_16x16x32_bf16 v[74:77], v[142:145], v[220:223], v[74:77]
	v_mfma_f32_16x16x32_bf16 v[126:129], v[146:149], v[180:183], v[126:129]
	v_mfma_f32_16x16x32_bf16 v[118:121], v[172:175], v[180:183], v[118:121]
	v_mfma_f32_16x16x32_bf16 v[102:105], v[146:149], v[194:197], v[102:105]
	v_mfma_f32_16x16x32_bf16 v[98:101], v[172:175], v[194:197], v[98:101]
	v_mfma_f32_16x16x32_bf16 v[86:89], v[146:149], v[202:205], v[86:89]
	v_mfma_f32_16x16x32_bf16 v[82:85], v[172:175], v[202:205], v[82:85]
	v_mfma_f32_16x16x32_bf16 v[70:73], v[146:149], v[210:213], v[70:73]
	v_mfma_f32_16x16x32_bf16 v[66:69], v[172:175], v[210:213], v[66:69]
	v_mfma_f32_16x16x32_bf16 v[126:129], v[150:153], v[184:187], v[126:129]
	v_mfma_f32_16x16x32_bf16 v[118:121], v[176:179], v[184:187], v[118:121]
	v_mfma_f32_16x16x32_bf16 v[102:105], v[150:153], v[198:201], v[102:105]
	v_mfma_f32_16x16x32_bf16 v[98:101], v[176:179], v[198:201], v[98:101]
	v_mfma_f32_16x16x32_bf16 v[86:89], v[150:153], v[206:209], v[86:89]
	v_mfma_f32_16x16x32_bf16 v[82:85], v[176:179], v[206:209], v[82:85]
	v_mfma_f32_16x16x32_bf16 v[70:73], v[150:153], v[220:223], v[70:73]
	v_mfma_f32_16x16x32_bf16 v[66:69], v[176:179], v[220:223], v[66:69]
	s_setprio 0
	s_barrier
	s_add_i32 s2, s55, s29
	v_lshl_add_u64 v[188:189], v[188:189], 0, s[24:25]
	s_mov_b32 m0, s2
	ds_read_b128 v[180:183], v193 offset:49152
	ds_read_b128 v[184:187], v193 offset:50176
	ds_read_b128 v[194:197], v193 offset:51200
	ds_read_b128 v[198:201], v193 offset:52224
	ds_read_b128 v[202:205], v193 offset:53248
	ds_read_b128 v[206:209], v193 offset:54272
	ds_read_b128 v[210:213], v193 offset:55296
	ds_read_b128 v[220:223], v193 offset:56320
	global_load_lds_dwordx4 v[188:189], off
	s_add_i32 m0, s2, 0x2000
	s_add_u32 s0, s0, 0x40080
	v_lshl_add_u64 v[188:189], v[224:225], 0, s[24:25]
	s_addc_u32 s1, s1, 0
	s_add_i32 s2, s56, s29
	global_load_lds_dwordx4 v[188:189], off
	v_lshl_add_u64 v[188:189], s[0:1], 0, v[166:167]
	s_mov_b32 m0, s2
	s_nop 0
	global_load_lds_dwordx4 v[188:189], off
	v_lshl_add_u64 v[188:189], s[0:1], 0, v[162:163]
	s_add_i32 m0, s2, 0x2000
	s_nop 0
	global_load_lds_dwordx4 v[188:189], off
	v_lshl_add_u64 v[188:189], v[226:227], 0, s[24:25]
	s_mov_b32 m0, s8
	s_nop 0
	global_load_lds_dwordx4 v[188:189], off
	v_lshl_add_u64 v[188:189], v[228:229], 0, s[24:25]
	s_mov_b32 m0, s12
	s_nop 0
	global_load_lds_dwordx4 v[188:189], off
	s_waitcnt vmcnt(8)
	s_waitcnt lgkmcnt(0)
	s_barrier
	s_setprio 1
	v_mfma_f32_16x16x32_bf16 v[62:65], v[114:117], v[180:183], v[62:65]
	v_mfma_f32_16x16x32_bf16 v[58:61], v[130:133], v[180:183], v[58:61]
	v_mfma_f32_16x16x32_bf16 v[46:49], v[114:117], v[194:197], v[46:49]
	v_mfma_f32_16x16x32_bf16 v[42:45], v[130:133], v[194:197], v[42:45]
	v_mfma_f32_16x16x32_bf16 v[28:31], v[114:117], v[202:205], v[28:31]
	v_mfma_f32_16x16x32_bf16 v[24:27], v[130:133], v[202:205], v[24:27]
	v_mfma_f32_16x16x32_bf16 v[12:15], v[114:117], v[210:213], v[12:15]
	v_mfma_f32_16x16x32_bf16 v[8:11], v[130:133], v[210:213], v[8:11]
	v_mfma_f32_16x16x32_bf16 v[62:65], v[122:125], v[184:187], v[62:65]
	v_mfma_f32_16x16x32_bf16 v[58:61], v[142:145], v[184:187], v[58:61]
	v_mfma_f32_16x16x32_bf16 v[46:49], v[122:125], v[198:201], v[46:49]
	v_mfma_f32_16x16x32_bf16 v[42:45], v[142:145], v[198:201], v[42:45]
	v_mfma_f32_16x16x32_bf16 v[28:31], v[122:125], v[206:209], v[28:31]
	v_mfma_f32_16x16x32_bf16 v[24:27], v[142:145], v[206:209], v[24:27]
	v_mfma_f32_16x16x32_bf16 v[12:15], v[122:125], v[220:223], v[12:15]
	v_mfma_f32_16x16x32_bf16 v[8:11], v[142:145], v[220:223], v[8:11]
	v_mfma_f32_16x16x32_bf16 v[54:57], v[146:149], v[180:183], v[54:57]
	v_mfma_f32_16x16x32_bf16 v[50:53], v[172:175], v[180:183], v[50:53]
	v_mfma_f32_16x16x32_bf16 v[38:41], v[146:149], v[194:197], v[38:41]
	v_mfma_f32_16x16x32_bf16 v[34:37], v[172:175], v[194:197], v[34:37]
	v_mfma_f32_16x16x32_bf16 v[20:23], v[146:149], v[202:205], v[20:23]
	v_mfma_f32_16x16x32_bf16 v[16:19], v[172:175], v[202:205], v[16:19]
	v_mfma_f32_16x16x32_bf16 v[4:7], v[146:149], v[210:213], v[4:7]
	v_mfma_f32_16x16x32_bf16 v[0:3], v[172:175], v[210:213], v[0:3]
	v_mfma_f32_16x16x32_bf16 v[54:57], v[150:153], v[184:187], v[54:57]
	v_mfma_f32_16x16x32_bf16 v[50:53], v[176:179], v[184:187], v[50:53]
	v_mfma_f32_16x16x32_bf16 v[38:41], v[150:153], v[198:201], v[38:41]
	v_mfma_f32_16x16x32_bf16 v[34:37], v[176:179], v[198:201], v[34:37]
	v_mfma_f32_16x16x32_bf16 v[20:23], v[150:153], v[206:209], v[20:23]
	v_mfma_f32_16x16x32_bf16 v[16:19], v[176:179], v[206:209], v[16:19]
	v_mfma_f32_16x16x32_bf16 v[4:7], v[150:153], v[220:223], v[4:7]
	v_mfma_f32_16x16x32_bf16 v[0:3], v[176:179], v[220:223], v[0:3]
	s_setprio 0
	s_barrier
	s_add_i32 s54, s54, 2
	s_add_u32 s50, s50, 0x100
	s_addc_u32 s51, s51, 0
	s_add_u32 s52, s52, 0x100
	s_addc_u32 s53, s53, 0
	s_cmp_gt_u32 s54, 13
	s_cbranch_scc0 .LBB0_2226
	s_and_b64 vcc, exec, s[40:41]
	s_cbranch_vccz .LBB0_2229
	s_barrier

.LBB0_2536:
	s_add_u32 s2, s56, 0xfffc0080
	s_addc_u32 s3, s57, -1
	s_add_i32 s34, 0, 0x10000
	s_cmp_eq_u32 s31, 12
	s_cselect_b32 s3, s19, s3
	s_cselect_b32 s2, s21, s2
	v_add_u32_e32 v158, s34, v165
	s_cselect_b32 s43, s23, s30
	s_cselect_b32 s42, s28, s29
	s_add_i32 s41, 0, 0x14000
	ds_read_b128 v[142:145], v158
	ds_read_b128 v[146:149], v158 offset:1024
	ds_read_b128 v[150:153], v158 offset:2048
	ds_read_b128 v[176:179], v158 offset:3072
	v_add_u32_e32 v158, s41, v165
	ds_read_b128 v[180:183], v158
	ds_read_b128 v[184:187], v158 offset:1024
	ds_read_b128 v[188:191], v158 offset:2048
	ds_read_b128 v[192:195], v158 offset:3072
	v_lshl_add_u64 v[158:159], s[56:57], 0, v[32:33]
	s_add_i32 m0, s75, 0xc000
	ds_read_b128 v[196:199], v175
	ds_read_b128 v[200:203], v175 offset:1024
	ds_read_b128 v[204:207], v175 offset:2048
	ds_read_b128 v[208:211], v175 offset:3072
	ds_read_b128 v[220:223], v175 offset:4096
	ds_read_b128 v[224:227], v175 offset:5120
	ds_read_b128 v[228:231], v175 offset:6144
	ds_read_b128 v[232:235], v175 offset:7168
	global_load_lds_dwordx4 v[158:159], off
	v_lshl_add_u64 v[158:159], s[56:57], 0, v[140:141]
	s_add_i32 m0, s75, 0xe000
	s_nop 0
	global_load_lds_dwordx4 v[158:159], off
	s_waitcnt vmcnt(8)
	s_waitcnt lgkmcnt(0)
	s_barrier
	s_setprio 1
	v_mfma_f32_16x16x32_bf16 v[126:129], v[142:145], v[196:199], v[126:129]
	v_mfma_f32_16x16x32_bf16 v[118:121], v[150:153], v[196:199], v[118:121]
	v_mfma_f32_16x16x32_bf16 v[110:113], v[142:145], v[204:207], v[110:113]
	v_mfma_f32_16x16x32_bf16 v[102:105], v[150:153], v[204:207], v[102:105]
	v_mfma_f32_16x16x32_bf16 v[94:97], v[142:145], v[220:223], v[94:97]
	v_mfma_f32_16x16x32_bf16 v[86:89], v[150:153], v[220:223], v[86:89]
	v_mfma_f32_16x16x32_bf16 v[78:81], v[142:145], v[228:231], v[78:81]
	v_mfma_f32_16x16x32_bf16 v[70:73], v[150:153], v[228:231], v[70:73]
	v_mfma_f32_16x16x32_bf16 v[126:129], v[146:149], v[200:203], v[126:129]
	v_mfma_f32_16x16x32_bf16 v[118:121], v[176:179], v[200:203], v[118:121]
	v_mfma_f32_16x16x32_bf16 v[110:113], v[146:149], v[208:211], v[110:113]
	v_mfma_f32_16x16x32_bf16 v[102:105], v[176:179], v[208:211], v[102:105]
	v_mfma_f32_16x16x32_bf16 v[94:97], v[146:149], v[224:227], v[94:97]
	v_mfma_f32_16x16x32_bf16 v[86:89], v[176:179], v[224:227], v[86:89]
	v_mfma_f32_16x16x32_bf16 v[78:81], v[146:149], v[232:235], v[78:81]
	v_mfma_f32_16x16x32_bf16 v[70:73], v[176:179], v[232:235], v[70:73]
	v_mfma_f32_16x16x32_bf16 v[122:125], v[180:183], v[196:199], v[122:125]
	v_mfma_f32_16x16x32_bf16 v[114:117], v[188:191], v[196:199], v[114:117]
	v_mfma_f32_16x16x32_bf16 v[106:109], v[180:183], v[204:207], v[106:109]
	v_mfma_f32_16x16x32_bf16 v[98:101], v[188:191], v[204:207], v[98:101]
	v_mfma_f32_16x16x32_bf16 v[90:93], v[180:183], v[220:223], v[90:93]
	v_mfma_f32_16x16x32_bf16 v[82:85], v[188:191], v[220:223], v[82:85]
	v_mfma_f32_16x16x32_bf16 v[74:77], v[180:183], v[228:231], v[74:77]
	v_mfma_f32_16x16x32_bf16 v[66:69], v[188:191], v[228:231], v[66:69]
	v_mfma_f32_16x16x32_bf16 v[122:125], v[184:187], v[200:203], v[122:125]
	v_mfma_f32_16x16x32_bf16 v[114:117], v[192:195], v[200:203], v[114:117]
	v_mfma_f32_16x16x32_bf16 v[106:109], v[184:187], v[208:211], v[106:109]
	v_mfma_f32_16x16x32_bf16 v[98:101], v[192:195], v[208:211], v[98:101]
	v_mfma_f32_16x16x32_bf16 v[90:93], v[184:187], v[224:227], v[90:93]
	v_mfma_f32_16x16x32_bf16 v[82:85], v[192:195], v[224:227], v[82:85]
	v_mfma_f32_16x16x32_bf16 v[74:77], v[184:187], v[232:235], v[74:77]
	v_mfma_f32_16x16x32_bf16 v[66:69], v[192:195], v[232:235], v[66:69]
	s_setprio 0
	s_barrier
	s_add_i32 s34, s34, s74
	v_lshl_add_u64 v[158:159], s[42:43], 0, v[134:135]
	s_mov_b32 m0, s34
	ds_read_b128 v[196:199], v175 offset:16384
	ds_read_b128 v[200:203], v175 offset:17408
	ds_read_b128 v[204:207], v175 offset:18432
	ds_read_b128 v[208:211], v175 offset:19456
	ds_read_b128 v[220:223], v175 offset:20480
	ds_read_b128 v[224:227], v175 offset:21504
	ds_read_b128 v[228:231], v175 offset:22528
	ds_read_b128 v[232:235], v175 offset:23552
	global_load_lds_dwordx4 v[158:159], off
	s_add_i32 m0, s34, 0x2000
	s_add_u32 s34, s42, 0x40000
	v_lshl_add_u64 v[160:161], s[42:43], 0, v[130:131]
	s_addc_u32 s35, s43, 0
	s_add_i32 s41, s41, s74
	global_load_lds_dwordx4 v[160:161], off
	v_lshl_add_u64 v[162:163], s[34:35], 0, v[134:135]
	s_mov_b32 m0, s41
	v_lshl_add_u64 v[212:213], s[2:3], 0, v[132:133]
	global_load_lds_dwordx4 v[162:163], off
	v_lshl_add_u64 v[162:163], s[34:35], 0, v[130:131]
	s_add_i32 m0, s41, 0x2000
	s_nop 0
	global_load_lds_dwordx4 v[162:163], off
	v_lshl_add_u64 v[162:163], s[2:3], 0, v[136:137]
	s_mov_b32 m0, s75
	s_nop 0
	global_load_lds_dwordx4 v[162:163], off
	s_mov_b32 m0, s76
	s_nop 0
	global_load_lds_dwordx4 v[212:213], off
	s_waitcnt vmcnt(8)
	s_waitcnt lgkmcnt(0)
	s_barrier
	s_setprio 1
	v_mfma_f32_16x16x32_bf16 v[62:65], v[142:145], v[196:199], v[62:65]
	v_mfma_f32_16x16x32_bf16 v[54:57], v[150:153], v[196:199], v[54:57]
	v_mfma_f32_16x16x32_bf16 v[46:49], v[142:145], v[204:207], v[46:49]
	v_mfma_f32_16x16x32_bf16 v[38:41], v[150:153], v[204:207], v[38:41]
	v_mfma_f32_16x16x32_bf16 v[28:31], v[142:145], v[220:223], v[28:31]
	v_mfma_f32_16x16x32_bf16 v[20:23], v[150:153], v[220:223], v[20:23]
	v_mfma_f32_16x16x32_bf16 v[12:15], v[142:145], v[228:231], v[12:15]
	v_mfma_f32_16x16x32_bf16 v[4:7], v[150:153], v[228:231], v[4:7]
	v_mfma_f32_16x16x32_bf16 v[62:65], v[146:149], v[200:203], v[62:65]
	v_mfma_f32_16x16x32_bf16 v[54:57], v[176:179], v[200:203], v[54:57]
	v_mfma_f32_16x16x32_bf16 v[46:49], v[146:149], v[208:211], v[46:49]
	v_mfma_f32_16x16x32_bf16 v[38:41], v[176:179], v[208:211], v[38:41]
	v_mfma_f32_16x16x32_bf16 v[28:31], v[146:149], v[224:227], v[28:31]
	v_mfma_f32_16x16x32_bf16 v[20:23], v[176:179], v[224:227], v[20:23]
	v_mfma_f32_16x16x32_bf16 v[12:15], v[146:149], v[232:235], v[12:15]
	v_mfma_f32_16x16x32_bf16 v[4:7], v[176:179], v[232:235], v[4:7]
	v_mfma_f32_16x16x32_bf16 v[58:61], v[180:183], v[196:199], v[58:61]
	v_mfma_f32_16x16x32_bf16 v[50:53], v[188:191], v[196:199], v[50:53]
	v_mfma_f32_16x16x32_bf16 v[42:45], v[180:183], v[204:207], v[42:45]
	v_mfma_f32_16x16x32_bf16 v[34:37], v[188:191], v[204:207], v[34:37]
	v_mfma_f32_16x16x32_bf16 v[24:27], v[180:183], v[220:223], v[24:27]
	v_mfma_f32_16x16x32_bf16 v[16:19], v[188:191], v[220:223], v[16:19]
	v_mfma_f32_16x16x32_bf16 v[8:11], v[180:183], v[228:231], v[8:11]
	v_mfma_f32_16x16x32_bf16 v[0:3], v[188:191], v[228:231], v[0:3]
	v_mfma_f32_16x16x32_bf16 v[58:61], v[184:187], v[200:203], v[58:61]
	v_mfma_f32_16x16x32_bf16 v[50:53], v[192:195], v[200:203], v[50:53]
	v_mfma_f32_16x16x32_bf16 v[42:45], v[184:187], v[208:211], v[42:45]
	v_mfma_f32_16x16x32_bf16 v[34:37], v[192:195], v[208:211], v[34:37]
	v_mfma_f32_16x16x32_bf16 v[24:27], v[184:187], v[224:227], v[24:27]
	v_mfma_f32_16x16x32_bf16 v[16:19], v[192:195], v[224:227], v[16:19]
	v_mfma_f32_16x16x32_bf16 v[8:11], v[184:187], v[232:235], v[8:11]
	v_mfma_f32_16x16x32_bf16 v[0:3], v[192:195], v[232:235], v[0:3]
	s_setprio 0
	s_barrier
	s_add_i32 s34, 0, 0x18000
	s_add_i32 s35, 0, 0x1c000
	v_add_u32_e32 v176, s34, v165
	v_add_u32_e32 v192, s35, v165
	ds_read_b128 v[142:145], v176
	ds_read_b128 v[146:149], v176 offset:1024
	ds_read_b128 v[150:153], v176 offset:2048
	ds_read_b128 v[176:179], v176 offset:3072
	ds_read_b128 v[180:183], v192
	ds_read_b128 v[184:187], v192 offset:1024
	ds_read_b128 v[188:191], v192 offset:2048
	ds_read_b128 v[192:195], v192 offset:3072
	s_add_u32 s2, s2, 0x40000
	s_addc_u32 s3, s3, 0
	s_mov_b32 m0, s77
	v_lshl_add_u64 v[236:237], s[2:3], 0, v[136:137]
	ds_read_b128 v[196:199], v175 offset:32768
	ds_read_b128 v[200:203], v175 offset:33792
	ds_read_b128 v[204:207], v175 offset:34816
	ds_read_b128 v[208:211], v175 offset:35840
	ds_read_b128 v[220:223], v175 offset:36864
	ds_read_b128 v[224:227], v175 offset:37888
	ds_read_b128 v[228:231], v175 offset:38912
	ds_read_b128 v[232:235], v175 offset:39936
	global_load_lds_dwordx4 v[236:237], off
	v_lshl_add_u64 v[236:237], s[2:3], 0, v[132:133]
	s_mov_b32 m0, s78
	s_nop 0
	global_load_lds_dwordx4 v[236:237], off
	s_waitcnt vmcnt(8)
	s_waitcnt lgkmcnt(0)
	s_barrier
	s_setprio 1
	v_mfma_f32_16x16x32_bf16 v[126:129], v[142:145], v[196:199], v[126:129]
	v_mfma_f32_16x16x32_bf16 v[118:121], v[150:153], v[196:199], v[118:121]
	v_mfma_f32_16x16x32_bf16 v[110:113], v[142:145], v[204:207], v[110:113]
	v_mfma_f32_16x16x32_bf16 v[102:105], v[150:153], v[204:207], v[102:105]
	v_mfma_f32_16x16x32_bf16 v[94:97], v[142:145], v[220:223], v[94:97]
	v_mfma_f32_16x16x32_bf16 v[86:89], v[150:153], v[220:223], v[86:89]
	v_mfma_f32_16x16x32_bf16 v[78:81], v[142:145], v[228:231], v[78:81]
	v_mfma_f32_16x16x32_bf16 v[70:73], v[150:153], v[228:231], v[70:73]
	v_mfma_f32_16x16x32_bf16 v[126:129], v[146:149], v[200:203], v[126:129]
	v_mfma_f32_16x16x32_bf16 v[118:121], v[176:179], v[200:203], v[118:121]
	v_mfma_f32_16x16x32_bf16 v[110:113], v[146:149], v[208:211], v[110:113]
	v_mfma_f32_16x16x32_bf16 v[102:105], v[176:179], v[208:211], v[102:105]
	v_mfma_f32_16x16x32_bf16 v[94:97], v[146:149], v[224:227], v[94:97]
	v_mfma_f32_16x16x32_bf16 v[86:89], v[176:179], v[224:227], v[86:89]
	v_mfma_f32_16x16x32_bf16 v[78:81], v[146:149], v[232:235], v[78:81]
	v_mfma_f32_16x16x32_bf16 v[70:73], v[176:179], v[232:235], v[70:73]
	v_mfma_f32_16x16x32_bf16 v[122:125], v[180:183], v[196:199], v[122:125]
	v_mfma_f32_16x16x32_bf16 v[114:117], v[188:191], v[196:199], v[114:117]
	v_mfma_f32_16x16x32_bf16 v[106:109], v[180:183], v[204:207], v[106:109]
	v_mfma_f32_16x16x32_bf16 v[98:101], v[188:191], v[204:207], v[98:101]
	v_mfma_f32_16x16x32_bf16 v[90:93], v[180:183], v[220:223], v[90:93]
	v_mfma_f32_16x16x32_bf16 v[82:85], v[188:191], v[220:223], v[82:85]
	v_mfma_f32_16x16x32_bf16 v[74:77], v[180:183], v[228:231], v[74:77]
	v_mfma_f32_16x16x32_bf16 v[66:69], v[188:191], v[228:231], v[66:69]
	v_mfma_f32_16x16x32_bf16 v[122:125], v[184:187], v[200:203], v[122:125]
	v_mfma_f32_16x16x32_bf16 v[114:117], v[192:195], v[200:203], v[114:117]
	v_mfma_f32_16x16x32_bf16 v[106:109], v[184:187], v[208:211], v[106:109]
	v_mfma_f32_16x16x32_bf16 v[98:101], v[192:195], v[208:211], v[98:101]
	v_mfma_f32_16x16x32_bf16 v[90:93], v[184:187], v[224:227], v[90:93]
	v_mfma_f32_16x16x32_bf16 v[82:85], v[192:195], v[224:227], v[82:85]
	v_mfma_f32_16x16x32_bf16 v[74:77], v[184:187], v[232:235], v[74:77]
	v_mfma_f32_16x16x32_bf16 v[66:69], v[192:195], v[232:235], v[66:69]
	s_setprio 0
	s_barrier
	s_add_i32 s2, s34, s74
	v_lshl_add_u64 v[158:159], v[158:159], 0, s[24:25]
	s_mov_b32 m0, s2
	ds_read_b128 v[196:199], v175 offset:49152
	ds_read_b128 v[200:203], v175 offset:50176
	ds_read_b128 v[204:207], v175 offset:51200
	ds_read_b128 v[208:211], v175 offset:52224
	ds_read_b128 v[220:223], v175 offset:53248
	ds_read_b128 v[224:227], v175 offset:54272
	ds_read_b128 v[228:231], v175 offset:55296
	ds_read_b128 v[232:235], v175 offset:56320
	global_load_lds_dwordx4 v[158:159], off
	s_add_i32 m0, s2, 0x2000
	s_add_u32 s2, s42, 0x40080
	v_lshl_add_u64 v[158:159], v[160:161], 0, s[24:25]
	s_addc_u32 s3, s43, 0
	s_add_i32 s34, s35, s74
	global_load_lds_dwordx4 v[158:159], off
	v_lshl_add_u64 v[158:159], s[2:3], 0, v[134:135]
	s_mov_b32 m0, s34
	s_nop 0
	global_load_lds_dwordx4 v[158:159], off
	v_lshl_add_u64 v[158:159], s[2:3], 0, v[130:131]
	s_add_i32 m0, s34, 0x2000
	s_nop 0
	global_load_lds_dwordx4 v[158:159], off
	v_lshl_add_u64 v[158:159], v[162:163], 0, s[24:25]
	s_mov_b32 m0, s8
	s_nop 0
	global_load_lds_dwordx4 v[158:159], off
	v_lshl_add_u64 v[158:159], v[212:213], 0, s[24:25]
	s_mov_b32 m0, s11
	s_nop 0
	global_load_lds_dwordx4 v[158:159], off
	s_waitcnt vmcnt(8)
	s_waitcnt lgkmcnt(0)
	s_barrier
	s_setprio 1
	v_mfma_f32_16x16x32_bf16 v[62:65], v[142:145], v[196:199], v[62:65]
	v_mfma_f32_16x16x32_bf16 v[54:57], v[150:153], v[196:199], v[54:57]
	v_mfma_f32_16x16x32_bf16 v[46:49], v[142:145], v[204:207], v[46:49]
	v_mfma_f32_16x16x32_bf16 v[38:41], v[150:153], v[204:207], v[38:41]
	v_mfma_f32_16x16x32_bf16 v[28:31], v[142:145], v[220:223], v[28:31]
	v_mfma_f32_16x16x32_bf16 v[20:23], v[150:153], v[220:223], v[20:23]
	v_mfma_f32_16x16x32_bf16 v[12:15], v[142:145], v[228:231], v[12:15]
	v_mfma_f32_16x16x32_bf16 v[4:7], v[150:153], v[228:231], v[4:7]
	v_mfma_f32_16x16x32_bf16 v[62:65], v[146:149], v[200:203], v[62:65]
	v_mfma_f32_16x16x32_bf16 v[54:57], v[176:179], v[200:203], v[54:57]
	v_mfma_f32_16x16x32_bf16 v[46:49], v[146:149], v[208:211], v[46:49]
	v_mfma_f32_16x16x32_bf16 v[38:41], v[176:179], v[208:211], v[38:41]
	v_mfma_f32_16x16x32_bf16 v[28:31], v[146:149], v[224:227], v[28:31]
	v_mfma_f32_16x16x32_bf16 v[20:23], v[176:179], v[224:227], v[20:23]
	v_mfma_f32_16x16x32_bf16 v[12:15], v[146:149], v[232:235], v[12:15]
	v_mfma_f32_16x16x32_bf16 v[4:7], v[176:179], v[232:235], v[4:7]
	v_mfma_f32_16x16x32_bf16 v[58:61], v[180:183], v[196:199], v[58:61]
	v_mfma_f32_16x16x32_bf16 v[50:53], v[188:191], v[196:199], v[50:53]
	v_mfma_f32_16x16x32_bf16 v[42:45], v[180:183], v[204:207], v[42:45]
	v_mfma_f32_16x16x32_bf16 v[34:37], v[188:191], v[204:207], v[34:37]
	v_mfma_f32_16x16x32_bf16 v[24:27], v[180:183], v[220:223], v[24:27]
	v_mfma_f32_16x16x32_bf16 v[16:19], v[188:191], v[220:223], v[16:19]
	v_mfma_f32_16x16x32_bf16 v[8:11], v[180:183], v[228:231], v[8:11]
	v_mfma_f32_16x16x32_bf16 v[0:3], v[188:191], v[228:231], v[0:3]
	v_mfma_f32_16x16x32_bf16 v[58:61], v[184:187], v[200:203], v[58:61]
	v_mfma_f32_16x16x32_bf16 v[50:53], v[192:195], v[200:203], v[50:53]
	v_mfma_f32_16x16x32_bf16 v[42:45], v[184:187], v[208:211], v[42:45]
	v_mfma_f32_16x16x32_bf16 v[34:37], v[192:195], v[208:211], v[34:37]
	v_mfma_f32_16x16x32_bf16 v[24:27], v[184:187], v[224:227], v[24:27]
	v_mfma_f32_16x16x32_bf16 v[16:19], v[192:195], v[224:227], v[16:19]
	v_mfma_f32_16x16x32_bf16 v[8:11], v[184:187], v[232:235], v[8:11]
	v_mfma_f32_16x16x32_bf16 v[0:3], v[192:195], v[232:235], v[0:3]
	s_setprio 0
	s_barrier
	s_add_i32 s31, s31, 2
	s_add_u32 s56, s56, 0x100
	s_addc_u32 s57, s57, 0
	s_add_u32 s29, s29, 0x100
	s_addc_u32 s30, s30, 0
	s_cmp_gt_u32 s31, 13
	s_cbranch_scc0 .LBB0_2536
	s_and_b64 vcc, exec, s[38:39]
	s_cbranch_vccz .LBB0_2539
	s_barrier

.LBB0_2557:
	s_add_u32 s2, s56, 0xfffc0080
	s_addc_u32 s3, s57, -1
	s_add_i32 s34, 0, 0x10000
	s_cmp_eq_u32 s31, 12
	s_cselect_b32 s3, s20, s3
	s_cselect_b32 s2, s21, s2
	v_add_u32_e32 v158, s34, v165
	s_cselect_b32 s59, s23, s30
	s_cselect_b32 s58, s28, s29
	s_add_i32 s43, 0, 0x14000
	ds_read_b128 v[142:145], v158
	ds_read_b128 v[146:149], v158 offset:1024
	ds_read_b128 v[150:153], v158 offset:2048
	ds_read_b128 v[176:179], v158 offset:3072
	v_add_u32_e32 v158, s43, v165
	ds_read_b128 v[180:183], v158
	ds_read_b128 v[184:187], v158 offset:1024
	ds_read_b128 v[188:191], v158 offset:2048
	ds_read_b128 v[192:195], v158 offset:3072
	v_lshl_add_u64 v[158:159], s[56:57], 0, v[138:139]
	s_add_i32 m0, s11, 0xc000
	ds_read_b128 v[196:199], v175
	ds_read_b128 v[200:203], v175 offset:1024
	ds_read_b128 v[204:207], v175 offset:2048
	ds_read_b128 v[208:211], v175 offset:3072
	ds_read_b128 v[220:223], v175 offset:4096
	ds_read_b128 v[224:227], v175 offset:5120
	ds_read_b128 v[228:231], v175 offset:6144
	ds_read_b128 v[232:235], v175 offset:7168
	global_load_lds_dwordx4 v[158:159], off
	v_lshl_add_u64 v[158:159], s[56:57], 0, v[140:141]
	s_add_i32 m0, s11, 0xe000
	s_nop 0
	global_load_lds_dwordx4 v[158:159], off
	s_waitcnt vmcnt(8)
	s_waitcnt lgkmcnt(0)
	s_barrier
	s_setprio 1
	v_mfma_f32_16x16x32_bf16 v[126:129], v[142:145], v[196:199], v[126:129]
	v_mfma_f32_16x16x32_bf16 v[118:121], v[150:153], v[196:199], v[118:121]
	v_mfma_f32_16x16x32_bf16 v[110:113], v[142:145], v[204:207], v[110:113]
	v_mfma_f32_16x16x32_bf16 v[102:105], v[150:153], v[204:207], v[102:105]
	v_mfma_f32_16x16x32_bf16 v[94:97], v[142:145], v[220:223], v[94:97]
	v_mfma_f32_16x16x32_bf16 v[86:89], v[150:153], v[220:223], v[86:89]
	v_mfma_f32_16x16x32_bf16 v[78:81], v[142:145], v[228:231], v[78:81]
	v_mfma_f32_16x16x32_bf16 v[70:73], v[150:153], v[228:231], v[70:73]
	v_mfma_f32_16x16x32_bf16 v[126:129], v[146:149], v[200:203], v[126:129]
	v_mfma_f32_16x16x32_bf16 v[118:121], v[176:179], v[200:203], v[118:121]
	v_mfma_f32_16x16x32_bf16 v[110:113], v[146:149], v[208:211], v[110:113]
	v_mfma_f32_16x16x32_bf16 v[102:105], v[176:179], v[208:211], v[102:105]
	v_mfma_f32_16x16x32_bf16 v[94:97], v[146:149], v[224:227], v[94:97]
	v_mfma_f32_16x16x32_bf16 v[86:89], v[176:179], v[224:227], v[86:89]
	v_mfma_f32_16x16x32_bf16 v[78:81], v[146:149], v[232:235], v[78:81]
	v_mfma_f32_16x16x32_bf16 v[70:73], v[176:179], v[232:235], v[70:73]
	v_mfma_f32_16x16x32_bf16 v[122:125], v[180:183], v[196:199], v[122:125]
	v_mfma_f32_16x16x32_bf16 v[114:117], v[188:191], v[196:199], v[114:117]
	v_mfma_f32_16x16x32_bf16 v[106:109], v[180:183], v[204:207], v[106:109]
	v_mfma_f32_16x16x32_bf16 v[98:101], v[188:191], v[204:207], v[98:101]
	v_mfma_f32_16x16x32_bf16 v[90:93], v[180:183], v[220:223], v[90:93]
	v_mfma_f32_16x16x32_bf16 v[82:85], v[188:191], v[220:223], v[82:85]
	v_mfma_f32_16x16x32_bf16 v[74:77], v[180:183], v[228:231], v[74:77]
	v_mfma_f32_16x16x32_bf16 v[66:69], v[188:191], v[228:231], v[66:69]
	v_mfma_f32_16x16x32_bf16 v[122:125], v[184:187], v[200:203], v[122:125]
	v_mfma_f32_16x16x32_bf16 v[114:117], v[192:195], v[200:203], v[114:117]
	v_mfma_f32_16x16x32_bf16 v[106:109], v[184:187], v[208:211], v[106:109]
	v_mfma_f32_16x16x32_bf16 v[98:101], v[192:195], v[208:211], v[98:101]
	v_mfma_f32_16x16x32_bf16 v[90:93], v[184:187], v[224:227], v[90:93]
	v_mfma_f32_16x16x32_bf16 v[82:85], v[192:195], v[224:227], v[82:85]
	v_mfma_f32_16x16x32_bf16 v[74:77], v[184:187], v[232:235], v[74:77]
	v_mfma_f32_16x16x32_bf16 v[66:69], v[192:195], v[232:235], v[66:69]
	s_setprio 0
	s_barrier
	s_add_i32 s34, s34, s8
	v_lshl_add_u64 v[158:159], s[58:59], 0, v[32:33]
	s_mov_b32 m0, s34
	ds_read_b128 v[196:199], v175 offset:16384
	ds_read_b128 v[200:203], v175 offset:17408
	ds_read_b128 v[204:207], v175 offset:18432
	ds_read_b128 v[208:211], v175 offset:19456
	ds_read_b128 v[220:223], v175 offset:20480
	ds_read_b128 v[224:227], v175 offset:21504
	ds_read_b128 v[228:231], v175 offset:22528
	ds_read_b128 v[232:235], v175 offset:23552
	global_load_lds_dwordx4 v[158:159], off
	s_add_i32 m0, s34, 0x2000
	s_add_u32 s34, s58, 0x40000
	v_lshl_add_u64 v[160:161], s[58:59], 0, v[130:131]
	s_addc_u32 s35, s59, 0
	s_add_i32 s43, s43, s8
	global_load_lds_dwordx4 v[160:161], off
	v_lshl_add_u64 v[162:163], s[34:35], 0, v[32:33]
	s_mov_b32 m0, s43
	v_lshl_add_u64 v[212:213], s[2:3], 0, v[132:133]
	global_load_lds_dwordx4 v[162:163], off
	v_lshl_add_u64 v[162:163], s[34:35], 0, v[130:131]
	s_add_i32 m0, s43, 0x2000
	s_nop 0
	global_load_lds_dwordx4 v[162:163], off
	v_lshl_add_u64 v[162:163], s[2:3], 0, v[134:135]
	s_mov_b32 m0, s11
	s_nop 0
	global_load_lds_dwordx4 v[162:163], off
	s_mov_b32 m0, s12
	s_nop 0
	global_load_lds_dwordx4 v[212:213], off
	s_waitcnt vmcnt(8)
	s_waitcnt lgkmcnt(0)
	s_barrier
	s_setprio 1
	v_mfma_f32_16x16x32_bf16 v[62:65], v[142:145], v[196:199], v[62:65]
	v_mfma_f32_16x16x32_bf16 v[54:57], v[150:153], v[196:199], v[54:57]
	v_mfma_f32_16x16x32_bf16 v[46:49], v[142:145], v[204:207], v[46:49]
	v_mfma_f32_16x16x32_bf16 v[38:41], v[150:153], v[204:207], v[38:41]
	v_mfma_f32_16x16x32_bf16 v[28:31], v[142:145], v[220:223], v[28:31]
	v_mfma_f32_16x16x32_bf16 v[20:23], v[150:153], v[220:223], v[20:23]
	v_mfma_f32_16x16x32_bf16 v[12:15], v[142:145], v[228:231], v[12:15]
	v_mfma_f32_16x16x32_bf16 v[4:7], v[150:153], v[228:231], v[4:7]
	v_mfma_f32_16x16x32_bf16 v[62:65], v[146:149], v[200:203], v[62:65]
	v_mfma_f32_16x16x32_bf16 v[54:57], v[176:179], v[200:203], v[54:57]
	v_mfma_f32_16x16x32_bf16 v[46:49], v[146:149], v[208:211], v[46:49]
	v_mfma_f32_16x16x32_bf16 v[38:41], v[176:179], v[208:211], v[38:41]
	v_mfma_f32_16x16x32_bf16 v[28:31], v[146:149], v[224:227], v[28:31]
	v_mfma_f32_16x16x32_bf16 v[20:23], v[176:179], v[224:227], v[20:23]
	v_mfma_f32_16x16x32_bf16 v[12:15], v[146:149], v[232:235], v[12:15]
	v_mfma_f32_16x16x32_bf16 v[4:7], v[176:179], v[232:235], v[4:7]
	v_mfma_f32_16x16x32_bf16 v[58:61], v[180:183], v[196:199], v[58:61]
	v_mfma_f32_16x16x32_bf16 v[50:53], v[188:191], v[196:199], v[50:53]
	v_mfma_f32_16x16x32_bf16 v[42:45], v[180:183], v[204:207], v[42:45]
	v_mfma_f32_16x16x32_bf16 v[34:37], v[188:191], v[204:207], v[34:37]
	v_mfma_f32_16x16x32_bf16 v[24:27], v[180:183], v[220:223], v[24:27]
	v_mfma_f32_16x16x32_bf16 v[16:19], v[188:191], v[220:223], v[16:19]
	v_mfma_f32_16x16x32_bf16 v[8:11], v[180:183], v[228:231], v[8:11]
	v_mfma_f32_16x16x32_bf16 v[0:3], v[188:191], v[228:231], v[0:3]
	v_mfma_f32_16x16x32_bf16 v[58:61], v[184:187], v[200:203], v[58:61]
	v_mfma_f32_16x16x32_bf16 v[50:53], v[192:195], v[200:203], v[50:53]
	v_mfma_f32_16x16x32_bf16 v[42:45], v[184:187], v[208:211], v[42:45]
	v_mfma_f32_16x16x32_bf16 v[34:37], v[192:195], v[208:211], v[34:37]
	v_mfma_f32_16x16x32_bf16 v[24:27], v[184:187], v[224:227], v[24:27]
	v_mfma_f32_16x16x32_bf16 v[16:19], v[192:195], v[224:227], v[16:19]
	v_mfma_f32_16x16x32_bf16 v[8:11], v[184:187], v[232:235], v[8:11]
	v_mfma_f32_16x16x32_bf16 v[0:3], v[192:195], v[232:235], v[0:3]
	s_setprio 0
	s_barrier
	s_add_i32 s34, 0, 0x18000
	s_add_i32 s35, 0, 0x1c000
	v_add_u32_e32 v176, s34, v165
	v_add_u32_e32 v192, s35, v165
	ds_read_b128 v[142:145], v176
	ds_read_b128 v[146:149], v176 offset:1024
	ds_read_b128 v[150:153], v176 offset:2048
	ds_read_b128 v[176:179], v176 offset:3072
	ds_read_b128 v[180:183], v192
	ds_read_b128 v[184:187], v192 offset:1024
	ds_read_b128 v[188:191], v192 offset:2048
	ds_read_b128 v[192:195], v192 offset:3072
	s_add_u32 s2, s2, 0x40000
	s_addc_u32 s3, s3, 0
	s_mov_b32 m0, s13
	v_lshl_add_u64 v[236:237], s[2:3], 0, v[134:135]
	ds_read_b128 v[196:199], v175 offset:32768
	ds_read_b128 v[200:203], v175 offset:33792
	ds_read_b128 v[204:207], v175 offset:34816
	ds_read_b128 v[208:211], v175 offset:35840
	ds_read_b128 v[220:223], v175 offset:36864
	ds_read_b128 v[224:227], v175 offset:37888
	ds_read_b128 v[228:231], v175 offset:38912
	ds_read_b128 v[232:235], v175 offset:39936
	global_load_lds_dwordx4 v[236:237], off
	v_lshl_add_u64 v[236:237], s[2:3], 0, v[132:133]
	s_mov_b32 m0, s14
	s_nop 0
	global_load_lds_dwordx4 v[236:237], off
	s_waitcnt vmcnt(8)
	s_waitcnt lgkmcnt(0)
	s_barrier
	s_setprio 1
	v_mfma_f32_16x16x32_bf16 v[126:129], v[142:145], v[196:199], v[126:129]
	v_mfma_f32_16x16x32_bf16 v[118:121], v[150:153], v[196:199], v[118:121]
	v_mfma_f32_16x16x32_bf16 v[110:113], v[142:145], v[204:207], v[110:113]
	v_mfma_f32_16x16x32_bf16 v[102:105], v[150:153], v[204:207], v[102:105]
	v_mfma_f32_16x16x32_bf16 v[94:97], v[142:145], v[220:223], v[94:97]
	v_mfma_f32_16x16x32_bf16 v[86:89], v[150:153], v[220:223], v[86:89]
	v_mfma_f32_16x16x32_bf16 v[78:81], v[142:145], v[228:231], v[78:81]
	v_mfma_f32_16x16x32_bf16 v[70:73], v[150:153], v[228:231], v[70:73]
	v_mfma_f32_16x16x32_bf16 v[126:129], v[146:149], v[200:203], v[126:129]
	v_mfma_f32_16x16x32_bf16 v[118:121], v[176:179], v[200:203], v[118:121]
	v_mfma_f32_16x16x32_bf16 v[110:113], v[146:149], v[208:211], v[110:113]
	v_mfma_f32_16x16x32_bf16 v[102:105], v[176:179], v[208:211], v[102:105]
	v_mfma_f32_16x16x32_bf16 v[94:97], v[146:149], v[224:227], v[94:97]
	v_mfma_f32_16x16x32_bf16 v[86:89], v[176:179], v[224:227], v[86:89]
	v_mfma_f32_16x16x32_bf16 v[78:81], v[146:149], v[232:235], v[78:81]
	v_mfma_f32_16x16x32_bf16 v[70:73], v[176:179], v[232:235], v[70:73]
	v_mfma_f32_16x16x32_bf16 v[122:125], v[180:183], v[196:199], v[122:125]
	v_mfma_f32_16x16x32_bf16 v[114:117], v[188:191], v[196:199], v[114:117]
	v_mfma_f32_16x16x32_bf16 v[106:109], v[180:183], v[204:207], v[106:109]
	v_mfma_f32_16x16x32_bf16 v[98:101], v[188:191], v[204:207], v[98:101]
	v_mfma_f32_16x16x32_bf16 v[90:93], v[180:183], v[220:223], v[90:93]
	v_mfma_f32_16x16x32_bf16 v[82:85], v[188:191], v[220:223], v[82:85]
	v_mfma_f32_16x16x32_bf16 v[74:77], v[180:183], v[228:231], v[74:77]
	v_mfma_f32_16x16x32_bf16 v[66:69], v[188:191], v[228:231], v[66:69]
	v_mfma_f32_16x16x32_bf16 v[122:125], v[184:187], v[200:203], v[122:125]
	v_mfma_f32_16x16x32_bf16 v[114:117], v[192:195], v[200:203], v[114:117]
	v_mfma_f32_16x16x32_bf16 v[106:109], v[184:187], v[208:211], v[106:109]
	v_mfma_f32_16x16x32_bf16 v[98:101], v[192:195], v[208:211], v[98:101]
	v_mfma_f32_16x16x32_bf16 v[90:93], v[184:187], v[224:227], v[90:93]
	v_mfma_f32_16x16x32_bf16 v[82:85], v[192:195], v[224:227], v[82:85]
	v_mfma_f32_16x16x32_bf16 v[74:77], v[184:187], v[232:235], v[74:77]
	v_mfma_f32_16x16x32_bf16 v[66:69], v[192:195], v[232:235], v[66:69]
	s_setprio 0
	s_barrier
	s_add_i32 s2, s34, s8
	v_lshl_add_u64 v[158:159], v[158:159], 0, s[24:25]
	s_mov_b32 m0, s2
	ds_read_b128 v[196:199], v175 offset:49152
	ds_read_b128 v[200:203], v175 offset:50176
	ds_read_b128 v[204:207], v175 offset:51200
	ds_read_b128 v[208:211], v175 offset:52224
	ds_read_b128 v[220:223], v175 offset:53248
	ds_read_b128 v[224:227], v175 offset:54272
	ds_read_b128 v[228:231], v175 offset:55296
	ds_read_b128 v[232:235], v175 offset:56320
	global_load_lds_dwordx4 v[158:159], off
	s_add_i32 m0, s2, 0x2000
	s_add_u32 s2, s58, 0x40080
	v_lshl_add_u64 v[158:159], v[160:161], 0, s[24:25]
	s_addc_u32 s3, s59, 0
	s_add_i32 s34, s35, s8
	global_load_lds_dwordx4 v[158:159], off
	v_lshl_add_u64 v[158:159], s[2:3], 0, v[32:33]
	s_mov_b32 m0, s34
	s_nop 0
	global_load_lds_dwordx4 v[158:159], off
	v_lshl_add_u64 v[158:159], s[2:3], 0, v[130:131]
	s_add_i32 m0, s34, 0x2000
	s_nop 0
	global_load_lds_dwordx4 v[158:159], off
	v_lshl_add_u64 v[158:159], v[162:163], 0, s[24:25]
	s_mov_b32 m0, s15
	s_nop 0
	global_load_lds_dwordx4 v[158:159], off
	v_lshl_add_u64 v[158:159], v[212:213], 0, s[24:25]
	s_mov_b32 m0, s17
	s_nop 0
	global_load_lds_dwordx4 v[158:159], off
	s_waitcnt vmcnt(8)
	s_waitcnt lgkmcnt(0)
	s_barrier
	s_setprio 1
	v_mfma_f32_16x16x32_bf16 v[62:65], v[142:145], v[196:199], v[62:65]
	v_mfma_f32_16x16x32_bf16 v[54:57], v[150:153], v[196:199], v[54:57]
	v_mfma_f32_16x16x32_bf16 v[46:49], v[142:145], v[204:207], v[46:49]
	v_mfma_f32_16x16x32_bf16 v[38:41], v[150:153], v[204:207], v[38:41]
	v_mfma_f32_16x16x32_bf16 v[28:31], v[142:145], v[220:223], v[28:31]
	v_mfma_f32_16x16x32_bf16 v[20:23], v[150:153], v[220:223], v[20:23]
	v_mfma_f32_16x16x32_bf16 v[12:15], v[142:145], v[228:231], v[12:15]
	v_mfma_f32_16x16x32_bf16 v[4:7], v[150:153], v[228:231], v[4:7]
	v_mfma_f32_16x16x32_bf16 v[62:65], v[146:149], v[200:203], v[62:65]
	v_mfma_f32_16x16x32_bf16 v[54:57], v[176:179], v[200:203], v[54:57]
	v_mfma_f32_16x16x32_bf16 v[46:49], v[146:149], v[208:211], v[46:49]
	v_mfma_f32_16x16x32_bf16 v[38:41], v[176:179], v[208:211], v[38:41]
	v_mfma_f32_16x16x32_bf16 v[28:31], v[146:149], v[224:227], v[28:31]
	v_mfma_f32_16x16x32_bf16 v[20:23], v[176:179], v[224:227], v[20:23]
	v_mfma_f32_16x16x32_bf16 v[12:15], v[146:149], v[232:235], v[12:15]
	v_mfma_f32_16x16x32_bf16 v[4:7], v[176:179], v[232:235], v[4:7]
	v_mfma_f32_16x16x32_bf16 v[58:61], v[180:183], v[196:199], v[58:61]
	v_mfma_f32_16x16x32_bf16 v[50:53], v[188:191], v[196:199], v[50:53]
	v_mfma_f32_16x16x32_bf16 v[42:45], v[180:183], v[204:207], v[42:45]
	v_mfma_f32_16x16x32_bf16 v[34:37], v[188:191], v[204:207], v[34:37]
	v_mfma_f32_16x16x32_bf16 v[24:27], v[180:183], v[220:223], v[24:27]
	v_mfma_f32_16x16x32_bf16 v[16:19], v[188:191], v[220:223], v[16:19]
	v_mfma_f32_16x16x32_bf16 v[8:11], v[180:183], v[228:231], v[8:11]
	v_mfma_f32_16x16x32_bf16 v[0:3], v[188:191], v[228:231], v[0:3]
	v_mfma_f32_16x16x32_bf16 v[58:61], v[184:187], v[200:203], v[58:61]
	v_mfma_f32_16x16x32_bf16 v[50:53], v[192:195], v[200:203], v[50:53]
	v_mfma_f32_16x16x32_bf16 v[42:45], v[184:187], v[208:211], v[42:45]
	v_mfma_f32_16x16x32_bf16 v[34:37], v[192:195], v[208:211], v[34:37]
	v_mfma_f32_16x16x32_bf16 v[24:27], v[184:187], v[224:227], v[24:27]
	v_mfma_f32_16x16x32_bf16 v[16:19], v[192:195], v[224:227], v[16:19]
	v_mfma_f32_16x16x32_bf16 v[8:11], v[184:187], v[232:235], v[8:11]
	v_mfma_f32_16x16x32_bf16 v[0:3], v[192:195], v[232:235], v[0:3]
	s_setprio 0
	s_barrier
	s_add_i32 s31, s31, 2
	s_add_u32 s56, s56, 0x100
	s_addc_u32 s57, s57, 0
	s_add_u32 s29, s29, 0x100
	s_addc_u32 s30, s30, 0
	s_cmp_gt_u32 s31, 13
	s_cbranch_scc0 .LBB0_2557
	s_and_b64 vcc, exec, s[40:41]
	s_cbranch_vccz .LBB0_2560
	s_barrier

.LBB0_2574:
	s_add_u32 s2, s21, s6
	s_addc_u32 s3, s23, s7
	s_add_u32 s2, s2, 0x9d00100
	s_addc_u32 s3, s3, 0
	s_add_u32 s31, s28, s6
	s_addc_u32 s35, s29, s7
	s_add_i32 s37, 0, 0x10000
	s_cmpk_eq_i32 s6, 0x700
	s_cselect_b32 s43, s41, s3
	s_cselect_b32 s42, s40, s2
	v_add_u32_e32 v81, s37, v79
	s_cselect_b32 s3, s39, s35
	s_cselect_b32 s2, s38, s31
	s_add_i32 s31, 0, 0x14000
	ds_read_b128 v[82:85], v81
	ds_read_b128 v[86:89], v81 offset:1024
	ds_read_b128 v[90:93], v81 offset:2048
	ds_read_b128 v[94:97], v81 offset:3072
	v_add_u32_e32 v81, s31, v79
	ds_read_b128 v[98:101], v81
	ds_read_b128 v[102:105], v81 offset:1024
	ds_read_b128 v[106:109], v81 offset:2048
	ds_read_b128 v[110:113], v81 offset:3072
	v_lshl_add_u64 v[146:147], v[72:73], 0, s[6:7]
	s_add_i32 m0, s13, 0xc000
	ds_read_b128 v[114:117], v80
	ds_read_b128 v[118:121], v80 offset:1024
	ds_read_b128 v[122:125], v80 offset:2048
	ds_read_b128 v[126:129], v80 offset:3072
	ds_read_b128 v[130:133], v80 offset:4096
	ds_read_b128 v[134:137], v80 offset:5120
	ds_read_b128 v[138:141], v80 offset:6144
	ds_read_b128 v[142:145], v80 offset:7168
	global_load_lds_dwordx4 v[146:147], off
	v_lshl_add_u64 v[146:147], v[74:75], 0, s[6:7]
	s_add_i32 m0, s13, 0xe000
	s_nop 0
	global_load_lds_dwordx4 v[146:147], off
	s_waitcnt vmcnt(8)
	s_waitcnt lgkmcnt(0)
	s_barrier
	s_setprio 1
	v_mfma_f32_16x16x32_bf16 v[62:65], v[82:85], v[114:117], v[62:65]
	v_mfma_f32_16x16x32_bf16 v[54:57], v[90:93], v[114:117], v[54:57]
	v_mfma_f32_16x16x32_bf16 v[46:49], v[82:85], v[122:125], v[46:49]
	v_mfma_f32_16x16x32_bf16 v[38:41], v[90:93], v[122:125], v[38:41]
	v_mfma_f32_16x16x32_bf16 v[28:31], v[82:85], v[130:133], v[28:31]
	v_mfma_f32_16x16x32_bf16 v[20:23], v[90:93], v[130:133], v[20:23]
	v_mfma_f32_16x16x32_bf16 v[12:15], v[82:85], v[138:141], v[12:15]
	v_mfma_f32_16x16x32_bf16 v[4:7], v[90:93], v[138:141], v[4:7]
	v_mfma_f32_16x16x32_bf16 v[62:65], v[86:89], v[118:121], v[62:65]
	v_mfma_f32_16x16x32_bf16 v[54:57], v[94:97], v[118:121], v[54:57]
	v_mfma_f32_16x16x32_bf16 v[46:49], v[86:89], v[126:129], v[46:49]
	v_mfma_f32_16x16x32_bf16 v[38:41], v[94:97], v[126:129], v[38:41]
	v_mfma_f32_16x16x32_bf16 v[28:31], v[86:89], v[134:137], v[28:31]
	v_mfma_f32_16x16x32_bf16 v[20:23], v[94:97], v[134:137], v[20:23]
	v_mfma_f32_16x16x32_bf16 v[12:15], v[86:89], v[142:145], v[12:15]
	v_mfma_f32_16x16x32_bf16 v[4:7], v[94:97], v[142:145], v[4:7]
	v_mfma_f32_16x16x32_bf16 v[58:61], v[98:101], v[114:117], v[58:61]
	v_mfma_f32_16x16x32_bf16 v[50:53], v[106:109], v[114:117], v[50:53]
	v_mfma_f32_16x16x32_bf16 v[42:45], v[98:101], v[122:125], v[42:45]
	v_mfma_f32_16x16x32_bf16 v[34:37], v[106:109], v[122:125], v[34:37]
	v_mfma_f32_16x16x32_bf16 v[24:27], v[98:101], v[130:133], v[24:27]
	v_mfma_f32_16x16x32_bf16 v[16:19], v[106:109], v[130:133], v[16:19]
	v_mfma_f32_16x16x32_bf16 v[8:11], v[98:101], v[138:141], v[8:11]
	v_mfma_f32_16x16x32_bf16 v[0:3], v[106:109], v[138:141], v[0:3]
	v_mfma_f32_16x16x32_bf16 v[58:61], v[102:105], v[118:121], v[58:61]
	v_mfma_f32_16x16x32_bf16 v[50:53], v[110:113], v[118:121], v[50:53]
	v_mfma_f32_16x16x32_bf16 v[42:45], v[102:105], v[126:129], v[42:45]
	v_mfma_f32_16x16x32_bf16 v[34:37], v[110:113], v[126:129], v[34:37]
	v_mfma_f32_16x16x32_bf16 v[24:27], v[102:105], v[134:137], v[24:27]
	v_mfma_f32_16x16x32_bf16 v[16:19], v[110:113], v[134:137], v[16:19]
	v_mfma_f32_16x16x32_bf16 v[8:11], v[102:105], v[142:145], v[8:11]
	v_mfma_f32_16x16x32_bf16 v[0:3], v[110:113], v[142:145], v[0:3]
	s_setprio 0
	s_barrier
	s_add_i32 s35, s37, s12
	v_lshl_add_u64 v[146:147], s[2:3], 0, v[32:33]
	s_mov_b32 m0, s35
	v_lshl_add_u64 v[148:149], s[2:3], 0, v[66:67]
	global_load_lds_dwordx4 v[146:147], off
	s_add_i32 m0, s35, 0x2000
	s_add_u32 s44, s2, 0x40000
	s_addc_u32 s45, s3, 0
	s_add_i32 s31, s31, s12
	global_load_lds_dwordx4 v[148:149], off
	v_lshl_add_u64 v[82:83], s[44:45], 0, v[32:33]
	s_mov_b32 m0, s31
	v_lshl_add_u64 v[150:151], s[42:43], 0, v[70:71]
	global_load_lds_dwordx4 v[82:83], off
	v_lshl_add_u64 v[82:83], s[44:45], 0, v[66:67]
	s_add_i32 m0, s31, 0x2000
	v_lshl_add_u64 v[152:153], s[42:43], 0, v[68:69]
	global_load_lds_dwordx4 v[82:83], off
	s_mov_b32 m0, s13
	s_nop 0
	global_load_lds_dwordx4 v[150:151], off
	s_mov_b32 m0, s14
	s_nop 0
	global_load_lds_dwordx4 v[152:153], off
	s_waitcnt vmcnt(8)
	s_waitcnt lgkmcnt(0)
	s_barrier
	s_barrier
	s_add_i32 s31, 0, 0x18000
	v_add_u32_e32 v81, s31, v79
	s_add_i32 s35, 0, 0x1c000
	ds_read_b128 v[82:85], v81
	ds_read_b128 v[86:89], v81 offset:1024
	ds_read_b128 v[90:93], v81 offset:2048
	ds_read_b128 v[94:97], v81 offset:3072
	v_add_u32_e32 v81, s35, v79
	ds_read_b128 v[98:101], v81
	ds_read_b128 v[102:105], v81 offset:1024
	ds_read_b128 v[106:109], v81 offset:2048
	ds_read_b128 v[110:113], v81 offset:3072
	s_add_u32 s42, s42, 0x40000
	s_addc_u32 s43, s43, 0
	s_mov_b32 m0, s15
	v_lshl_add_u64 v[158:159], s[42:43], 0, v[70:71]
	ds_read_b128 v[114:117], v80 offset:32768
	ds_read_b128 v[118:121], v80 offset:33792
	ds_read_b128 v[122:125], v80 offset:34816
	ds_read_b128 v[126:129], v80 offset:35840
	ds_read_b128 v[130:133], v80 offset:36864
	ds_read_b128 v[134:137], v80 offset:37888
	ds_read_b128 v[138:141], v80 offset:38912
	ds_read_b128 v[142:145], v80 offset:39936
	global_load_lds_dwordx4 v[158:159], off
	v_lshl_add_u64 v[158:159], s[42:43], 0, v[68:69]
	s_mov_b32 m0, s17
	s_nop 0
	global_load_lds_dwordx4 v[158:159], off
	s_waitcnt vmcnt(8)
	s_waitcnt lgkmcnt(0)
	s_barrier
	s_setprio 1
	v_mfma_f32_16x16x32_bf16 v[62:65], v[82:85], v[114:117], v[62:65]
	v_mfma_f32_16x16x32_bf16 v[54:57], v[90:93], v[114:117], v[54:57]
	v_mfma_f32_16x16x32_bf16 v[46:49], v[82:85], v[122:125], v[46:49]
	v_mfma_f32_16x16x32_bf16 v[38:41], v[90:93], v[122:125], v[38:41]
	v_mfma_f32_16x16x32_bf16 v[28:31], v[82:85], v[130:133], v[28:31]
	v_mfma_f32_16x16x32_bf16 v[20:23], v[90:93], v[130:133], v[20:23]
	v_mfma_f32_16x16x32_bf16 v[12:15], v[82:85], v[138:141], v[12:15]
	v_mfma_f32_16x16x32_bf16 v[4:7], v[90:93], v[138:141], v[4:7]
	v_mfma_f32_16x16x32_bf16 v[62:65], v[86:89], v[118:121], v[62:65]
	v_mfma_f32_16x16x32_bf16 v[54:57], v[94:97], v[118:121], v[54:57]
	v_mfma_f32_16x16x32_bf16 v[46:49], v[86:89], v[126:129], v[46:49]
	v_mfma_f32_16x16x32_bf16 v[38:41], v[94:97], v[126:129], v[38:41]
	v_mfma_f32_16x16x32_bf16 v[28:31], v[86:89], v[134:137], v[28:31]
	v_mfma_f32_16x16x32_bf16 v[20:23], v[94:97], v[134:137], v[20:23]
	v_mfma_f32_16x16x32_bf16 v[12:15], v[86:89], v[142:145], v[12:15]
	v_mfma_f32_16x16x32_bf16 v[4:7], v[94:97], v[142:145], v[4:7]
	v_mfma_f32_16x16x32_bf16 v[58:61], v[98:101], v[114:117], v[58:61]
	v_mfma_f32_16x16x32_bf16 v[50:53], v[106:109], v[114:117], v[50:53]
	v_mfma_f32_16x16x32_bf16 v[42:45], v[98:101], v[122:125], v[42:45]
	v_mfma_f32_16x16x32_bf16 v[34:37], v[106:109], v[122:125], v[34:37]
	v_mfma_f32_16x16x32_bf16 v[24:27], v[98:101], v[130:133], v[24:27]
	v_mfma_f32_16x16x32_bf16 v[16:19], v[106:109], v[130:133], v[16:19]
	v_mfma_f32_16x16x32_bf16 v[8:11], v[98:101], v[138:141], v[8:11]
	v_mfma_f32_16x16x32_bf16 v[0:3], v[106:109], v[138:141], v[0:3]
	v_mfma_f32_16x16x32_bf16 v[58:61], v[102:105], v[118:121], v[58:61]
	v_mfma_f32_16x16x32_bf16 v[50:53], v[110:113], v[118:121], v[50:53]
	v_mfma_f32_16x16x32_bf16 v[42:45], v[102:105], v[126:129], v[42:45]
	v_mfma_f32_16x16x32_bf16 v[34:37], v[110:113], v[126:129], v[34:37]
	v_mfma_f32_16x16x32_bf16 v[24:27], v[102:105], v[134:137], v[24:27]
	v_mfma_f32_16x16x32_bf16 v[16:19], v[110:113], v[134:137], v[16:19]
	v_mfma_f32_16x16x32_bf16 v[8:11], v[102:105], v[142:145], v[8:11]
	v_mfma_f32_16x16x32_bf16 v[0:3], v[110:113], v[142:145], v[0:3]
	s_setprio 0
	s_barrier
	s_add_i32 s31, s31, s12
	v_lshl_add_u64 v[82:83], v[146:147], 0, s[24:25]
	s_mov_b32 m0, s31
	s_nop 0
	global_load_lds_dwordx4 v[82:83], off
	s_add_i32 m0, s31, 0x2000
	s_add_u32 s2, s2, 0x40080
	v_lshl_add_u64 v[82:83], v[148:149], 0, s[24:25]
	s_addc_u32 s3, s3, 0
	s_add_i32 s31, s35, s12
	global_load_lds_dwordx4 v[82:83], off
	v_lshl_add_u64 v[82:83], s[2:3], 0, v[32:33]
	s_mov_b32 m0, s31
	s_nop 0
	global_load_lds_dwordx4 v[82:83], off
	v_lshl_add_u64 v[82:83], s[2:3], 0, v[66:67]
	s_add_i32 m0, s31, 0x2000
	s_nop 0
	global_load_lds_dwordx4 v[82:83], off
	v_lshl_add_u64 v[82:83], v[150:151], 0, s[24:25]
	s_mov_b32 m0, s19
	s_nop 0
	global_load_lds_dwordx4 v[82:83], off
	v_lshl_add_u64 v[82:83], v[152:153], 0, s[24:25]
	s_mov_b32 m0, s20
	s_nop 0
	global_load_lds_dwordx4 v[82:83], off
	s_waitcnt vmcnt(8)
	s_waitcnt lgkmcnt(0)
	s_barrier
	s_barrier
	s_add_i32 s30, s30, 2
	s_add_u32 s6, s6, 0x100
	s_addc_u32 s7, s7, 0
	s_cmp_gt_u32 s30, 13
	s_cbranch_scc0 .LBB0_2574
	s_cmpk_lt_u32 s8, 0x100
	s_cbranch_scc0 .LBB0_2577
	s_barrier

.LBB0_2858:
	s_add_u32 s56, s58, 0x100
	s_addc_u32 s57, s59, 0
	s_add_i32 s63, 0, 0x10000
	s_cmp_eq_u32 s62, 40
	s_cselect_b32 s3, s43, s57
	s_cselect_b32 s2, s42, s56
	s_cselect_b32 s61, s55, s29
	s_cselect_b32 s60, s54, s28
	s_add_i32 s64, 0, 0x14000
	v_add_u32_e32 v142, s63, v210
	v_add_u32_e32 v158, s64, v210
	ds_read_b128 v[114:117], v142
	ds_read_b128 v[122:125], v142 offset:1024
	ds_read_b128 v[130:133], v142 offset:2048
	ds_read_b128 v[142:145], v142 offset:3072
	ds_read_b128 v[146:149], v158
	ds_read_b128 v[150:153], v158 offset:1024
	ds_read_b128 v[182:185], v158 offset:2048
	ds_read_b128 v[186:189], v158 offset:3072
	v_lshl_add_u64 v[158:159], s[58:59], 0, v[178:179]
	s_add_i32 m0, s30, 0xc000
	ds_read_b128 v[190:193], v32
	ds_read_b128 v[194:197], v32 offset:1024
	ds_read_b128 v[220:223], v32 offset:2048
	ds_read_b128 v[224:227], v32 offset:3072
	ds_read_b128 v[228:231], v32 offset:4096
	ds_read_b128 v[232:235], v32 offset:5120
	ds_read_b128 v[236:239], v32 offset:6144
	ds_read_b128 v[240:243], v32 offset:7168
	global_load_lds_dwordx4 v[158:159], off
	v_lshl_add_u64 v[158:159], s[58:59], 0, v[180:181]
	s_add_i32 m0, s30, 0xe000
	s_nop 0
	global_load_lds_dwordx4 v[158:159], off
	s_waitcnt vmcnt(8)
	s_waitcnt lgkmcnt(0)
	s_barrier
	s_setprio 1
	v_mfma_f32_16x16x32_bf16 v[138:141], v[114:117], v[190:193], v[138:141]
	v_mfma_f32_16x16x32_bf16 v[134:137], v[130:133], v[190:193], v[134:137]
	v_mfma_f32_16x16x32_bf16 v[110:113], v[114:117], v[220:223], v[110:113]
	v_mfma_f32_16x16x32_bf16 v[106:109], v[130:133], v[220:223], v[106:109]
	v_mfma_f32_16x16x32_bf16 v[94:97], v[114:117], v[228:231], v[94:97]
	v_mfma_f32_16x16x32_bf16 v[90:93], v[130:133], v[228:231], v[90:93]
	v_mfma_f32_16x16x32_bf16 v[78:81], v[114:117], v[236:239], v[78:81]
	v_mfma_f32_16x16x32_bf16 v[74:77], v[130:133], v[236:239], v[74:77]
	v_mfma_f32_16x16x32_bf16 v[138:141], v[122:125], v[194:197], v[138:141]
	v_mfma_f32_16x16x32_bf16 v[134:137], v[142:145], v[194:197], v[134:137]
	v_mfma_f32_16x16x32_bf16 v[110:113], v[122:125], v[224:227], v[110:113]
	v_mfma_f32_16x16x32_bf16 v[106:109], v[142:145], v[224:227], v[106:109]
	v_mfma_f32_16x16x32_bf16 v[94:97], v[122:125], v[232:235], v[94:97]
	v_mfma_f32_16x16x32_bf16 v[90:93], v[142:145], v[232:235], v[90:93]
	v_mfma_f32_16x16x32_bf16 v[78:81], v[122:125], v[240:243], v[78:81]
	v_mfma_f32_16x16x32_bf16 v[74:77], v[142:145], v[240:243], v[74:77]
	v_mfma_f32_16x16x32_bf16 v[126:129], v[146:149], v[190:193], v[126:129]
	v_mfma_f32_16x16x32_bf16 v[118:121], v[182:185], v[190:193], v[118:121]
	v_mfma_f32_16x16x32_bf16 v[102:105], v[146:149], v[220:223], v[102:105]
	v_mfma_f32_16x16x32_bf16 v[98:101], v[182:185], v[220:223], v[98:101]
	v_mfma_f32_16x16x32_bf16 v[86:89], v[146:149], v[228:231], v[86:89]
	v_mfma_f32_16x16x32_bf16 v[82:85], v[182:185], v[228:231], v[82:85]
	v_mfma_f32_16x16x32_bf16 v[70:73], v[146:149], v[236:239], v[70:73]
	v_mfma_f32_16x16x32_bf16 v[66:69], v[182:185], v[236:239], v[66:69]
	v_mfma_f32_16x16x32_bf16 v[126:129], v[150:153], v[194:197], v[126:129]
	v_mfma_f32_16x16x32_bf16 v[118:121], v[186:189], v[194:197], v[118:121]
	v_mfma_f32_16x16x32_bf16 v[102:105], v[150:153], v[224:227], v[102:105]
	v_mfma_f32_16x16x32_bf16 v[98:101], v[186:189], v[224:227], v[98:101]
	v_mfma_f32_16x16x32_bf16 v[86:89], v[150:153], v[232:235], v[86:89]
	v_mfma_f32_16x16x32_bf16 v[82:85], v[186:189], v[232:235], v[82:85]
	v_mfma_f32_16x16x32_bf16 v[70:73], v[150:153], v[240:243], v[70:73]
	v_mfma_f32_16x16x32_bf16 v[66:69], v[186:189], v[240:243], v[66:69]
	s_setprio 0
	s_barrier
	s_add_i32 s58, s63, s17
	v_lshl_add_u64 v[158:159], s[60:61], 0, v[174:175]
	s_mov_b32 m0, s58
	ds_read_b128 v[190:193], v32 offset:16384
	ds_read_b128 v[194:197], v32 offset:17408
	ds_read_b128 v[220:223], v32 offset:18432
	ds_read_b128 v[224:227], v32 offset:19456
	ds_read_b128 v[228:231], v32 offset:20480
	ds_read_b128 v[232:235], v32 offset:21504
	ds_read_b128 v[236:239], v32 offset:22528
	ds_read_b128 v[240:243], v32 offset:23552
	global_load_lds_dwordx4 v[158:159], off
	s_add_i32 m0, s58, 0x2000
	s_add_u32 s58, s60, 0xb0000
	v_lshl_add_u64 v[160:161], s[60:61], 0, v[170:171]
	s_addc_u32 s59, s61, 0
	s_add_i32 s63, s64, s17
	global_load_lds_dwordx4 v[160:161], off
	v_lshl_add_u64 v[198:199], s[58:59], 0, v[174:175]
	s_mov_b32 m0, s63
	v_lshl_add_u64 v[212:213], s[2:3], 0, v[172:173]
	global_load_lds_dwordx4 v[198:199], off
	v_lshl_add_u64 v[198:199], s[58:59], 0, v[170:171]
	s_add_i32 m0, s63, 0x2000
	s_nop 0
	global_load_lds_dwordx4 v[198:199], off
	v_lshl_add_u64 v[198:199], s[2:3], 0, v[176:177]
	s_mov_b32 m0, s30
	s_nop 0
	global_load_lds_dwordx4 v[198:199], off
	s_mov_b32 m0, s31
	s_nop 0
	global_load_lds_dwordx4 v[212:213], off
	s_waitcnt vmcnt(8)
	s_waitcnt lgkmcnt(0)
	s_barrier
	s_setprio 1
	v_mfma_f32_16x16x32_bf16 v[62:65], v[114:117], v[190:193], v[62:65]
	v_mfma_f32_16x16x32_bf16 v[58:61], v[130:133], v[190:193], v[58:61]
	v_mfma_f32_16x16x32_bf16 v[46:49], v[114:117], v[220:223], v[46:49]
	v_mfma_f32_16x16x32_bf16 v[42:45], v[130:133], v[220:223], v[42:45]
	v_mfma_f32_16x16x32_bf16 v[28:31], v[114:117], v[228:231], v[28:31]
	v_mfma_f32_16x16x32_bf16 v[24:27], v[130:133], v[228:231], v[24:27]
	v_mfma_f32_16x16x32_bf16 v[12:15], v[114:117], v[236:239], v[12:15]
	v_mfma_f32_16x16x32_bf16 v[8:11], v[130:133], v[236:239], v[8:11]
	v_mfma_f32_16x16x32_bf16 v[62:65], v[122:125], v[194:197], v[62:65]
	v_mfma_f32_16x16x32_bf16 v[58:61], v[142:145], v[194:197], v[58:61]
	v_mfma_f32_16x16x32_bf16 v[46:49], v[122:125], v[224:227], v[46:49]
	v_mfma_f32_16x16x32_bf16 v[42:45], v[142:145], v[224:227], v[42:45]
	v_mfma_f32_16x16x32_bf16 v[28:31], v[122:125], v[232:235], v[28:31]
	v_mfma_f32_16x16x32_bf16 v[24:27], v[142:145], v[232:235], v[24:27]
	v_mfma_f32_16x16x32_bf16 v[12:15], v[122:125], v[240:243], v[12:15]
	v_mfma_f32_16x16x32_bf16 v[8:11], v[142:145], v[240:243], v[8:11]
	v_mfma_f32_16x16x32_bf16 v[54:57], v[146:149], v[190:193], v[54:57]
	v_mfma_f32_16x16x32_bf16 v[50:53], v[182:185], v[190:193], v[50:53]
	v_mfma_f32_16x16x32_bf16 v[38:41], v[146:149], v[220:223], v[38:41]
	v_mfma_f32_16x16x32_bf16 v[34:37], v[182:185], v[220:223], v[34:37]
	v_mfma_f32_16x16x32_bf16 v[20:23], v[146:149], v[228:231], v[20:23]
	v_mfma_f32_16x16x32_bf16 v[16:19], v[182:185], v[228:231], v[16:19]
	v_mfma_f32_16x16x32_bf16 v[4:7], v[146:149], v[236:239], v[4:7]
	v_mfma_f32_16x16x32_bf16 v[0:3], v[182:185], v[236:239], v[0:3]
	v_mfma_f32_16x16x32_bf16 v[54:57], v[150:153], v[194:197], v[54:57]
	v_mfma_f32_16x16x32_bf16 v[50:53], v[186:189], v[194:197], v[50:53]
	v_mfma_f32_16x16x32_bf16 v[38:41], v[150:153], v[224:227], v[38:41]
	v_mfma_f32_16x16x32_bf16 v[34:37], v[186:189], v[224:227], v[34:37]
	v_mfma_f32_16x16x32_bf16 v[20:23], v[150:153], v[232:235], v[20:23]
	v_mfma_f32_16x16x32_bf16 v[16:19], v[186:189], v[232:235], v[16:19]
	v_mfma_f32_16x16x32_bf16 v[4:7], v[150:153], v[240:243], v[4:7]
	v_mfma_f32_16x16x32_bf16 v[0:3], v[186:189], v[240:243], v[0:3]
	s_setprio 0
	s_barrier
	s_add_i32 s58, 0, 0x18000
	s_add_i32 s59, 0, 0x1c000
	v_add_u32_e32 v142, s58, v210
	v_add_u32_e32 v186, s59, v210
	ds_read_b128 v[114:117], v142
	ds_read_b128 v[122:125], v142 offset:1024
	ds_read_b128 v[130:133], v142 offset:2048
	ds_read_b128 v[142:145], v142 offset:3072
	ds_read_b128 v[146:149], v186
	ds_read_b128 v[150:153], v186 offset:1024
	ds_read_b128 v[182:185], v186 offset:2048
	ds_read_b128 v[186:189], v186 offset:3072
	s_add_u32 s2, s2, 0xb0000
	s_addc_u32 s3, s3, 0
	s_mov_b32 m0, s79
	v_lshl_add_u64 v[244:245], s[2:3], 0, v[176:177]
	ds_read_b128 v[190:193], v32 offset:32768
	ds_read_b128 v[194:197], v32 offset:33792
	ds_read_b128 v[220:223], v32 offset:34816
	ds_read_b128 v[224:227], v32 offset:35840
	ds_read_b128 v[228:231], v32 offset:36864
	ds_read_b128 v[232:235], v32 offset:37888
	ds_read_b128 v[236:239], v32 offset:38912
	ds_read_b128 v[240:243], v32 offset:39936
	global_load_lds_dwordx4 v[244:245], off
	v_lshl_add_u64 v[244:245], s[2:3], 0, v[172:173]
	s_mov_b32 m0, s80
	s_nop 0
	global_load_lds_dwordx4 v[244:245], off
	s_waitcnt vmcnt(8)
	s_waitcnt lgkmcnt(0)
	s_barrier
	s_setprio 1
	v_mfma_f32_16x16x32_bf16 v[138:141], v[114:117], v[190:193], v[138:141]
	v_mfma_f32_16x16x32_bf16 v[134:137], v[130:133], v[190:193], v[134:137]
	v_mfma_f32_16x16x32_bf16 v[110:113], v[114:117], v[220:223], v[110:113]
	v_mfma_f32_16x16x32_bf16 v[106:109], v[130:133], v[220:223], v[106:109]
	v_mfma_f32_16x16x32_bf16 v[94:97], v[114:117], v[228:231], v[94:97]
	v_mfma_f32_16x16x32_bf16 v[90:93], v[130:133], v[228:231], v[90:93]
	v_mfma_f32_16x16x32_bf16 v[78:81], v[114:117], v[236:239], v[78:81]
	v_mfma_f32_16x16x32_bf16 v[74:77], v[130:133], v[236:239], v[74:77]
	v_mfma_f32_16x16x32_bf16 v[138:141], v[122:125], v[194:197], v[138:141]
	v_mfma_f32_16x16x32_bf16 v[134:137], v[142:145], v[194:197], v[134:137]
	v_mfma_f32_16x16x32_bf16 v[110:113], v[122:125], v[224:227], v[110:113]
	v_mfma_f32_16x16x32_bf16 v[106:109], v[142:145], v[224:227], v[106:109]
	v_mfma_f32_16x16x32_bf16 v[94:97], v[122:125], v[232:235], v[94:97]
	v_mfma_f32_16x16x32_bf16 v[90:93], v[142:145], v[232:235], v[90:93]
	v_mfma_f32_16x16x32_bf16 v[78:81], v[122:125], v[240:243], v[78:81]
	v_mfma_f32_16x16x32_bf16 v[74:77], v[142:145], v[240:243], v[74:77]
	v_mfma_f32_16x16x32_bf16 v[126:129], v[146:149], v[190:193], v[126:129]
	v_mfma_f32_16x16x32_bf16 v[118:121], v[182:185], v[190:193], v[118:121]
	v_mfma_f32_16x16x32_bf16 v[102:105], v[146:149], v[220:223], v[102:105]
	v_mfma_f32_16x16x32_bf16 v[98:101], v[182:185], v[220:223], v[98:101]
	v_mfma_f32_16x16x32_bf16 v[86:89], v[146:149], v[228:231], v[86:89]
	v_mfma_f32_16x16x32_bf16 v[82:85], v[182:185], v[228:231], v[82:85]
	v_mfma_f32_16x16x32_bf16 v[70:73], v[146:149], v[236:239], v[70:73]
	v_mfma_f32_16x16x32_bf16 v[66:69], v[182:185], v[236:239], v[66:69]
	v_mfma_f32_16x16x32_bf16 v[126:129], v[150:153], v[194:197], v[126:129]
	v_mfma_f32_16x16x32_bf16 v[118:121], v[186:189], v[194:197], v[118:121]
	v_mfma_f32_16x16x32_bf16 v[102:105], v[150:153], v[224:227], v[102:105]
	v_mfma_f32_16x16x32_bf16 v[98:101], v[186:189], v[224:227], v[98:101]
	v_mfma_f32_16x16x32_bf16 v[86:89], v[150:153], v[232:235], v[86:89]
	v_mfma_f32_16x16x32_bf16 v[82:85], v[186:189], v[232:235], v[82:85]
	v_mfma_f32_16x16x32_bf16 v[70:73], v[150:153], v[240:243], v[70:73]
	v_mfma_f32_16x16x32_bf16 v[66:69], v[186:189], v[240:243], v[66:69]
	s_setprio 0
	s_barrier
	s_add_i32 s2, s58, s17
	v_lshl_add_u64 v[158:159], v[158:159], 0, s[24:25]
	s_mov_b32 m0, s2
	ds_read_b128 v[190:193], v32 offset:49152
	ds_read_b128 v[194:197], v32 offset:50176
	ds_read_b128 v[220:223], v32 offset:51200
	ds_read_b128 v[224:227], v32 offset:52224
	ds_read_b128 v[228:231], v32 offset:53248
	ds_read_b128 v[232:235], v32 offset:54272
	ds_read_b128 v[236:239], v32 offset:55296
	ds_read_b128 v[240:243], v32 offset:56320
	global_load_lds_dwordx4 v[158:159], off
	s_add_i32 m0, s2, 0x2000
	s_add_u32 s2, s60, 0xb0080
	v_lshl_add_u64 v[158:159], v[160:161], 0, s[24:25]
	s_addc_u32 s3, s61, 0
	s_add_i32 s58, s59, s17
	global_load_lds_dwordx4 v[158:159], off
	v_lshl_add_u64 v[158:159], s[2:3], 0, v[174:175]
	s_mov_b32 m0, s58
	s_nop 0
	global_load_lds_dwordx4 v[158:159], off
	v_lshl_add_u64 v[158:159], s[2:3], 0, v[170:171]
	s_add_i32 m0, s58, 0x2000
	s_nop 0
	global_load_lds_dwordx4 v[158:159], off
	v_lshl_add_u64 v[158:159], v[198:199], 0, s[24:25]
	s_mov_b32 m0, s8
	s_nop 0
	global_load_lds_dwordx4 v[158:159], off
	v_lshl_add_u64 v[158:159], v[212:213], 0, s[24:25]
	s_mov_b32 m0, s11
	s_nop 0
	global_load_lds_dwordx4 v[158:159], off
	s_waitcnt vmcnt(8)
	s_waitcnt lgkmcnt(0)
	s_barrier
	s_setprio 1
	v_mfma_f32_16x16x32_bf16 v[62:65], v[114:117], v[190:193], v[62:65]
	v_mfma_f32_16x16x32_bf16 v[58:61], v[130:133], v[190:193], v[58:61]
	v_mfma_f32_16x16x32_bf16 v[46:49], v[114:117], v[220:223], v[46:49]
	v_mfma_f32_16x16x32_bf16 v[42:45], v[130:133], v[220:223], v[42:45]
	v_mfma_f32_16x16x32_bf16 v[28:31], v[114:117], v[228:231], v[28:31]
	v_mfma_f32_16x16x32_bf16 v[24:27], v[130:133], v[228:231], v[24:27]
	v_mfma_f32_16x16x32_bf16 v[12:15], v[114:117], v[236:239], v[12:15]
	v_mfma_f32_16x16x32_bf16 v[8:11], v[130:133], v[236:239], v[8:11]
	v_mfma_f32_16x16x32_bf16 v[62:65], v[122:125], v[194:197], v[62:65]
	v_mfma_f32_16x16x32_bf16 v[58:61], v[142:145], v[194:197], v[58:61]
	v_mfma_f32_16x16x32_bf16 v[46:49], v[122:125], v[224:227], v[46:49]
	v_mfma_f32_16x16x32_bf16 v[42:45], v[142:145], v[224:227], v[42:45]
	v_mfma_f32_16x16x32_bf16 v[28:31], v[122:125], v[232:235], v[28:31]
	v_mfma_f32_16x16x32_bf16 v[24:27], v[142:145], v[232:235], v[24:27]
	v_mfma_f32_16x16x32_bf16 v[12:15], v[122:125], v[240:243], v[12:15]
	v_mfma_f32_16x16x32_bf16 v[8:11], v[142:145], v[240:243], v[8:11]
	v_mfma_f32_16x16x32_bf16 v[54:57], v[146:149], v[190:193], v[54:57]
	v_mfma_f32_16x16x32_bf16 v[50:53], v[182:185], v[190:193], v[50:53]
	v_mfma_f32_16x16x32_bf16 v[38:41], v[146:149], v[220:223], v[38:41]
	v_mfma_f32_16x16x32_bf16 v[34:37], v[182:185], v[220:223], v[34:37]
	v_mfma_f32_16x16x32_bf16 v[20:23], v[146:149], v[228:231], v[20:23]
	v_mfma_f32_16x16x32_bf16 v[16:19], v[182:185], v[228:231], v[16:19]
	v_mfma_f32_16x16x32_bf16 v[4:7], v[146:149], v[236:239], v[4:7]
	v_mfma_f32_16x16x32_bf16 v[0:3], v[182:185], v[236:239], v[0:3]
	v_mfma_f32_16x16x32_bf16 v[54:57], v[150:153], v[194:197], v[54:57]
	v_mfma_f32_16x16x32_bf16 v[50:53], v[186:189], v[194:197], v[50:53]
	v_mfma_f32_16x16x32_bf16 v[38:41], v[150:153], v[224:227], v[38:41]
	v_mfma_f32_16x16x32_bf16 v[34:37], v[186:189], v[224:227], v[34:37]
	v_mfma_f32_16x16x32_bf16 v[20:23], v[150:153], v[232:235], v[20:23]
	v_mfma_f32_16x16x32_bf16 v[16:19], v[186:189], v[232:235], v[16:19]
	v_mfma_f32_16x16x32_bf16 v[4:7], v[150:153], v[240:243], v[4:7]
	v_mfma_f32_16x16x32_bf16 v[0:3], v[186:189], v[240:243], v[0:3]
	s_setprio 0
	s_barrier
	s_add_i32 s62, s62, 2
	s_add_u32 s28, s28, 0x100
	s_addc_u32 s29, s29, 0
	s_cmp_gt_u32 s62, 41
	s_mov_b64 s[58:59], s[56:57]
	s_cbranch_scc0 .LBB0_2858
	s_and_b64 vcc, exec, s[52:53]
	s_cbranch_vccz .LBB0_2861
	s_barrier

.LBB0_2949:
	s_add_u32 s2, s40, s48
	s_addc_u32 s3, s41, s49
	s_add_u32 s2, s2, 0x100
	s_addc_u32 s3, s3, 0
	s_add_u32 s50, s52, s48
	s_addc_u32 s51, s53, s49
	s_add_i32 s57, 0, 0x10000
	s_cmpk_eq_i32 s48, 0x1500
	s_cselect_b32 s3, s43, s3
	s_cselect_b32 s2, s42, s2
	v_add_u32_e32 v152, s57, v146
	s_cselect_b32 s51, s39, s51
	s_cselect_b32 s50, s38, s50
	s_add_i32 s60, 0, 0x14000
	ds_read_b128 v[148:151], v152
	ds_read_b128 v[162:165], v152 offset:1024
	ds_read_b128 v[166:169], v152 offset:2048
	ds_read_b128 v[170:173], v152 offset:3072
	v_add_u32_e32 v152, s60, v146
	ds_read_b128 v[174:177], v152
	ds_read_b128 v[178:181], v152 offset:1024
	ds_read_b128 v[182:185], v152 offset:2048
	ds_read_b128 v[186:189], v152 offset:3072
	v_lshl_add_u64 v[152:153], v[140:141], 0, s[48:49]
	s_add_i32 m0, s12, 0xc000
	ds_read_b128 v[192:195], v147
	ds_read_b128 v[196:199], v147 offset:1024
	ds_read_b128 v[200:203], v147 offset:2048
	ds_read_b128 v[204:207], v147 offset:3072
	ds_read_b128 v[208:211], v147 offset:4096
	ds_read_b128 v[220:223], v147 offset:5120
	ds_read_b128 v[224:227], v147 offset:6144
	ds_read_b128 v[228:231], v147 offset:7168
	global_load_lds_dwordx4 v[152:153], off
	v_lshl_add_u64 v[152:153], v[142:143], 0, s[48:49]
	s_add_i32 m0, s12, 0xe000
	s_nop 0
	global_load_lds_dwordx4 v[152:153], off
	s_waitcnt vmcnt(8)
	s_waitcnt lgkmcnt(0)
	s_barrier
	s_setprio 1
	v_mfma_f32_16x16x32_bf16 v[126:129], v[148:151], v[192:195], v[126:129]
	v_mfma_f32_16x16x32_bf16 v[122:125], v[166:169], v[192:195], v[122:125]
	v_mfma_f32_16x16x32_bf16 v[110:113], v[148:151], v[200:203], v[110:113]
	v_mfma_f32_16x16x32_bf16 v[106:109], v[166:169], v[200:203], v[106:109]
	v_mfma_f32_16x16x32_bf16 v[94:97], v[148:151], v[208:211], v[94:97]
	v_mfma_f32_16x16x32_bf16 v[90:93], v[166:169], v[208:211], v[90:93]
	v_mfma_f32_16x16x32_bf16 v[78:81], v[148:151], v[224:227], v[78:81]
	v_mfma_f32_16x16x32_bf16 v[74:77], v[166:169], v[224:227], v[74:77]
	v_mfma_f32_16x16x32_bf16 v[126:129], v[162:165], v[196:199], v[126:129]
	v_mfma_f32_16x16x32_bf16 v[122:125], v[170:173], v[196:199], v[122:125]
	v_mfma_f32_16x16x32_bf16 v[110:113], v[162:165], v[204:207], v[110:113]
	v_mfma_f32_16x16x32_bf16 v[106:109], v[170:173], v[204:207], v[106:109]
	v_mfma_f32_16x16x32_bf16 v[94:97], v[162:165], v[220:223], v[94:97]
	v_mfma_f32_16x16x32_bf16 v[90:93], v[170:173], v[220:223], v[90:93]
	v_mfma_f32_16x16x32_bf16 v[78:81], v[162:165], v[228:231], v[78:81]
	v_mfma_f32_16x16x32_bf16 v[74:77], v[170:173], v[228:231], v[74:77]
	v_mfma_f32_16x16x32_bf16 v[118:121], v[174:177], v[192:195], v[118:121]
	v_mfma_f32_16x16x32_bf16 v[114:117], v[182:185], v[192:195], v[114:117]
	v_mfma_f32_16x16x32_bf16 v[102:105], v[174:177], v[200:203], v[102:105]
	v_mfma_f32_16x16x32_bf16 v[98:101], v[182:185], v[200:203], v[98:101]
	v_mfma_f32_16x16x32_bf16 v[86:89], v[174:177], v[208:211], v[86:89]
	v_mfma_f32_16x16x32_bf16 v[82:85], v[182:185], v[208:211], v[82:85]
	v_mfma_f32_16x16x32_bf16 v[70:73], v[174:177], v[224:227], v[70:73]
	v_mfma_f32_16x16x32_bf16 v[66:69], v[182:185], v[224:227], v[66:69]
	v_mfma_f32_16x16x32_bf16 v[118:121], v[178:181], v[196:199], v[118:121]
	v_mfma_f32_16x16x32_bf16 v[114:117], v[186:189], v[196:199], v[114:117]
	v_mfma_f32_16x16x32_bf16 v[102:105], v[178:181], v[204:207], v[102:105]
	v_mfma_f32_16x16x32_bf16 v[98:101], v[186:189], v[204:207], v[98:101]
	v_mfma_f32_16x16x32_bf16 v[86:89], v[178:181], v[220:223], v[86:89]
	v_mfma_f32_16x16x32_bf16 v[82:85], v[186:189], v[220:223], v[82:85]
	v_mfma_f32_16x16x32_bf16 v[70:73], v[178:181], v[228:231], v[70:73]
	v_mfma_f32_16x16x32_bf16 v[66:69], v[186:189], v[228:231], v[66:69]
	s_setprio 0
	s_barrier
	s_add_i32 s57, s57, s11
	v_lshl_add_u64 v[152:153], s[50:51], 0, v[32:33]
	s_mov_b32 m0, s57
	ds_read_b128 v[192:195], v147 offset:16384
	ds_read_b128 v[196:199], v147 offset:17408
	ds_read_b128 v[200:203], v147 offset:18432
	ds_read_b128 v[204:207], v147 offset:19456
	ds_read_b128 v[208:211], v147 offset:20480
	ds_read_b128 v[220:223], v147 offset:21504
	ds_read_b128 v[224:227], v147 offset:22528
	ds_read_b128 v[228:231], v147 offset:23552
	global_load_lds_dwordx4 v[152:153], off
	s_add_i32 m0, s57, 0x2000
	s_add_u32 s58, s50, 0xb0000
	v_lshl_add_u64 v[158:159], s[50:51], 0, v[130:131]
	s_addc_u32 s59, s51, 0
	s_add_i32 s57, s60, s11
	global_load_lds_dwordx4 v[158:159], off
	v_lshl_add_u64 v[160:161], s[58:59], 0, v[32:33]
	s_mov_b32 m0, s57
	v_lshl_add_u64 v[212:213], s[2:3], 0, v[132:133]
	global_load_lds_dwordx4 v[160:161], off
	v_lshl_add_u64 v[160:161], s[58:59], 0, v[130:131]
	s_add_i32 m0, s57, 0x2000
	s_nop 0
	global_load_lds_dwordx4 v[160:161], off
	v_lshl_add_u64 v[160:161], s[2:3], 0, v[134:135]
	s_mov_b32 m0, s12
	s_nop 0
	global_load_lds_dwordx4 v[160:161], off
	s_mov_b32 m0, s14
	s_nop 0
	global_load_lds_dwordx4 v[212:213], off
	s_waitcnt vmcnt(8)
	s_waitcnt lgkmcnt(0)
	s_barrier
	s_setprio 1
	v_mfma_f32_16x16x32_bf16 v[62:65], v[148:151], v[192:195], v[62:65]
	v_mfma_f32_16x16x32_bf16 v[58:61], v[166:169], v[192:195], v[58:61]
	v_mfma_f32_16x16x32_bf16 v[46:49], v[148:151], v[200:203], v[46:49]
	v_mfma_f32_16x16x32_bf16 v[42:45], v[166:169], v[200:203], v[42:45]
	v_mfma_f32_16x16x32_bf16 v[28:31], v[148:151], v[208:211], v[28:31]
	v_mfma_f32_16x16x32_bf16 v[24:27], v[166:169], v[208:211], v[24:27]
	v_mfma_f32_16x16x32_bf16 v[12:15], v[148:151], v[224:227], v[12:15]
	v_mfma_f32_16x16x32_bf16 v[8:11], v[166:169], v[224:227], v[8:11]
	v_mfma_f32_16x16x32_bf16 v[62:65], v[162:165], v[196:199], v[62:65]
	v_mfma_f32_16x16x32_bf16 v[58:61], v[170:173], v[196:199], v[58:61]
	v_mfma_f32_16x16x32_bf16 v[46:49], v[162:165], v[204:207], v[46:49]
	v_mfma_f32_16x16x32_bf16 v[42:45], v[170:173], v[204:207], v[42:45]
	v_mfma_f32_16x16x32_bf16 v[28:31], v[162:165], v[220:223], v[28:31]
	v_mfma_f32_16x16x32_bf16 v[24:27], v[170:173], v[220:223], v[24:27]
	v_mfma_f32_16x16x32_bf16 v[12:15], v[162:165], v[228:231], v[12:15]
	v_mfma_f32_16x16x32_bf16 v[8:11], v[170:173], v[228:231], v[8:11]
	v_mfma_f32_16x16x32_bf16 v[54:57], v[174:177], v[192:195], v[54:57]
	v_mfma_f32_16x16x32_bf16 v[50:53], v[182:185], v[192:195], v[50:53]
	v_mfma_f32_16x16x32_bf16 v[38:41], v[174:177], v[200:203], v[38:41]
	v_mfma_f32_16x16x32_bf16 v[34:37], v[182:185], v[200:203], v[34:37]
	v_mfma_f32_16x16x32_bf16 v[20:23], v[174:177], v[208:211], v[20:23]
	v_mfma_f32_16x16x32_bf16 v[16:19], v[182:185], v[208:211], v[16:19]
	v_mfma_f32_16x16x32_bf16 v[4:7], v[174:177], v[224:227], v[4:7]
	v_mfma_f32_16x16x32_bf16 v[0:3], v[182:185], v[224:227], v[0:3]
	v_mfma_f32_16x16x32_bf16 v[54:57], v[178:181], v[196:199], v[54:57]
	v_mfma_f32_16x16x32_bf16 v[50:53], v[186:189], v[196:199], v[50:53]
	v_mfma_f32_16x16x32_bf16 v[38:41], v[178:181], v[204:207], v[38:41]
	v_mfma_f32_16x16x32_bf16 v[34:37], v[186:189], v[204:207], v[34:37]
	v_mfma_f32_16x16x32_bf16 v[20:23], v[178:181], v[220:223], v[20:23]
	v_mfma_f32_16x16x32_bf16 v[16:19], v[186:189], v[220:223], v[16:19]
	v_mfma_f32_16x16x32_bf16 v[4:7], v[178:181], v[228:231], v[4:7]
	v_mfma_f32_16x16x32_bf16 v[0:3], v[186:189], v[228:231], v[0:3]
	s_setprio 0
	s_barrier
	s_add_i32 s57, 0, 0x18000
	s_add_i32 s58, 0, 0x1c000
	v_add_u32_e32 v170, s57, v146
	v_add_u32_e32 v186, s58, v146
	ds_read_b128 v[148:151], v170
	ds_read_b128 v[162:165], v170 offset:1024
	ds_read_b128 v[166:169], v170 offset:2048
	ds_read_b128 v[170:173], v170 offset:3072
	ds_read_b128 v[174:177], v186
	ds_read_b128 v[178:181], v186 offset:1024
	ds_read_b128 v[182:185], v186 offset:2048
	ds_read_b128 v[186:189], v186 offset:3072
	s_add_u32 s2, s2, 0xb0000
	s_addc_u32 s3, s3, 0
	s_mov_b32 m0, s15
	v_lshl_add_u64 v[232:233], s[2:3], 0, v[134:135]
	ds_read_b128 v[192:195], v147 offset:32768
	ds_read_b128 v[196:199], v147 offset:33792
	ds_read_b128 v[200:203], v147 offset:34816
	ds_read_b128 v[204:207], v147 offset:35840
	ds_read_b128 v[208:211], v147 offset:36864
	ds_read_b128 v[220:223], v147 offset:37888
	ds_read_b128 v[224:227], v147 offset:38912
	ds_read_b128 v[228:231], v147 offset:39936
	global_load_lds_dwordx4 v[232:233], off
	v_lshl_add_u64 v[232:233], s[2:3], 0, v[132:133]
	s_mov_b32 m0, s17
	s_nop 0
	global_load_lds_dwordx4 v[232:233], off
	s_waitcnt vmcnt(8)
	s_waitcnt lgkmcnt(0)
	s_barrier
	s_setprio 1
	v_mfma_f32_16x16x32_bf16 v[126:129], v[148:151], v[192:195], v[126:129]
	v_mfma_f32_16x16x32_bf16 v[122:125], v[166:169], v[192:195], v[122:125]
	v_mfma_f32_16x16x32_bf16 v[110:113], v[148:151], v[200:203], v[110:113]
	v_mfma_f32_16x16x32_bf16 v[106:109], v[166:169], v[200:203], v[106:109]
	v_mfma_f32_16x16x32_bf16 v[94:97], v[148:151], v[208:211], v[94:97]
	v_mfma_f32_16x16x32_bf16 v[90:93], v[166:169], v[208:211], v[90:93]
	v_mfma_f32_16x16x32_bf16 v[78:81], v[148:151], v[224:227], v[78:81]
	v_mfma_f32_16x16x32_bf16 v[74:77], v[166:169], v[224:227], v[74:77]
	v_mfma_f32_16x16x32_bf16 v[126:129], v[162:165], v[196:199], v[126:129]
	v_mfma_f32_16x16x32_bf16 v[122:125], v[170:173], v[196:199], v[122:125]
	v_mfma_f32_16x16x32_bf16 v[110:113], v[162:165], v[204:207], v[110:113]
	v_mfma_f32_16x16x32_bf16 v[106:109], v[170:173], v[204:207], v[106:109]
	v_mfma_f32_16x16x32_bf16 v[94:97], v[162:165], v[220:223], v[94:97]
	v_mfma_f32_16x16x32_bf16 v[90:93], v[170:173], v[220:223], v[90:93]
	v_mfma_f32_16x16x32_bf16 v[78:81], v[162:165], v[228:231], v[78:81]
	v_mfma_f32_16x16x32_bf16 v[74:77], v[170:173], v[228:231], v[74:77]
	v_mfma_f32_16x16x32_bf16 v[118:121], v[174:177], v[192:195], v[118:121]
	v_mfma_f32_16x16x32_bf16 v[114:117], v[182:185], v[192:195], v[114:117]
	v_mfma_f32_16x16x32_bf16 v[102:105], v[174:177], v[200:203], v[102:105]
	v_mfma_f32_16x16x32_bf16 v[98:101], v[182:185], v[200:203], v[98:101]
	v_mfma_f32_16x16x32_bf16 v[86:89], v[174:177], v[208:211], v[86:89]
	v_mfma_f32_16x16x32_bf16 v[82:85], v[182:185], v[208:211], v[82:85]
	v_mfma_f32_16x16x32_bf16 v[70:73], v[174:177], v[224:227], v[70:73]
	v_mfma_f32_16x16x32_bf16 v[66:69], v[182:185], v[224:227], v[66:69]
	v_mfma_f32_16x16x32_bf16 v[118:121], v[178:181], v[196:199], v[118:121]
	v_mfma_f32_16x16x32_bf16 v[114:117], v[186:189], v[196:199], v[114:117]
	v_mfma_f32_16x16x32_bf16 v[102:105], v[178:181], v[204:207], v[102:105]
	v_mfma_f32_16x16x32_bf16 v[98:101], v[186:189], v[204:207], v[98:101]
	v_mfma_f32_16x16x32_bf16 v[86:89], v[178:181], v[220:223], v[86:89]
	v_mfma_f32_16x16x32_bf16 v[82:85], v[186:189], v[220:223], v[82:85]
	v_mfma_f32_16x16x32_bf16 v[70:73], v[178:181], v[228:231], v[70:73]
	v_mfma_f32_16x16x32_bf16 v[66:69], v[186:189], v[228:231], v[66:69]
	s_setprio 0
	s_barrier
	s_add_i32 s2, s57, s11
	v_lshl_add_u64 v[152:153], v[152:153], 0, s[24:25]
	s_mov_b32 m0, s2
	ds_read_b128 v[192:195], v147 offset:49152
	ds_read_b128 v[196:199], v147 offset:50176
	ds_read_b128 v[200:203], v147 offset:51200
	ds_read_b128 v[204:207], v147 offset:52224
	ds_read_b128 v[208:211], v147 offset:53248
	ds_read_b128 v[220:223], v147 offset:54272
	ds_read_b128 v[224:227], v147 offset:55296
	ds_read_b128 v[228:231], v147 offset:56320
	global_load_lds_dwordx4 v[152:153], off
	s_add_i32 m0, s2, 0x2000
	s_add_u32 s2, s50, 0xb0080
	v_lshl_add_u64 v[152:153], v[158:159], 0, s[24:25]
	s_addc_u32 s3, s51, 0
	s_add_i32 s50, s58, s11
	global_load_lds_dwordx4 v[152:153], off
	v_lshl_add_u64 v[152:153], s[2:3], 0, v[32:33]
	s_mov_b32 m0, s50
	s_nop 0
	global_load_lds_dwordx4 v[152:153], off
	v_lshl_add_u64 v[152:153], s[2:3], 0, v[130:131]
	s_add_i32 m0, s50, 0x2000
	s_nop 0
	global_load_lds_dwordx4 v[152:153], off
	v_lshl_add_u64 v[152:153], v[160:161], 0, s[24:25]
	s_mov_b32 m0, s23
	s_nop 0
	global_load_lds_dwordx4 v[152:153], off
	v_lshl_add_u64 v[152:153], v[212:213], 0, s[24:25]
	s_mov_b32 m0, s28
	s_nop 0
	global_load_lds_dwordx4 v[152:153], off
	s_waitcnt vmcnt(8)
	s_waitcnt lgkmcnt(0)
	s_barrier
	s_setprio 1
	v_mfma_f32_16x16x32_bf16 v[62:65], v[148:151], v[192:195], v[62:65]
	v_mfma_f32_16x16x32_bf16 v[58:61], v[166:169], v[192:195], v[58:61]
	v_mfma_f32_16x16x32_bf16 v[46:49], v[148:151], v[200:203], v[46:49]
	v_mfma_f32_16x16x32_bf16 v[42:45], v[166:169], v[200:203], v[42:45]
	v_mfma_f32_16x16x32_bf16 v[28:31], v[148:151], v[208:211], v[28:31]
	v_mfma_f32_16x16x32_bf16 v[24:27], v[166:169], v[208:211], v[24:27]
	v_mfma_f32_16x16x32_bf16 v[12:15], v[148:151], v[224:227], v[12:15]
	v_mfma_f32_16x16x32_bf16 v[8:11], v[166:169], v[224:227], v[8:11]
	v_mfma_f32_16x16x32_bf16 v[62:65], v[162:165], v[196:199], v[62:65]
	v_mfma_f32_16x16x32_bf16 v[58:61], v[170:173], v[196:199], v[58:61]
	v_mfma_f32_16x16x32_bf16 v[46:49], v[162:165], v[204:207], v[46:49]
	v_mfma_f32_16x16x32_bf16 v[42:45], v[170:173], v[204:207], v[42:45]
	v_mfma_f32_16x16x32_bf16 v[28:31], v[162:165], v[220:223], v[28:31]
	v_mfma_f32_16x16x32_bf16 v[24:27], v[170:173], v[220:223], v[24:27]
	v_mfma_f32_16x16x32_bf16 v[12:15], v[162:165], v[228:231], v[12:15]
	v_mfma_f32_16x16x32_bf16 v[8:11], v[170:173], v[228:231], v[8:11]
	v_mfma_f32_16x16x32_bf16 v[54:57], v[174:177], v[192:195], v[54:57]
	v_mfma_f32_16x16x32_bf16 v[50:53], v[182:185], v[192:195], v[50:53]
	v_mfma_f32_16x16x32_bf16 v[38:41], v[174:177], v[200:203], v[38:41]
	v_mfma_f32_16x16x32_bf16 v[34:37], v[182:185], v[200:203], v[34:37]
	v_mfma_f32_16x16x32_bf16 v[20:23], v[174:177], v[208:211], v[20:23]
	v_mfma_f32_16x16x32_bf16 v[16:19], v[182:185], v[208:211], v[16:19]
	v_mfma_f32_16x16x32_bf16 v[4:7], v[174:177], v[224:227], v[4:7]
	v_mfma_f32_16x16x32_bf16 v[0:3], v[182:185], v[224:227], v[0:3]
	v_mfma_f32_16x16x32_bf16 v[54:57], v[178:181], v[196:199], v[54:57]
	v_mfma_f32_16x16x32_bf16 v[50:53], v[186:189], v[196:199], v[50:53]
	v_mfma_f32_16x16x32_bf16 v[38:41], v[178:181], v[204:207], v[38:41]
	v_mfma_f32_16x16x32_bf16 v[34:37], v[186:189], v[204:207], v[34:37]
	v_mfma_f32_16x16x32_bf16 v[20:23], v[178:181], v[220:223], v[20:23]
	v_mfma_f32_16x16x32_bf16 v[16:19], v[186:189], v[220:223], v[16:19]
	v_mfma_f32_16x16x32_bf16 v[4:7], v[178:181], v[228:231], v[4:7]
	v_mfma_f32_16x16x32_bf16 v[0:3], v[186:189], v[228:231], v[0:3]
	s_setprio 0
	s_barrier
	s_add_i32 s56, s56, 2
	s_add_u32 s48, s48, 0x100
	s_addc_u32 s49, s49, 0
	s_cmp_gt_u32 s56, 41
	s_cbranch_scc0 .LBB0_2949
	s_add_u32 s2, s52, 0xffffff00
	s_addc_u32 s3, s53, -1
	s_and_b64 vcc, exec, s[36:37]
	s_cbranch_vccnz .LBB0_2936
	v_mov_b32_e32 v0, 0
	s_mov_b32 s30, s31
	s_mov_b32 s20, s54
	s_mov_b64 s[40:41], s[42:43]
	s_mov_b32 s29, s55
	v_mov_b32_e32 v1, v0
	v_mov_b32_e32 v2, v0
	v_mov_b32_e32 v3, v0
	v_mov_b32_e32 v4, v0
	v_mov_b32_e32 v5, v0
	v_mov_b32_e32 v6, v0
	v_mov_b32_e32 v7, v0
	v_mov_b32_e32 v16, v0
	v_mov_b32_e32 v17, v0
	v_mov_b32_e32 v18, v0
	v_mov_b32_e32 v19, v0
	v_mov_b32_e32 v20, v0
	v_mov_b32_e32 v21, v0
	v_mov_b32_e32 v22, v0
	v_mov_b32_e32 v23, v0
	v_mov_b32_e32 v34, v0
	v_mov_b32_e32 v35, v0
	v_mov_b32_e32 v36, v0
	v_mov_b32_e32 v37, v0
	v_mov_b32_e32 v38, v0
	v_mov_b32_e32 v39, v0
	v_mov_b32_e32 v40, v0
	v_mov_b32_e32 v41, v0
	v_mov_b32_e32 v50, v0
	v_mov_b32_e32 v51, v0
	v_mov_b32_e32 v52, v0
	v_mov_b32_e32 v53, v0
	v_mov_b32_e32 v54, v0
	v_mov_b32_e32 v55, v0
	v_mov_b32_e32 v56, v0
	v_mov_b32_e32 v57, v0
	v_mov_b32_e32 v8, v0
	v_mov_b32_e32 v9, v0
	v_mov_b32_e32 v10, v0
	v_mov_b32_e32 v11, v0
	v_mov_b32_e32 v12, v0
	v_mov_b32_e32 v13, v0
	v_mov_b32_e32 v14, v0
	v_mov_b32_e32 v15, v0
	v_mov_b32_e32 v24, v0
	v_mov_b32_e32 v25, v0
	v_mov_b32_e32 v26, v0
	v_mov_b32_e32 v27, v0
	v_mov_b32_e32 v28, v0
	v_mov_b32_e32 v29, v0
	v_mov_b32_e32 v30, v0
	v_mov_b32_e32 v31, v0
	v_mov_b32_e32 v42, v0
	v_mov_b32_e32 v43, v0
	v_mov_b32_e32 v44, v0
	v_mov_b32_e32 v45, v0
	v_mov_b32_e32 v46, v0
	v_mov_b32_e32 v47, v0
	v_mov_b32_e32 v48, v0
	v_mov_b32_e32 v49, v0
	v_mov_b32_e32 v58, v0
	v_mov_b32_e32 v59, v0
	v_mov_b32_e32 v60, v0
	v_mov_b32_e32 v61, v0
	v_mov_b32_e32 v62, v0
	v_mov_b32_e32 v63, v0
	v_mov_b32_e32 v64, v0
	v_mov_b32_e32 v65, v0
	v_mov_b32_e32 v66, v0
	v_mov_b32_e32 v67, v0
	v_mov_b32_e32 v68, v0
	v_mov_b32_e32 v69, v0
	v_mov_b32_e32 v70, v0
	v_mov_b32_e32 v71, v0
	v_mov_b32_e32 v72, v0
	v_mov_b32_e32 v73, v0
	v_mov_b32_e32 v82, v0
	v_mov_b32_e32 v83, v0
	v_mov_b32_e32 v84, v0
	v_mov_b32_e32 v85, v0
	v_mov_b32_e32 v86, v0
	v_mov_b32_e32 v87, v0
	v_mov_b32_e32 v88, v0
	v_mov_b32_e32 v89, v0
	v_mov_b32_e32 v98, v0
	v_mov_b32_e32 v99, v0
	v_mov_b32_e32 v100, v0
	v_mov_b32_e32 v101, v0
	v_mov_b32_e32 v102, v0
	v_mov_b32_e32 v103, v0
	v_mov_b32_e32 v104, v0
	v_mov_b32_e32 v105, v0
	v_mov_b32_e32 v114, v0
	v_mov_b32_e32 v115, v0
	v_mov_b32_e32 v116, v0
	v_mov_b32_e32 v117, v0
	v_mov_b32_e32 v118, v0
	v_mov_b32_e32 v119, v0
	v_mov_b32_e32 v120, v0
	v_mov_b32_e32 v121, v0
	v_mov_b32_e32 v74, v0
	v_mov_b32_e32 v75, v0
	v_mov_b32_e32 v76, v0
	v_mov_b32_e32 v77, v0
	v_mov_b32_e32 v78, v0
	v_mov_b32_e32 v79, v0
	v_mov_b32_e32 v80, v0
	v_mov_b32_e32 v81, v0
	v_mov_b32_e32 v90, v0
	v_mov_b32_e32 v91, v0
	v_mov_b32_e32 v92, v0
	v_mov_b32_e32 v93, v0
	v_mov_b32_e32 v94, v0
	v_mov_b32_e32 v95, v0
	v_mov_b32_e32 v96, v0
	v_mov_b32_e32 v97, v0
	v_mov_b32_e32 v106, v0
	v_mov_b32_e32 v107, v0
	v_mov_b32_e32 v108, v0
	v_mov_b32_e32 v109, v0
	v_mov_b32_e32 v110, v0
	v_mov_b32_e32 v111, v0
	v_mov_b32_e32 v112, v0
	v_mov_b32_e32 v113, v0
	v_mov_b32_e32 v122, v0
	v_mov_b32_e32 v123, v0
	v_mov_b32_e32 v124, v0
	v_mov_b32_e32 v125, v0
	v_mov_b32_e32 v126, v0
	v_mov_b32_e32 v127, v0
	v_mov_b32_e32 v128, v0
	v_mov_b32_e32 v129, v0
	s_andn2_b64 vcc, exec, s[34:35]
	s_cbranch_vccnz .LBB0_2937
